# K-loop: the vmcnt(8) and lgkmcnt(0) waits in front of each barrier merged into one s_waitcnt
# speedup vs baseline: 1.0054x; 1.0046x over previous
; #define PG8_STAGEA(bufoff, gbase, voff) PG8_STAGE_X(bufoff, gbase, voff, AUXA)
; #define PG8_STR(x) PG8_STR2(x)
;     ...
;         const bool has_next = S.next(ui + 1, nxt);
;         const char* nA = has_next ? (const char*)g.A + (size_t)nxt.pm * tstepA : cA; const char* nB = has_next ? (const char*)g.Bt + (size_t)nxt.pn * tstepB : cB;
;         int t0 = 0;
;         if constexpr (SP2 && GEMM_RELAX == 1) { if (ui > 0) {
;             const char* a1 = cA + kstepA; const char* a2 = cA + 2 * kstepA; const char* b2 = cB + 2 * kstepB; const char* a3 = a2 + kstepA; const char* b3 = b2 + kstepB;
;             PG8_LDB(B0, 0, 0); PG8_LDB(B1, 0, 1); PG8_SCHED; PG8_LDA(At, 0, 0); PG8_STAGEA(PG8_SA(1, 1), a1 + hstepA, voffA);
;             PG8_WAIT_V(24); PG8_WAIT_L(0); PG8_BAR; PG8_MMA(0, 0, At, B0); PG8_MMA(0, 1, At, B1); PG8_BAR; PG8_SCHED;
;             PG8_LDA(At, 0, 1); PG8_STAGEB(PG8_SB(0, 0), b2, voffB); PG8_STAGEB(PG8_SB(0, 1), b2 + hstepB, voffB); PG8_STAGEA(PG8_SA(0, 0), a2, voffA);
;             PG8_WAIT_V(24); PG8_WAIT_L(0); PG8_BAR; PG8_MMA(1, 0, At, B0); PG8_MMA(1, 1, At, B1); PG8_BAR; PG8_SCHED;
;             PG8_LDB(B0, 1, 0); PG8_LDB(B1, 1, 1); PG8_SCHED; PG8_LDA(At, 1, 0); PG8_STAGEA(PG8_SA(0, 1), a2 + hstepA, voffA);
;             PG8_WAIT_V(8); PG8_WAIT_L(0); PG8_BAR; PG8_MMA(0, 0, At, B0); PG8_MMA(0, 1, At, B1); PG8_BAR; PG8_SCHED;
;             PG8_LDA(At, 1, 1); PG8_STAGEB(PG8_SB(1, 0), b3, voffB); PG8_STAGEB(PG8_SB(1, 1), b3 + hstepB, voffB); PG8_STAGEA(PG8_SA(1, 0), a3, voffA);
;             PG8_WAIT_V(8); PG8_WAIT_L(0); PG8_BAR; PG8_MMA(1, 0, At, B0); PG8_MMA(1, 1, At, B1); PG8_BAR; PG8_SCHED;
;             t0 = 2; } }
;     ...
;         asm volatile(".p2align " PG8_STR(GEMM_LOOP_ALIGN) ::: "memory");
;     ...
;         for (int t = t0; t < nt; t += 2) {
;             const bool last = (t == nt - 2);
;             const char* a1 = cA + (size_t)(t + 1) * kstepA;
;             const char* a2 = last ? nA : cA + (size_t)(t + 2) * kstepA; const char* b2 = last ? nB : cB + (size_t)(t + 2) * kstepB;
;             const char* a3 = a2 + kstepA; const char* b3 = b2 + kstepB;
;             if (last && has_next) S.a_ready(nxt);
;             if constexpr (SP2) {
;             PG8_LDB(B0, 0, 0); PG8_LDB(B1, 0, 1); PG8_SCHED; PG8_LDA(At, 0, 0); PG8_STAGEA(PG8_SA(1, 1), a1 + hstepA, voffA);
;     ...
;             const int relax = __builtin_amdgcn_readfirstlane((t == 0 && ui > 0) ? 1 : 0);
.LBB0_128:
	s_ashr_i32 s37, s36, 31
	s_lshl_b64 s[4:5], s[36:37], 21
	s_add_u32 s38, s56, s4
	s_addc_u32 s39, s57, s5
	s_and_b64 s[4:5], s[6:7], exec
	s_cselect_b32 s4, s39, s1
	s_cselect_b32 s5, s38, s0
	s_ashr_i32 s27, s26, 31
	s_lshl_b64 s[8:9], s[26:27], 21
	s_add_u32 s40, s43, s8
	s_addc_u32 s41, s50, s9
	s_and_b64 s[8:9], s[6:7], exec
	s_cselect_b32 s16, s41, s11
	s_cselect_b32 s17, s40, s10
	s_add_u32 s8, s0, 0x100080
	s_addc_u32 s9, s1, 0
	s_add_u32 s0, s10, 0x100
	s_addc_u32 s1, s11, 0
	s_mov_b32 s27, -2
	s_add_u32 s10, s8, 0xfff00080
	s_addc_u32 s11, s9, -1
	s_add_i32 s18, 0, 0x10000
	s_cmp_eq_u32 s27, 60
	s_cselect_b32 s15, s4, s11
	s_cselect_b32 s14, s5, s10
	v_add_u32_e32 v16, s18, v167
	s_cselect_b32 s11, s16, s1
	s_cselect_b32 s10, s17, s0
	s_add_i32 s20, 0, 0x14000
	s_waitcnt lgkmcnt(0)
	ds_read_b128 v[130:133], v16
	ds_read_b128 v[134:137], v16 offset:1024
	ds_read_b128 v[152:155], v16 offset:2048
	ds_read_b128 v[156:159], v16 offset:3072
	v_add_u32_e32 v16, s20, v167
	ds_read_b128 v[160:163], v16
	ds_read_b128 v[174:177], v16 offset:1024
	ds_read_b128 v[178:181], v16 offset:2048
	ds_read_b128 v[182:185], v16 offset:3072
	v_lshl_add_u64 v[164:165], s[8:9], 0, v[148:149]
	s_add_i32 m0, s51, 0xc000
	ds_read_b128 v[186:189], v172
	ds_read_b128 v[190:193], v172 offset:1024
	ds_read_b128 v[194:197], v172 offset:2048
	ds_read_b128 v[198:201], v172 offset:3072
	ds_read_b128 v[202:205], v172 offset:4096
	ds_read_b128 v[206:209], v172 offset:5120
	ds_read_b128 v[210:213], v172 offset:6144
	ds_read_b128 v[214:217], v172 offset:7168
	global_load_lds_dwordx4 v[164:165], off
	v_lshl_add_u64 v[164:165], s[8:9], 0, v[150:151]
	s_add_i32 m0, s51, 0xe000
	s_nop 0
	global_load_lds_dwordx4 v[164:165], off
	s_waitcnt vmcnt(8) lgkmcnt(0)
	s_nop 0
	s_nop 0
	s_barrier
	v_mfma_f32_16x16x32_bf16 v[126:129], v[130:133], v[186:189], 0
	v_mfma_f32_16x16x32_bf16 v[122:125], v[152:155], v[186:189], 0
	v_mfma_f32_16x16x32_bf16 v[110:113], v[130:133], v[194:197], 0
	v_mfma_f32_16x16x32_bf16 v[106:109], v[152:155], v[194:197], 0
	v_mfma_f32_16x16x32_bf16 v[94:97], v[130:133], v[202:205], 0
	v_mfma_f32_16x16x32_bf16 v[90:93], v[152:155], v[202:205], 0
	v_mfma_f32_16x16x32_bf16 v[78:81], v[130:133], v[210:213], 0
	v_mfma_f32_16x16x32_bf16 v[74:77], v[152:155], v[210:213], 0
	v_mfma_f32_16x16x32_bf16 v[126:129], v[134:137], v[190:193], v[126:129]
	v_mfma_f32_16x16x32_bf16 v[122:125], v[156:159], v[190:193], v[122:125]
	v_mfma_f32_16x16x32_bf16 v[110:113], v[134:137], v[198:201], v[110:113]
	v_mfma_f32_16x16x32_bf16 v[106:109], v[156:159], v[198:201], v[106:109]
	v_mfma_f32_16x16x32_bf16 v[94:97], v[134:137], v[206:209], v[94:97]
	v_mfma_f32_16x16x32_bf16 v[90:93], v[156:159], v[206:209], v[90:93]
	v_mfma_f32_16x16x32_bf16 v[78:81], v[134:137], v[214:217], v[78:81]
	v_mfma_f32_16x16x32_bf16 v[74:77], v[156:159], v[214:217], v[74:77]
	v_mfma_f32_16x16x32_bf16 v[118:121], v[160:163], v[186:189], 0
	v_mfma_f32_16x16x32_bf16 v[114:117], v[178:181], v[186:189], 0
	v_mfma_f32_16x16x32_bf16 v[102:105], v[160:163], v[194:197], 0
	v_mfma_f32_16x16x32_bf16 v[98:101], v[178:181], v[194:197], 0
	v_mfma_f32_16x16x32_bf16 v[86:89], v[160:163], v[202:205], 0
	v_mfma_f32_16x16x32_bf16 v[82:85], v[178:181], v[202:205], 0
	v_mfma_f32_16x16x32_bf16 v[70:73], v[160:163], v[210:213], 0
	v_mfma_f32_16x16x32_bf16 v[66:69], v[178:181], v[210:213], 0
	v_mfma_f32_16x16x32_bf16 v[118:121], v[174:177], v[190:193], v[118:121]
	v_mfma_f32_16x16x32_bf16 v[114:117], v[182:185], v[190:193], v[114:117]
	v_mfma_f32_16x16x32_bf16 v[102:105], v[174:177], v[198:201], v[102:105]
	v_mfma_f32_16x16x32_bf16 v[98:101], v[182:185], v[198:201], v[98:101]
	v_mfma_f32_16x16x32_bf16 v[86:89], v[174:177], v[206:209], v[86:89]
	v_mfma_f32_16x16x32_bf16 v[82:85], v[182:185], v[206:209], v[82:85]
	v_mfma_f32_16x16x32_bf16 v[70:73], v[174:177], v[214:217], v[70:73]
	v_mfma_f32_16x16x32_bf16 v[66:69], v[182:185], v[214:217], v[66:69]
	s_barrier
	s_add_i32 s18, s18, s42
	v_lshl_add_u64 v[164:165], s[10:11], 0, v[142:143]
	s_mov_b32 m0, s18
	ds_read_b128 v[186:189], v172 offset:16384
	ds_read_b128 v[190:193], v172 offset:17408
	ds_read_b128 v[194:197], v172 offset:18432
	ds_read_b128 v[198:201], v172 offset:19456
	ds_read_b128 v[202:205], v172 offset:20480
	ds_read_b128 v[206:209], v172 offset:21504
	ds_read_b128 v[210:213], v172 offset:22528
	ds_read_b128 v[214:217], v172 offset:23552
	global_load_lds_dwordx4 v[164:165], off
	s_add_i32 m0, s18, 0x2000
	s_add_u32 s18, s10, 0x100000
	v_lshl_add_u64 v[218:219], s[10:11], 0, v[138:139]
	s_addc_u32 s19, s11, 0
	s_add_i32 s20, s20, s42
	global_load_lds_dwordx4 v[218:219], off
	v_lshl_add_u64 v[220:221], s[18:19], 0, v[142:143]
	s_mov_b32 m0, s20
	v_lshl_add_u64 v[222:223], s[14:15], 0, v[140:141]
	global_load_lds_dwordx4 v[220:221], off
	v_lshl_add_u64 v[220:221], s[18:19], 0, v[138:139]
	s_add_i32 m0, s20, 0x2000
	s_nop 0
	global_load_lds_dwordx4 v[220:221], off
	v_lshl_add_u64 v[220:221], s[14:15], 0, v[144:145]
	s_mov_b32 m0, s51
	s_nop 0
	global_load_lds_dwordx4 v[220:221], off
	s_mov_b32 m0, s68
	s_nop 0
	global_load_lds_dwordx4 v[222:223], off
	s_waitcnt vmcnt(8) lgkmcnt(0)
	s_nop 0
	s_barrier
; #define PG8_STAGEA(bufoff, gbase, voff) PG8_STAGE_X(bufoff, gbase, voff, AUXA)
; #define PG8_STAGEB(bufoff, gbase, voff) PG8_STAGE_X(bufoff, gbase, voff, AUXB)
; #define PG8_LDA(dst, b, h) do { _Pragma("unroll") for (int m = 0; m < 4; ++m) _Pragma("unroll") for (int k = 0; k < 2; ++k) dst[m][k] = *(const PG8_LAS bf16x8*)(lds + PG8_SA(b, h) + aoff + m * 2048 + k * 1024); } while (0)
; #define PG8_LDB(dst, b, h) do { _Pragma("unroll") for (int n = 0; n < 2; ++n) _Pragma("unroll") for (int k = 0; k < 2; ++k) dst[n][k] = *(const PG8_LAS bf16x8*)(lds + PG8_SB(b, h) + boff + n * 2048 + k * 1024); } while (0)
; #define PG8_MMA(ai, bj, At, Bt) do { if (GEMM_PRIO_MODE == 0) __builtin_amdgcn_s_setprio(1); PG8_MMA_LOOPS \
;         acc[ai][bj][m][n] = __builtin_amdgcn_mfma_f32_16x16x32_bf16(Bt[n][k], At[m][k], acc[ai][bj][m][n], 0, 0, 0); if (GEMM_PRIO_MODE == 0) __builtin_amdgcn_s_setprio(0); } while (0)
; #define PG8_WAIT_V(n) asm volatile("s_waitcnt vmcnt(" #n ")" ::: "memory")
; #define PG8_WAIT_VR(n, nr, flag) asm volatile("s_cmp_eq_u32 %0, 0\n\ts_cbranch_scc1 .Lpg8s%=\n\ts_waitcnt vmcnt(" #nr ")\n\ts_branch .Lpg8d%=\n.Lpg8s%=:\n\ts_waitcnt vmcnt(" #n ")\n.Lpg8d%=:" :: "s"(flag) : "memory", "scc")
; #define PG8_WAIT_L(n) asm volatile("s_waitcnt lgkmcnt(" #n ")" ::: "memory")
; #define PG8_BAR __builtin_amdgcn_s_barrier()
; #define PG8_SCHED __builtin_amdgcn_sched_barrier(0)
;     ...
;             PG8_LDA(At, 0, 1); PG8_STAGEB(PG8_SB(0, 0), b2, voffB); PG8_STAGEB(PG8_SB(0, 1), b2 + hstepB, voffB); PG8_STAGEA(PG8_SA(0, 0), a2, voffA);
;     ...
;             PG8_WAIT_VR(8, 24, relax); PG8_WAIT_L(0); PG8_BAR; PG8_MMA(1, 0, At, B0); PG8_MMA(1, 1, At, B1); PG8_BAR; PG8_SCHED;
;     ...
;             PG8_WAIT_V(8); PG8_WAIT_L(0); PG8_BAR; PG8_MMA(1, 0, At, B0); PG8_MMA(1, 1, At, B1); PG8_BAR; PG8_SCHED;
;     ...
;             PG8_LDB(B0, 1, 0); PG8_LDB(B1, 1, 1); PG8_SCHED; PG8_LDA(At, 1, 0); PG8_STAGEA(PG8_SA(0, 1), a2 + hstepA, voffA);
;             PG8_WAIT_V(8); PG8_WAIT_L(0); PG8_BAR; PG8_MMA(0, 0, At, B0); PG8_MMA(0, 1, At, B1); PG8_BAR; PG8_SCHED;
;             PG8_LDA(At, 1, 1); PG8_STAGEB(PG8_SB(1, 0), b3, voffB); PG8_STAGEB(PG8_SB(1, 1), b3 + hstepB, voffB); PG8_STAGEA(PG8_SA(1, 0), a3, voffA);
;             PG8_WAIT_V(8); PG8_WAIT_L(0); PG8_BAR; PG8_MMA(1, 0, At, B0); PG8_MMA(1, 1, At, B1); PG8_BAR; PG8_SCHED;
	v_mfma_f32_16x16x32_bf16 v[62:65], v[130:133], v[186:189], 0
	v_mfma_f32_16x16x32_bf16 v[58:61], v[152:155], v[186:189], 0
	v_mfma_f32_16x16x32_bf16 v[46:49], v[130:133], v[194:197], 0
	v_mfma_f32_16x16x32_bf16 v[42:45], v[152:155], v[194:197], 0
	v_mfma_f32_16x16x32_bf16 v[30:33], v[130:133], v[202:205], 0
	v_mfma_f32_16x16x32_bf16 v[26:29], v[152:155], v[202:205], 0
	v_mfma_f32_16x16x32_bf16 v[12:15], v[130:133], v[210:213], 0
	v_mfma_f32_16x16x32_bf16 v[8:11], v[152:155], v[210:213], 0
	v_mfma_f32_16x16x32_bf16 v[62:65], v[134:137], v[190:193], v[62:65]
	v_mfma_f32_16x16x32_bf16 v[58:61], v[156:159], v[190:193], v[58:61]
	v_mfma_f32_16x16x32_bf16 v[46:49], v[134:137], v[198:201], v[46:49]
	v_mfma_f32_16x16x32_bf16 v[42:45], v[156:159], v[198:201], v[42:45]
	v_mfma_f32_16x16x32_bf16 v[30:33], v[134:137], v[206:209], v[30:33]
	v_mfma_f32_16x16x32_bf16 v[26:29], v[156:159], v[206:209], v[26:29]
	v_mfma_f32_16x16x32_bf16 v[12:15], v[134:137], v[214:217], v[12:15]
	v_mfma_f32_16x16x32_bf16 v[8:11], v[156:159], v[214:217], v[8:11]
	v_mfma_f32_16x16x32_bf16 v[54:57], v[160:163], v[186:189], 0
	v_mfma_f32_16x16x32_bf16 v[50:53], v[178:181], v[186:189], 0
	v_mfma_f32_16x16x32_bf16 v[38:41], v[160:163], v[194:197], 0
	v_mfma_f32_16x16x32_bf16 v[34:37], v[178:181], v[194:197], 0
	v_mfma_f32_16x16x32_bf16 v[22:25], v[160:163], v[202:205], 0
	v_mfma_f32_16x16x32_bf16 v[18:21], v[178:181], v[202:205], 0
	v_mfma_f32_16x16x32_bf16 v[4:7], v[160:163], v[210:213], 0
	v_mfma_f32_16x16x32_bf16 v[0:3], v[178:181], v[210:213], 0
	v_mfma_f32_16x16x32_bf16 v[54:57], v[174:177], v[190:193], v[54:57]
	v_mfma_f32_16x16x32_bf16 v[50:53], v[182:185], v[190:193], v[50:53]
	v_mfma_f32_16x16x32_bf16 v[38:41], v[174:177], v[198:201], v[38:41]
	v_mfma_f32_16x16x32_bf16 v[34:37], v[182:185], v[198:201], v[34:37]
	v_mfma_f32_16x16x32_bf16 v[22:25], v[174:177], v[206:209], v[22:25]
	v_mfma_f32_16x16x32_bf16 v[18:21], v[182:185], v[206:209], v[18:21]
	v_mfma_f32_16x16x32_bf16 v[4:7], v[174:177], v[214:217], v[4:7]
	v_mfma_f32_16x16x32_bf16 v[0:3], v[182:185], v[214:217], v[0:3]
	s_barrier
	s_add_i32 s18, 0, 0x18000
	v_add_u32_e32 v16, s18, v167
	s_add_i32 s19, 0, 0x1c000
	ds_read_b128 v[130:133], v16
	ds_read_b128 v[134:137], v16 offset:1024
	ds_read_b128 v[152:155], v16 offset:2048
	ds_read_b128 v[156:159], v16 offset:3072
	v_add_u32_e32 v16, s19, v167
	ds_read_b128 v[160:163], v16
	ds_read_b128 v[174:177], v16 offset:1024
	ds_read_b128 v[178:181], v16 offset:2048
	ds_read_b128 v[182:185], v16 offset:3072
	s_add_u32 s14, s14, 0x100000
	s_addc_u32 s15, s15, 0
	s_mov_b32 m0, s69
	v_lshl_add_u64 v[224:225], s[14:15], 0, v[144:145]
	ds_read_b128 v[186:189], v172 offset:32768
	ds_read_b128 v[190:193], v172 offset:33792
	ds_read_b128 v[194:197], v172 offset:34816
	ds_read_b128 v[198:201], v172 offset:35840
	ds_read_b128 v[202:205], v172 offset:36864
	ds_read_b128 v[206:209], v172 offset:37888
	ds_read_b128 v[210:213], v172 offset:38912
	ds_read_b128 v[214:217], v172 offset:39936
	global_load_lds_dwordx4 v[224:225], off
	v_lshl_add_u64 v[224:225], s[14:15], 0, v[140:141]
	s_mov_b32 m0, s72
	s_nop 0
	global_load_lds_dwordx4 v[224:225], off
	s_waitcnt vmcnt(8) lgkmcnt(0)
	s_nop 0
	s_barrier
	v_mfma_f32_16x16x32_bf16 v[126:129], v[130:133], v[186:189], v[126:129]
	v_mfma_f32_16x16x32_bf16 v[122:125], v[152:155], v[186:189], v[122:125]
	v_mfma_f32_16x16x32_bf16 v[110:113], v[130:133], v[194:197], v[110:113]
	v_mfma_f32_16x16x32_bf16 v[106:109], v[152:155], v[194:197], v[106:109]
	v_mfma_f32_16x16x32_bf16 v[94:97], v[130:133], v[202:205], v[94:97]
	v_mfma_f32_16x16x32_bf16 v[90:93], v[152:155], v[202:205], v[90:93]
	v_mfma_f32_16x16x32_bf16 v[78:81], v[130:133], v[210:213], v[78:81]
	v_mfma_f32_16x16x32_bf16 v[74:77], v[152:155], v[210:213], v[74:77]
	v_mfma_f32_16x16x32_bf16 v[126:129], v[134:137], v[190:193], v[126:129]
	v_mfma_f32_16x16x32_bf16 v[122:125], v[156:159], v[190:193], v[122:125]
	v_mfma_f32_16x16x32_bf16 v[110:113], v[134:137], v[198:201], v[110:113]
	v_mfma_f32_16x16x32_bf16 v[106:109], v[156:159], v[198:201], v[106:109]
	v_mfma_f32_16x16x32_bf16 v[94:97], v[134:137], v[206:209], v[94:97]
	v_mfma_f32_16x16x32_bf16 v[90:93], v[156:159], v[206:209], v[90:93]
	v_mfma_f32_16x16x32_bf16 v[78:81], v[134:137], v[214:217], v[78:81]
	v_mfma_f32_16x16x32_bf16 v[74:77], v[156:159], v[214:217], v[74:77]
	v_mfma_f32_16x16x32_bf16 v[118:121], v[160:163], v[186:189], v[118:121]
	v_mfma_f32_16x16x32_bf16 v[114:117], v[178:181], v[186:189], v[114:117]
	v_mfma_f32_16x16x32_bf16 v[102:105], v[160:163], v[194:197], v[102:105]
	v_mfma_f32_16x16x32_bf16 v[98:101], v[178:181], v[194:197], v[98:101]
	v_mfma_f32_16x16x32_bf16 v[86:89], v[160:163], v[202:205], v[86:89]
	v_mfma_f32_16x16x32_bf16 v[82:85], v[178:181], v[202:205], v[82:85]
	v_mfma_f32_16x16x32_bf16 v[70:73], v[160:163], v[210:213], v[70:73]
	v_mfma_f32_16x16x32_bf16 v[66:69], v[178:181], v[210:213], v[66:69]
	v_mfma_f32_16x16x32_bf16 v[118:121], v[174:177], v[190:193], v[118:121]
	v_mfma_f32_16x16x32_bf16 v[114:117], v[182:185], v[190:193], v[114:117]
	v_mfma_f32_16x16x32_bf16 v[102:105], v[174:177], v[198:201], v[102:105]
	v_mfma_f32_16x16x32_bf16 v[98:101], v[182:185], v[198:201], v[98:101]
	v_mfma_f32_16x16x32_bf16 v[86:89], v[174:177], v[206:209], v[86:89]
	v_mfma_f32_16x16x32_bf16 v[82:85], v[182:185], v[206:209], v[82:85]
	v_mfma_f32_16x16x32_bf16 v[70:73], v[174:177], v[214:217], v[70:73]
	v_mfma_f32_16x16x32_bf16 v[66:69], v[182:185], v[214:217], v[66:69]
	s_barrier
; #define PG8_STAGEA(bufoff, gbase, voff) PG8_STAGE_X(bufoff, gbase, voff, AUXA)
; #define PG8_STAGEB(bufoff, gbase, voff) PG8_STAGE_X(bufoff, gbase, voff, AUXB)
; #define PG8_LDA(dst, b, h) do { _Pragma("unroll") for (int m = 0; m < 4; ++m) _Pragma("unroll") for (int k = 0; k < 2; ++k) dst[m][k] = *(const PG8_LAS bf16x8*)(lds + PG8_SA(b, h) + aoff + m * 2048 + k * 1024); } while (0)
; #define PG8_WAIT_V(n) asm volatile("s_waitcnt vmcnt(" #n ")" ::: "memory")
; #define PG8_WAIT_L(n) asm volatile("s_waitcnt lgkmcnt(" #n ")" ::: "memory")
;     ...
;         for (int t = t0; t < nt; t += 2) {
;             const bool last = (t == nt - 2);
;             const char* a1 = cA + (size_t)(t + 1) * kstepA;
;             const char* a2 = last ? nA : cA + (size_t)(t + 2) * kstepA; const char* b2 = last ? nB : cB + (size_t)(t + 2) * kstepB;
;             const char* a3 = a2 + kstepA; const char* b3 = b2 + kstepB;
;             if (last && has_next) S.a_ready(nxt);
;             if constexpr (SP2) {
;             PG8_LDB(B0, 0, 0); PG8_LDB(B1, 0, 1); PG8_SCHED; PG8_LDA(At, 0, 0); PG8_STAGEA(PG8_SA(1, 1), a1 + hstepA, voffA);
;     ...
;             const int relax = __builtin_amdgcn_readfirstlane((t == 0 && ui > 0) ? 1 : 0);
;             PG8_WAIT_VR(8, 24, relax); PG8_WAIT_L(0); PG8_BAR; PG8_MMA(0, 0, At, B0); PG8_MMA(0, 1, At, B1); PG8_BAR; PG8_SCHED;
;     ...
;             PG8_WAIT_V(8); PG8_WAIT_L(0); PG8_BAR; PG8_MMA(0, 0, At, B0); PG8_MMA(0, 1, At, B1); PG8_BAR; PG8_SCHED;
;     ...
;             PG8_LDA(At, 0, 1); PG8_STAGEB(PG8_SB(0, 0), b2, voffB); PG8_STAGEB(PG8_SB(0, 1), b2 + hstepB, voffB); PG8_STAGEA(PG8_SA(0, 0), a2, voffA);
;     ...
;             PG8_WAIT_VR(8, 24, relax); PG8_WAIT_L(0); PG8_BAR; PG8_MMA(1, 0, At, B0); PG8_MMA(1, 1, At, B1); PG8_BAR; PG8_SCHED;
;     ...
;             PG8_WAIT_V(8); PG8_WAIT_L(0); PG8_BAR; PG8_MMA(1, 0, At, B0); PG8_MMA(1, 1, At, B1); PG8_BAR; PG8_SCHED;
;     ...
;             PG8_LDB(B0, 1, 0); PG8_LDB(B1, 1, 1); PG8_SCHED; PG8_LDA(At, 1, 0); PG8_STAGEA(PG8_SA(0, 1), a2 + hstepA, voffA);
;             PG8_WAIT_V(8); PG8_WAIT_L(0); PG8_BAR; PG8_MMA(0, 0, At, B0); PG8_MMA(0, 1, At, B1); PG8_BAR; PG8_SCHED;
;             PG8_LDA(At, 1, 1); PG8_STAGEB(PG8_SB(1, 0), b3, voffB); PG8_STAGEB(PG8_SB(1, 1), b3 + hstepB, voffB); PG8_STAGEA(PG8_SA(1, 0), a3, voffA);
;             PG8_WAIT_V(8); PG8_WAIT_L(0); PG8_BAR; PG8_MMA(1, 0, At, B0); PG8_MMA(1, 1, At, B1); PG8_BAR; PG8_SCHED;
	s_add_i32 s14, s18, s42
	v_lshl_add_u64 v[164:165], v[164:165], 0, s[86:87]
	s_mov_b32 m0, s14
	ds_read_b128 v[186:189], v172 offset:49152
	ds_read_b128 v[190:193], v172 offset:50176
	ds_read_b128 v[194:197], v172 offset:51200
	ds_read_b128 v[198:201], v172 offset:52224
	ds_read_b128 v[202:205], v172 offset:53248
	ds_read_b128 v[206:209], v172 offset:54272
	ds_read_b128 v[210:213], v172 offset:55296
	ds_read_b128 v[214:217], v172 offset:56320
	global_load_lds_dwordx4 v[164:165], off
	s_add_i32 m0, s14, 0x2000
	s_add_u32 s10, s10, 0x100080
	v_lshl_add_u64 v[164:165], v[218:219], 0, s[86:87]
	s_addc_u32 s11, s11, 0
	s_add_i32 s14, s19, s42
	global_load_lds_dwordx4 v[164:165], off
	v_lshl_add_u64 v[164:165], s[10:11], 0, v[142:143]
	s_mov_b32 m0, s14
	s_nop 0
	global_load_lds_dwordx4 v[164:165], off
	v_lshl_add_u64 v[164:165], s[10:11], 0, v[138:139]
	s_add_i32 m0, s14, 0x2000
	s_nop 0
	global_load_lds_dwordx4 v[164:165], off
	v_lshl_add_u64 v[164:165], v[220:221], 0, s[86:87]
	s_mov_b32 m0, s73
	s_nop 0
	global_load_lds_dwordx4 v[164:165], off
	v_lshl_add_u64 v[164:165], v[222:223], 0, s[86:87]
	s_mov_b32 m0, s82
	s_nop 0
	global_load_lds_dwordx4 v[164:165], off
	s_waitcnt vmcnt(8) lgkmcnt(0)
	s_barrier
	v_mfma_f32_16x16x32_bf16 v[62:65], v[130:133], v[186:189], v[62:65]
	v_mfma_f32_16x16x32_bf16 v[58:61], v[152:155], v[186:189], v[58:61]
	v_mfma_f32_16x16x32_bf16 v[46:49], v[130:133], v[194:197], v[46:49]
	v_mfma_f32_16x16x32_bf16 v[42:45], v[152:155], v[194:197], v[42:45]
	v_mfma_f32_16x16x32_bf16 v[30:33], v[130:133], v[202:205], v[30:33]
	v_mfma_f32_16x16x32_bf16 v[26:29], v[152:155], v[202:205], v[26:29]
	v_mfma_f32_16x16x32_bf16 v[12:15], v[130:133], v[210:213], v[12:15]
	v_mfma_f32_16x16x32_bf16 v[8:11], v[152:155], v[210:213], v[8:11]
	v_mfma_f32_16x16x32_bf16 v[62:65], v[134:137], v[190:193], v[62:65]
	v_mfma_f32_16x16x32_bf16 v[58:61], v[156:159], v[190:193], v[58:61]
	v_mfma_f32_16x16x32_bf16 v[46:49], v[134:137], v[198:201], v[46:49]
	v_mfma_f32_16x16x32_bf16 v[42:45], v[156:159], v[198:201], v[42:45]
	v_mfma_f32_16x16x32_bf16 v[30:33], v[134:137], v[206:209], v[30:33]
	v_mfma_f32_16x16x32_bf16 v[26:29], v[156:159], v[206:209], v[26:29]
	v_mfma_f32_16x16x32_bf16 v[12:15], v[134:137], v[214:217], v[12:15]
	v_mfma_f32_16x16x32_bf16 v[8:11], v[156:159], v[214:217], v[8:11]
	v_mfma_f32_16x16x32_bf16 v[54:57], v[160:163], v[186:189], v[54:57]
	v_mfma_f32_16x16x32_bf16 v[50:53], v[178:181], v[186:189], v[50:53]
	v_mfma_f32_16x16x32_bf16 v[38:41], v[160:163], v[194:197], v[38:41]
	v_mfma_f32_16x16x32_bf16 v[34:37], v[178:181], v[194:197], v[34:37]
	v_mfma_f32_16x16x32_bf16 v[22:25], v[160:163], v[202:205], v[22:25]
	v_mfma_f32_16x16x32_bf16 v[18:21], v[178:181], v[202:205], v[18:21]
	v_mfma_f32_16x16x32_bf16 v[4:7], v[160:163], v[210:213], v[4:7]
	v_mfma_f32_16x16x32_bf16 v[0:3], v[178:181], v[210:213], v[0:3]
	v_mfma_f32_16x16x32_bf16 v[54:57], v[174:177], v[190:193], v[54:57]
	v_mfma_f32_16x16x32_bf16 v[50:53], v[182:185], v[190:193], v[50:53]
	v_mfma_f32_16x16x32_bf16 v[38:41], v[174:177], v[198:201], v[38:41]
	v_mfma_f32_16x16x32_bf16 v[34:37], v[182:185], v[198:201], v[34:37]
	v_mfma_f32_16x16x32_bf16 v[22:25], v[174:177], v[206:209], v[22:25]
	v_mfma_f32_16x16x32_bf16 v[18:21], v[182:185], v[206:209], v[18:21]
	v_mfma_f32_16x16x32_bf16 v[4:7], v[174:177], v[214:217], v[4:7]
	v_mfma_f32_16x16x32_bf16 v[0:3], v[182:185], v[214:217], v[0:3]
	s_barrier
	s_add_i32 s27, s27, 2
	s_add_u32 s8, s8, 0x100
	s_addc_u32 s9, s9, 0
	s_add_u32 s0, s0, 0x100
	s_addc_u32 s1, s1, 0
	v_add_u32_e32 v226, 0x10000, v167
.LBB0_129:
	s_add_u32 s10, s8, 0xfff00080
	s_addc_u32 s11, s9, -1
	s_add_i32 s18, 0, 0x10000
	s_cmp_eq_u32 s27, 60
	s_cselect_b32 s15, s4, s11
	s_cselect_b32 s14, s5, s10
	s_cselect_b32 s11, s16, s1
	s_cselect_b32 s10, s17, s0
	s_add_i32 s20, 0, 0x14000
	s_waitcnt lgkmcnt(0)
	ds_read_b128 v[130:133], v226
	ds_read_b128 v[134:137], v226 offset:1024
	ds_read_b128 v[152:155], v226 offset:2048
	ds_read_b128 v[156:159], v226 offset:3072
	ds_read_b128 v[160:163], v226 offset:16384
	ds_read_b128 v[174:177], v226 offset:17408
	ds_read_b128 v[178:181], v226 offset:18432
	ds_read_b128 v[182:185], v226 offset:19456
	s_add_i32 m0, s51, 0xc000
	ds_read_b128 v[186:189], v172
	ds_read_b128 v[190:193], v172 offset:1024
	ds_read_b128 v[194:197], v172 offset:2048
	ds_read_b128 v[198:201], v172 offset:3072
	ds_read_b128 v[202:205], v172 offset:4096
	ds_read_b128 v[206:209], v172 offset:5120
	ds_read_b128 v[210:213], v172 offset:6144
	global_load_lds_dwordx4 v148, s[8:9]
	s_add_i32 m0, s51, 0xe000
	ds_read_b128 v[214:217], v172 offset:7168
	global_load_lds_dwordx4 v150, s[8:9]
	s_waitcnt vmcnt(8) lgkmcnt(0)
	s_nop 0
	s_barrier
; #define PG8_STAGEA(bufoff, gbase, voff) PG8_STAGE_X(bufoff, gbase, voff, AUXA)
; #define PG8_STAGEB(bufoff, gbase, voff) PG8_STAGE_X(bufoff, gbase, voff, AUXB)
; #define PG8_LDA(dst, b, h) do { _Pragma("unroll") for (int m = 0; m < 4; ++m) _Pragma("unroll") for (int k = 0; k < 2; ++k) dst[m][k] = *(const PG8_LAS bf16x8*)(lds + PG8_SA(b, h) + aoff + m * 2048 + k * 1024); } while (0)
; #define PG8_LDB(dst, b, h) do { _Pragma("unroll") for (int n = 0; n < 2; ++n) _Pragma("unroll") for (int k = 0; k < 2; ++k) dst[n][k] = *(const PG8_LAS bf16x8*)(lds + PG8_SB(b, h) + boff + n * 2048 + k * 1024); } while (0)
; #define PG8_MMA(ai, bj, At, Bt) do { if (GEMM_PRIO_MODE == 0) __builtin_amdgcn_s_setprio(1); PG8_MMA_LOOPS \
;         acc[ai][bj][m][n] = __builtin_amdgcn_mfma_f32_16x16x32_bf16(Bt[n][k], At[m][k], acc[ai][bj][m][n], 0, 0, 0); if (GEMM_PRIO_MODE == 0) __builtin_amdgcn_s_setprio(0); } while (0)
; #define PG8_WAIT_V(n) asm volatile("s_waitcnt vmcnt(" #n ")" ::: "memory")
; #define PG8_WAIT_VR(n, nr, flag) asm volatile("s_cmp_eq_u32 %0, 0\n\ts_cbranch_scc1 .Lpg8s%=\n\ts_waitcnt vmcnt(" #nr ")\n\ts_branch .Lpg8d%=\n.Lpg8s%=:\n\ts_waitcnt vmcnt(" #n ")\n.Lpg8d%=:" :: "s"(flag) : "memory", "scc")
; #define PG8_WAIT_L(n) asm volatile("s_waitcnt lgkmcnt(" #n ")" ::: "memory")
; #define PG8_BAR __builtin_amdgcn_s_barrier()
; #define PG8_SCHED __builtin_amdgcn_sched_barrier(0)
;     ...
;             PG8_LDB(B0, 0, 0); PG8_LDB(B1, 0, 1); PG8_SCHED; PG8_LDA(At, 0, 0); PG8_STAGEA(PG8_SA(1, 1), a1 + hstepA, voffA);
;     ...
;             const int relax = __builtin_amdgcn_readfirstlane((t == 0 && ui > 0) ? 1 : 0);
;             PG8_WAIT_VR(8, 24, relax); PG8_WAIT_L(0); PG8_BAR; PG8_MMA(0, 0, At, B0); PG8_MMA(0, 1, At, B1); PG8_BAR; PG8_SCHED;
;     ...
;             PG8_WAIT_V(8); PG8_WAIT_L(0); PG8_BAR; PG8_MMA(0, 0, At, B0); PG8_MMA(0, 1, At, B1); PG8_BAR; PG8_SCHED;
;     ...
;             PG8_LDA(At, 0, 1); PG8_STAGEB(PG8_SB(0, 0), b2, voffB); PG8_STAGEB(PG8_SB(0, 1), b2 + hstepB, voffB); PG8_STAGEA(PG8_SA(0, 0), a2, voffA);
;     ...
;             PG8_WAIT_VR(8, 24, relax); PG8_WAIT_L(0); PG8_BAR; PG8_MMA(1, 0, At, B0); PG8_MMA(1, 1, At, B1); PG8_BAR; PG8_SCHED;
;     ...
;             PG8_WAIT_V(8); PG8_WAIT_L(0); PG8_BAR; PG8_MMA(1, 0, At, B0); PG8_MMA(1, 1, At, B1); PG8_BAR; PG8_SCHED;
	v_mfma_f32_16x16x32_bf16 v[126:129], v[130:133], v[186:189], v[126:129]
	v_mfma_f32_16x16x32_bf16 v[122:125], v[152:155], v[186:189], v[122:125]
	v_mfma_f32_16x16x32_bf16 v[110:113], v[130:133], v[194:197], v[110:113]
	v_mfma_f32_16x16x32_bf16 v[106:109], v[152:155], v[194:197], v[106:109]
	v_mfma_f32_16x16x32_bf16 v[94:97], v[130:133], v[202:205], v[94:97]
	v_mfma_f32_16x16x32_bf16 v[90:93], v[152:155], v[202:205], v[90:93]
	v_mfma_f32_16x16x32_bf16 v[78:81], v[130:133], v[210:213], v[78:81]
	v_mfma_f32_16x16x32_bf16 v[74:77], v[152:155], v[210:213], v[74:77]
	v_mfma_f32_16x16x32_bf16 v[126:129], v[134:137], v[190:193], v[126:129]
	v_mfma_f32_16x16x32_bf16 v[122:125], v[156:159], v[190:193], v[122:125]
	v_mfma_f32_16x16x32_bf16 v[110:113], v[134:137], v[198:201], v[110:113]
	v_mfma_f32_16x16x32_bf16 v[106:109], v[156:159], v[198:201], v[106:109]
	v_mfma_f32_16x16x32_bf16 v[94:97], v[134:137], v[206:209], v[94:97]
	v_mfma_f32_16x16x32_bf16 v[90:93], v[156:159], v[206:209], v[90:93]
	v_mfma_f32_16x16x32_bf16 v[78:81], v[134:137], v[214:217], v[78:81]
	v_mfma_f32_16x16x32_bf16 v[74:77], v[156:159], v[214:217], v[74:77]
	v_mfma_f32_16x16x32_bf16 v[118:121], v[160:163], v[186:189], v[118:121]
	v_mfma_f32_16x16x32_bf16 v[114:117], v[178:181], v[186:189], v[114:117]
	v_mfma_f32_16x16x32_bf16 v[102:105], v[160:163], v[194:197], v[102:105]
	v_mfma_f32_16x16x32_bf16 v[98:101], v[178:181], v[194:197], v[98:101]
	v_mfma_f32_16x16x32_bf16 v[86:89], v[160:163], v[202:205], v[86:89]
	v_mfma_f32_16x16x32_bf16 v[82:85], v[178:181], v[202:205], v[82:85]
	v_mfma_f32_16x16x32_bf16 v[70:73], v[160:163], v[210:213], v[70:73]
	v_mfma_f32_16x16x32_bf16 v[66:69], v[178:181], v[210:213], v[66:69]
	v_mfma_f32_16x16x32_bf16 v[118:121], v[174:177], v[190:193], v[118:121]
	v_mfma_f32_16x16x32_bf16 v[114:117], v[182:185], v[190:193], v[114:117]
	v_mfma_f32_16x16x32_bf16 v[102:105], v[174:177], v[198:201], v[102:105]
	v_mfma_f32_16x16x32_bf16 v[98:101], v[182:185], v[198:201], v[98:101]
	v_mfma_f32_16x16x32_bf16 v[86:89], v[174:177], v[206:209], v[86:89]
	v_mfma_f32_16x16x32_bf16 v[82:85], v[182:185], v[206:209], v[82:85]
	v_mfma_f32_16x16x32_bf16 v[70:73], v[174:177], v[214:217], v[70:73]
	v_mfma_f32_16x16x32_bf16 v[66:69], v[182:185], v[214:217], v[66:69]
	s_barrier
	s_add_i32 s18, s18, s42
	s_mov_b32 m0, s18
	ds_read_b128 v[186:189], v172 offset:16384
	ds_read_b128 v[190:193], v172 offset:17408
	ds_read_b128 v[194:197], v172 offset:18432
	ds_read_b128 v[198:201], v172 offset:19456
	s_add_u32 s100, s14, 0x80
	s_addc_u32 s101, s15, 0
	global_load_lds_dwordx4 v142, s[10:11]
	s_add_i32 m0, s18, 0x2000
	s_add_u32 s18, s10, 0x100000
	s_addc_u32 s19, s11, 0
	s_add_i32 s20, s20, s42
	global_load_lds_dwordx4 v138, s[10:11]
	s_mov_b32 m0, s20
	ds_read_b128 v[214:217], v172 offset:23552
	global_load_lds_dwordx4 v142, s[18:19]
	s_add_i32 m0, s20, 0x2000
	ds_read_b128 v[210:213], v172 offset:22528
	global_load_lds_dwordx4 v138, s[18:19]
	s_mov_b32 m0, s51
	ds_read_b128 v[206:209], v172 offset:21504
	global_load_lds_dwordx4 v144, s[14:15]
	s_mov_b32 m0, s68
	ds_read_b128 v[202:205], v172 offset:20480
	global_load_lds_dwordx4 v140, s[14:15]
	s_waitcnt vmcnt(8) lgkmcnt(0)
	s_nop 0
	s_barrier
	v_mfma_f32_16x16x32_bf16 v[62:65], v[130:133], v[186:189], v[62:65]
	v_mfma_f32_16x16x32_bf16 v[58:61], v[152:155], v[186:189], v[58:61]
	v_mfma_f32_16x16x32_bf16 v[46:49], v[130:133], v[194:197], v[46:49]
	v_mfma_f32_16x16x32_bf16 v[42:45], v[152:155], v[194:197], v[42:45]
	v_mfma_f32_16x16x32_bf16 v[30:33], v[130:133], v[202:205], v[30:33]
	v_mfma_f32_16x16x32_bf16 v[26:29], v[152:155], v[202:205], v[26:29]
	v_mfma_f32_16x16x32_bf16 v[12:15], v[130:133], v[210:213], v[12:15]
	v_mfma_f32_16x16x32_bf16 v[8:11], v[152:155], v[210:213], v[8:11]
	v_mfma_f32_16x16x32_bf16 v[62:65], v[134:137], v[190:193], v[62:65]
	v_mfma_f32_16x16x32_bf16 v[58:61], v[156:159], v[190:193], v[58:61]
	v_mfma_f32_16x16x32_bf16 v[46:49], v[134:137], v[198:201], v[46:49]
	v_mfma_f32_16x16x32_bf16 v[42:45], v[156:159], v[198:201], v[42:45]
	v_mfma_f32_16x16x32_bf16 v[30:33], v[134:137], v[206:209], v[30:33]
	v_mfma_f32_16x16x32_bf16 v[26:29], v[156:159], v[206:209], v[26:29]
	v_mfma_f32_16x16x32_bf16 v[12:15], v[134:137], v[214:217], v[12:15]
	v_mfma_f32_16x16x32_bf16 v[8:11], v[156:159], v[214:217], v[8:11]
	v_mfma_f32_16x16x32_bf16 v[54:57], v[160:163], v[186:189], v[54:57]
	v_mfma_f32_16x16x32_bf16 v[50:53], v[178:181], v[186:189], v[50:53]
	v_mfma_f32_16x16x32_bf16 v[38:41], v[160:163], v[194:197], v[38:41]
	v_mfma_f32_16x16x32_bf16 v[34:37], v[178:181], v[194:197], v[34:37]
	v_mfma_f32_16x16x32_bf16 v[22:25], v[160:163], v[202:205], v[22:25]
	v_mfma_f32_16x16x32_bf16 v[18:21], v[178:181], v[202:205], v[18:21]
	v_mfma_f32_16x16x32_bf16 v[4:7], v[160:163], v[210:213], v[4:7]
	v_mfma_f32_16x16x32_bf16 v[0:3], v[178:181], v[210:213], v[0:3]
	v_mfma_f32_16x16x32_bf16 v[54:57], v[174:177], v[190:193], v[54:57]
	v_mfma_f32_16x16x32_bf16 v[50:53], v[182:185], v[190:193], v[50:53]
	v_mfma_f32_16x16x32_bf16 v[38:41], v[174:177], v[198:201], v[38:41]
	v_mfma_f32_16x16x32_bf16 v[34:37], v[182:185], v[198:201], v[34:37]
	v_mfma_f32_16x16x32_bf16 v[22:25], v[174:177], v[206:209], v[22:25]
	v_mfma_f32_16x16x32_bf16 v[18:21], v[182:185], v[206:209], v[18:21]
	v_mfma_f32_16x16x32_bf16 v[4:7], v[174:177], v[214:217], v[4:7]
	v_mfma_f32_16x16x32_bf16 v[0:3], v[182:185], v[214:217], v[0:3]
	s_barrier
; #define PG8_STAGEA(bufoff, gbase, voff) PG8_STAGE_X(bufoff, gbase, voff, AUXA)
; #define PG8_STAGEB(bufoff, gbase, voff) PG8_STAGE_X(bufoff, gbase, voff, AUXB)
; #define PG8_LDA(dst, b, h) do { _Pragma("unroll") for (int m = 0; m < 4; ++m) _Pragma("unroll") for (int k = 0; k < 2; ++k) dst[m][k] = *(const PG8_LAS bf16x8*)(lds + PG8_SA(b, h) + aoff + m * 2048 + k * 1024); } while (0)
; #define PG8_LDB(dst, b, h) do { _Pragma("unroll") for (int n = 0; n < 2; ++n) _Pragma("unroll") for (int k = 0; k < 2; ++k) dst[n][k] = *(const PG8_LAS bf16x8*)(lds + PG8_SB(b, h) + boff + n * 2048 + k * 1024); } while (0)
; #define PG8_MMA(ai, bj, At, Bt) do { if (GEMM_PRIO_MODE == 0) __builtin_amdgcn_s_setprio(1); PG8_MMA_LOOPS \
;         acc[ai][bj][m][n] = __builtin_amdgcn_mfma_f32_16x16x32_bf16(Bt[n][k], At[m][k], acc[ai][bj][m][n], 0, 0, 0); if (GEMM_PRIO_MODE == 0) __builtin_amdgcn_s_setprio(0); } while (0)
; #define PG8_WAIT_V(n) asm volatile("s_waitcnt vmcnt(" #n ")" ::: "memory")
; #define PG8_WAIT_L(n) asm volatile("s_waitcnt lgkmcnt(" #n ")" ::: "memory")
; #define PG8_BAR __builtin_amdgcn_s_barrier()
; #define PG8_SCHED __builtin_amdgcn_sched_barrier(0)
;     ...
;         for (int t = t0; t < nt; t += 2) {
;             const bool last = (t == nt - 2);
;             const char* a1 = cA + (size_t)(t + 1) * kstepA;
;             const char* a2 = last ? nA : cA + (size_t)(t + 2) * kstepA; const char* b2 = last ? nB : cB + (size_t)(t + 2) * kstepB;
;     ...
;             PG8_LDB(B0, 1, 0); PG8_LDB(B1, 1, 1); PG8_SCHED; PG8_LDA(At, 1, 0); PG8_STAGEA(PG8_SA(0, 1), a2 + hstepA, voffA);
;             PG8_WAIT_V(8); PG8_WAIT_L(0); PG8_BAR; PG8_MMA(0, 0, At, B0); PG8_MMA(0, 1, At, B1); PG8_BAR; PG8_SCHED;
;             PG8_LDA(At, 1, 1); PG8_STAGEB(PG8_SB(1, 0), b3, voffB); PG8_STAGEB(PG8_SB(1, 1), b3 + hstepB, voffB); PG8_STAGEA(PG8_SA(1, 0), a3, voffA);
;             PG8_WAIT_V(8); PG8_WAIT_L(0); PG8_BAR; PG8_MMA(1, 0, At, B0); PG8_MMA(1, 1, At, B1); PG8_BAR; PG8_SCHED;
	s_add_i32 s18, 0, 0x18000
	s_add_i32 s19, 0, 0x1c000
	ds_read_b128 v[130:133], v226 offset:32768
	ds_read_b128 v[134:137], v226 offset:33792
	ds_read_b128 v[152:155], v226 offset:34816
	ds_read_b128 v[156:159], v226 offset:35840
	ds_read_b128 v[160:163], v226 offset:49152
	ds_read_b128 v[174:177], v226 offset:50176
	ds_read_b128 v[178:181], v226 offset:51200
	ds_read_b128 v[182:185], v226 offset:52224
	s_add_u32 s14, s14, 0x100000
	s_addc_u32 s15, s15, 0
	s_mov_b32 m0, s69
	ds_read_b128 v[186:189], v172 offset:32768
	ds_read_b128 v[190:193], v172 offset:33792
	ds_read_b128 v[194:197], v172 offset:34816
	ds_read_b128 v[198:201], v172 offset:35840
	ds_read_b128 v[202:205], v172 offset:36864
	ds_read_b128 v[206:209], v172 offset:37888
	ds_read_b128 v[210:213], v172 offset:38912
	global_load_lds_dwordx4 v144, s[14:15]
	s_mov_b32 m0, s72
	ds_read_b128 v[214:217], v172 offset:39936
	global_load_lds_dwordx4 v140, s[14:15]
	s_waitcnt vmcnt(8) lgkmcnt(0)
	s_barrier
	v_mfma_f32_16x16x32_bf16 v[126:129], v[130:133], v[186:189], v[126:129]
	v_mfma_f32_16x16x32_bf16 v[122:125], v[152:155], v[186:189], v[122:125]
	v_mfma_f32_16x16x32_bf16 v[110:113], v[130:133], v[194:197], v[110:113]
	v_mfma_f32_16x16x32_bf16 v[106:109], v[152:155], v[194:197], v[106:109]
	v_mfma_f32_16x16x32_bf16 v[94:97], v[130:133], v[202:205], v[94:97]
	v_mfma_f32_16x16x32_bf16 v[90:93], v[152:155], v[202:205], v[90:93]
	v_mfma_f32_16x16x32_bf16 v[78:81], v[130:133], v[210:213], v[78:81]
	v_mfma_f32_16x16x32_bf16 v[74:77], v[152:155], v[210:213], v[74:77]
	v_mfma_f32_16x16x32_bf16 v[126:129], v[134:137], v[190:193], v[126:129]
	v_mfma_f32_16x16x32_bf16 v[122:125], v[156:159], v[190:193], v[122:125]
	v_mfma_f32_16x16x32_bf16 v[110:113], v[134:137], v[198:201], v[110:113]
	v_mfma_f32_16x16x32_bf16 v[106:109], v[156:159], v[198:201], v[106:109]
	v_mfma_f32_16x16x32_bf16 v[94:97], v[134:137], v[206:209], v[94:97]
	v_mfma_f32_16x16x32_bf16 v[90:93], v[156:159], v[206:209], v[90:93]
	v_mfma_f32_16x16x32_bf16 v[78:81], v[134:137], v[214:217], v[78:81]
	v_mfma_f32_16x16x32_bf16 v[74:77], v[156:159], v[214:217], v[74:77]
	v_mfma_f32_16x16x32_bf16 v[118:121], v[160:163], v[186:189], v[118:121]
	v_mfma_f32_16x16x32_bf16 v[114:117], v[178:181], v[186:189], v[114:117]
	v_mfma_f32_16x16x32_bf16 v[102:105], v[160:163], v[194:197], v[102:105]
	v_mfma_f32_16x16x32_bf16 v[98:101], v[178:181], v[194:197], v[98:101]
	v_mfma_f32_16x16x32_bf16 v[86:89], v[160:163], v[202:205], v[86:89]
	v_mfma_f32_16x16x32_bf16 v[82:85], v[178:181], v[202:205], v[82:85]
	v_mfma_f32_16x16x32_bf16 v[70:73], v[160:163], v[210:213], v[70:73]
	v_mfma_f32_16x16x32_bf16 v[66:69], v[178:181], v[210:213], v[66:69]
	v_mfma_f32_16x16x32_bf16 v[118:121], v[174:177], v[190:193], v[118:121]
	v_mfma_f32_16x16x32_bf16 v[114:117], v[182:185], v[190:193], v[114:117]
	v_mfma_f32_16x16x32_bf16 v[102:105], v[174:177], v[198:201], v[102:105]
	v_mfma_f32_16x16x32_bf16 v[98:101], v[182:185], v[198:201], v[98:101]
	v_mfma_f32_16x16x32_bf16 v[86:89], v[174:177], v[206:209], v[86:89]
	v_mfma_f32_16x16x32_bf16 v[82:85], v[182:185], v[206:209], v[82:85]
	v_mfma_f32_16x16x32_bf16 v[70:73], v[174:177], v[214:217], v[70:73]
	v_mfma_f32_16x16x32_bf16 v[66:69], v[182:185], v[214:217], v[66:69]
	s_barrier
	s_add_i32 s14, s18, s42
	s_mov_b32 m0, s14
	ds_read_b128 v[186:189], v172 offset:49152
	ds_read_b128 v[190:193], v172 offset:50176
	ds_read_b128 v[194:197], v172 offset:51200
	ds_read_b128 v[198:201], v172 offset:52224
	s_add_u32 vcc_lo, s10, 0x80
	s_addc_u32 vcc_hi, s11, 0
	global_load_lds_dwordx4 v142, vcc
	s_add_i32 m0, s14, 0x2000
	s_add_u32 s10, s10, 0x100080
	s_addc_u32 s11, s11, 0
	s_add_i32 s14, s19, s42
	global_load_lds_dwordx4 v138, vcc
	s_mov_b32 m0, s14
	ds_read_b128 v[214:217], v172 offset:56320
	global_load_lds_dwordx4 v142, s[10:11]
	s_add_i32 m0, s14, 0x2000
	ds_read_b128 v[210:213], v172 offset:55296
	global_load_lds_dwordx4 v138, s[10:11]
	s_mov_b32 m0, s73
	ds_read_b128 v[206:209], v172 offset:54272
	global_load_lds_dwordx4 v144, s[100:101]
	s_mov_b32 m0, s82
	ds_read_b128 v[202:205], v172 offset:53248
	global_load_lds_dwordx4 v140, s[100:101]
	s_waitcnt vmcnt(8) lgkmcnt(0)
	s_nop 0
	s_barrier
	v_mfma_f32_16x16x32_bf16 v[62:65], v[130:133], v[186:189], v[62:65]
	v_mfma_f32_16x16x32_bf16 v[58:61], v[152:155], v[186:189], v[58:61]
	v_mfma_f32_16x16x32_bf16 v[46:49], v[130:133], v[194:197], v[46:49]
	v_mfma_f32_16x16x32_bf16 v[42:45], v[152:155], v[194:197], v[42:45]
	v_mfma_f32_16x16x32_bf16 v[30:33], v[130:133], v[202:205], v[30:33]
	v_mfma_f32_16x16x32_bf16 v[26:29], v[152:155], v[202:205], v[26:29]
	v_mfma_f32_16x16x32_bf16 v[12:15], v[130:133], v[210:213], v[12:15]
	v_mfma_f32_16x16x32_bf16 v[8:11], v[152:155], v[210:213], v[8:11]
	v_mfma_f32_16x16x32_bf16 v[62:65], v[134:137], v[190:193], v[62:65]
	v_mfma_f32_16x16x32_bf16 v[58:61], v[156:159], v[190:193], v[58:61]
	v_mfma_f32_16x16x32_bf16 v[46:49], v[134:137], v[198:201], v[46:49]
	v_mfma_f32_16x16x32_bf16 v[42:45], v[156:159], v[198:201], v[42:45]
	v_mfma_f32_16x16x32_bf16 v[30:33], v[134:137], v[206:209], v[30:33]
	v_mfma_f32_16x16x32_bf16 v[26:29], v[156:159], v[206:209], v[26:29]
	v_mfma_f32_16x16x32_bf16 v[12:15], v[134:137], v[214:217], v[12:15]
	v_mfma_f32_16x16x32_bf16 v[8:11], v[156:159], v[214:217], v[8:11]
	v_mfma_f32_16x16x32_bf16 v[54:57], v[160:163], v[186:189], v[54:57]
	v_mfma_f32_16x16x32_bf16 v[50:53], v[178:181], v[186:189], v[50:53]
	v_mfma_f32_16x16x32_bf16 v[38:41], v[160:163], v[194:197], v[38:41]
	v_mfma_f32_16x16x32_bf16 v[34:37], v[178:181], v[194:197], v[34:37]
	v_mfma_f32_16x16x32_bf16 v[22:25], v[160:163], v[202:205], v[22:25]
	v_mfma_f32_16x16x32_bf16 v[18:21], v[178:181], v[202:205], v[18:21]
	v_mfma_f32_16x16x32_bf16 v[4:7], v[160:163], v[210:213], v[4:7]
	v_mfma_f32_16x16x32_bf16 v[0:3], v[178:181], v[210:213], v[0:3]
	v_mfma_f32_16x16x32_bf16 v[54:57], v[174:177], v[190:193], v[54:57]
	v_mfma_f32_16x16x32_bf16 v[50:53], v[182:185], v[190:193], v[50:53]
	v_mfma_f32_16x16x32_bf16 v[38:41], v[174:177], v[198:201], v[38:41]
	v_mfma_f32_16x16x32_bf16 v[34:37], v[182:185], v[198:201], v[34:37]
	v_mfma_f32_16x16x32_bf16 v[22:25], v[174:177], v[206:209], v[22:25]
	v_mfma_f32_16x16x32_bf16 v[18:21], v[182:185], v[206:209], v[18:21]
	v_mfma_f32_16x16x32_bf16 v[4:7], v[174:177], v[214:217], v[4:7]
	v_mfma_f32_16x16x32_bf16 v[0:3], v[182:185], v[214:217], v[0:3]
	s_barrier
	s_add_i32 s27, s27, 2
	s_add_u32 s8, s8, 0x100
	s_addc_u32 s9, s9, 0
	s_add_u32 s0, s0, 0x100
	s_addc_u32 s1, s1, 0
	s_cmp_gt_u32 s27, 61
	s_cbranch_scc0 .LBB0_129
	s_and_b64 vcc, exec, s[24:25]
	s_cbranch_vccz .LBB0_132
	s_barrier

; #define PG8_STAGEA(bufoff, gbase, voff) PG8_STAGE_X(bufoff, gbase, voff, AUXA)
; #define PG8_STR(x) PG8_STR2(x)
;     ...
;         const bool has_next = S.next(ui + 1, nxt);
;         const char* nA = has_next ? (const char*)g.A + (size_t)nxt.pm * tstepA : cA; const char* nB = has_next ? (const char*)g.Bt + (size_t)nxt.pn * tstepB : cB;
;         int t0 = 0;
;         if constexpr (SP2 && GEMM_RELAX == 1) { if (ui > 0) {
;             const char* a1 = cA + kstepA; const char* a2 = cA + 2 * kstepA; const char* b2 = cB + 2 * kstepB; const char* a3 = a2 + kstepA; const char* b3 = b2 + kstepB;
;             PG8_LDB(B0, 0, 0); PG8_LDB(B1, 0, 1); PG8_SCHED; PG8_LDA(At, 0, 0); PG8_STAGEA(PG8_SA(1, 1), a1 + hstepA, voffA);
;             PG8_WAIT_V(24); PG8_WAIT_L(0); PG8_BAR; PG8_MMA(0, 0, At, B0); PG8_MMA(0, 1, At, B1); PG8_BAR; PG8_SCHED;
;             PG8_LDA(At, 0, 1); PG8_STAGEB(PG8_SB(0, 0), b2, voffB); PG8_STAGEB(PG8_SB(0, 1), b2 + hstepB, voffB); PG8_STAGEA(PG8_SA(0, 0), a2, voffA);
;             PG8_WAIT_V(24); PG8_WAIT_L(0); PG8_BAR; PG8_MMA(1, 0, At, B0); PG8_MMA(1, 1, At, B1); PG8_BAR; PG8_SCHED;
;             PG8_LDB(B0, 1, 0); PG8_LDB(B1, 1, 1); PG8_SCHED; PG8_LDA(At, 1, 0); PG8_STAGEA(PG8_SA(0, 1), a2 + hstepA, voffA);
;             PG8_WAIT_V(8); PG8_WAIT_L(0); PG8_BAR; PG8_MMA(0, 0, At, B0); PG8_MMA(0, 1, At, B1); PG8_BAR; PG8_SCHED;
;             PG8_LDA(At, 1, 1); PG8_STAGEB(PG8_SB(1, 0), b3, voffB); PG8_STAGEB(PG8_SB(1, 1), b3 + hstepB, voffB); PG8_STAGEA(PG8_SA(1, 0), a3, voffA);
;             PG8_WAIT_V(8); PG8_WAIT_L(0); PG8_BAR; PG8_MMA(1, 0, At, B0); PG8_MMA(1, 1, At, B1); PG8_BAR; PG8_SCHED;
;             t0 = 2; } }
;     ...
;         asm volatile(".p2align " PG8_STR(GEMM_LOOP_ALIGN) ::: "memory");
;     ...
;         for (int t = t0; t < nt; t += 2) {
;             const bool last = (t == nt - 2);
;             const char* a1 = cA + (size_t)(t + 1) * kstepA;
;             const char* a2 = last ? nA : cA + (size_t)(t + 2) * kstepA; const char* b2 = last ? nB : cB + (size_t)(t + 2) * kstepB;
;             const char* a3 = a2 + kstepA; const char* b3 = b2 + kstepB;
;             if (last && has_next) S.a_ready(nxt);
;             if constexpr (SP2) {
;             PG8_LDB(B0, 0, 0); PG8_LDB(B1, 0, 1); PG8_SCHED; PG8_LDA(At, 0, 0); PG8_STAGEA(PG8_SA(1, 1), a1 + hstepA, voffA);
;     ...
;             const int relax = __builtin_amdgcn_readfirstlane((t == 0 && ui > 0) ? 1 : 0);
.LBB0_557:
	s_ashr_i32 s21, s20, 31
	s_lshl_b64 s[6:7], s[20:21], 21
	s_add_u32 s24, s60, s6
	s_addc_u32 s25, s61, s7
	s_and_b64 s[6:7], s[26:27], exec
	s_cselect_b32 s21, s25, s1
	s_cselect_b32 s82, s24, s0
	s_ashr_i32 s23, s22, 31
	s_lshl_b64 s[6:7], s[22:23], 21
	s_add_u32 s36, s4, s6
	s_addc_u32 s37, s5, s7
	s_and_b64 s[6:7], s[26:27], exec
	s_cselect_b32 s23, s37, s41
	s_cselect_b32 s83, s36, s40
	s_add_u32 s38, s0, 0x100080
	s_addc_u32 s39, s1, 0
	s_add_u32 s0, s40, 0x100
	s_addc_u32 s1, s41, 0
	s_mov_b32 s90, -2
	s_waitcnt lgkmcnt(0)
	s_waitcnt vmcnt(0)
	s_add_u32 s6, s38, 0xfff00080
	s_addc_u32 s7, s39, -1
	s_add_i32 s91, 0, 0x10000
	s_cmp_eq_u32 s90, 60
	s_cselect_b32 s41, s21, s7
	s_cselect_b32 s40, s82, s6
	s_cselect_b32 s17, s23, s1
	s_cselect_b32 s16, s83, s0
	s_add_i32 s94, 0, 0x14000
	v_add_u32_e32 v152, s91, v157
	v_add_u32_e32 v174, s94, v157
	ds_read_b128 v[130:133], v152
	ds_read_b128 v[134:137], v152 offset:1024
	ds_read_b128 v[148:151], v152 offset:2048
	ds_read_b128 v[152:155], v152 offset:3072
	ds_read_b128 v[162:165], v174
	ds_read_b128 v[166:169], v174 offset:1024
	ds_read_b128 v[170:173], v174 offset:2048
	ds_read_b128 v[174:177], v174 offset:3072
	v_lshl_add_u64 v[210:211], s[38:39], 0, v[144:145]
	s_add_i32 m0, s13, 0xc000
	ds_read_b128 v[178:181], v161
	ds_read_b128 v[182:185], v161 offset:1024
	ds_read_b128 v[186:189], v161 offset:2048
	ds_read_b128 v[190:193], v161 offset:3072
	ds_read_b128 v[194:197], v161 offset:4096
	ds_read_b128 v[198:201], v161 offset:5120
	ds_read_b128 v[202:205], v161 offset:6144
	ds_read_b128 v[206:209], v161 offset:7168
	global_load_lds_dwordx4 v[210:211], off
	v_lshl_add_u64 v[210:211], s[38:39], 0, v[146:147]
	s_add_i32 m0, s13, 0xe000
	s_nop 0
	global_load_lds_dwordx4 v[210:211], off
	s_waitcnt vmcnt(8) lgkmcnt(0)
	s_nop 0
	s_barrier
	v_mfma_f32_16x16x32_bf16 v[126:129], v[130:133], v[178:181], 0
	v_mfma_f32_16x16x32_bf16 v[122:125], v[148:151], v[178:181], 0
	v_mfma_f32_16x16x32_bf16 v[110:113], v[130:133], v[186:189], 0
	v_mfma_f32_16x16x32_bf16 v[106:109], v[148:151], v[186:189], 0
	v_mfma_f32_16x16x32_bf16 v[94:97], v[130:133], v[194:197], 0
	v_mfma_f32_16x16x32_bf16 v[90:93], v[148:151], v[194:197], 0
	v_mfma_f32_16x16x32_bf16 v[78:81], v[130:133], v[202:205], 0
	v_mfma_f32_16x16x32_bf16 v[74:77], v[148:151], v[202:205], 0
	v_mfma_f32_16x16x32_bf16 v[126:129], v[134:137], v[182:185], v[126:129]
	v_mfma_f32_16x16x32_bf16 v[122:125], v[152:155], v[182:185], v[122:125]
	v_mfma_f32_16x16x32_bf16 v[110:113], v[134:137], v[190:193], v[110:113]
	v_mfma_f32_16x16x32_bf16 v[106:109], v[152:155], v[190:193], v[106:109]
	v_mfma_f32_16x16x32_bf16 v[94:97], v[134:137], v[198:201], v[94:97]
	v_mfma_f32_16x16x32_bf16 v[90:93], v[152:155], v[198:201], v[90:93]
	v_mfma_f32_16x16x32_bf16 v[78:81], v[134:137], v[206:209], v[78:81]
	v_mfma_f32_16x16x32_bf16 v[74:77], v[152:155], v[206:209], v[74:77]
	v_mfma_f32_16x16x32_bf16 v[118:121], v[162:165], v[178:181], 0
	v_mfma_f32_16x16x32_bf16 v[114:117], v[170:173], v[178:181], 0
	v_mfma_f32_16x16x32_bf16 v[102:105], v[162:165], v[186:189], 0
	v_mfma_f32_16x16x32_bf16 v[98:101], v[170:173], v[186:189], 0
	v_mfma_f32_16x16x32_bf16 v[86:89], v[162:165], v[194:197], 0
	v_mfma_f32_16x16x32_bf16 v[82:85], v[170:173], v[194:197], 0
	v_mfma_f32_16x16x32_bf16 v[70:73], v[162:165], v[202:205], 0
	v_mfma_f32_16x16x32_bf16 v[66:69], v[170:173], v[202:205], 0
	v_mfma_f32_16x16x32_bf16 v[118:121], v[166:169], v[182:185], v[118:121]
	v_mfma_f32_16x16x32_bf16 v[114:117], v[174:177], v[182:185], v[114:117]
	v_mfma_f32_16x16x32_bf16 v[102:105], v[166:169], v[190:193], v[102:105]
	v_mfma_f32_16x16x32_bf16 v[98:101], v[174:177], v[190:193], v[98:101]
	v_mfma_f32_16x16x32_bf16 v[86:89], v[166:169], v[198:201], v[86:89]
	v_mfma_f32_16x16x32_bf16 v[82:85], v[174:177], v[198:201], v[82:85]
	v_mfma_f32_16x16x32_bf16 v[70:73], v[166:169], v[206:209], v[70:73]
	v_mfma_f32_16x16x32_bf16 v[66:69], v[174:177], v[206:209], v[66:69]
	s_barrier
	s_add_i32 s6, s91, s12
	v_lshl_add_u64 v[210:211], s[16:17], 0, v[16:17]
	s_mov_b32 m0, s6
	ds_read_b128 v[178:181], v161 offset:16384
	ds_read_b128 v[182:185], v161 offset:17408
	ds_read_b128 v[186:189], v161 offset:18432
	ds_read_b128 v[190:193], v161 offset:19456
	ds_read_b128 v[194:197], v161 offset:20480
	ds_read_b128 v[198:201], v161 offset:21504
	ds_read_b128 v[202:205], v161 offset:22528
	ds_read_b128 v[206:209], v161 offset:23552
	global_load_lds_dwordx4 v[210:211], off
	s_add_i32 m0, s6, 0x2000
	s_add_u32 s6, s16, 0x100000
	v_lshl_add_u64 v[212:213], s[16:17], 0, v[138:139]
	s_addc_u32 s7, s17, 0
	s_add_i32 s91, s94, s12
	global_load_lds_dwordx4 v[212:213], off
	v_lshl_add_u64 v[214:215], s[6:7], 0, v[16:17]
	s_mov_b32 m0, s91
	v_lshl_add_u64 v[216:217], s[40:41], 0, v[140:141]
	global_load_lds_dwordx4 v[214:215], off
	v_lshl_add_u64 v[214:215], s[6:7], 0, v[138:139]
	s_add_i32 m0, s91, 0x2000
	s_nop 0
	global_load_lds_dwordx4 v[214:215], off
	v_lshl_add_u64 v[214:215], s[40:41], 0, v[142:143]
	s_mov_b32 m0, s13
	s_nop 0
	global_load_lds_dwordx4 v[214:215], off
	s_mov_b32 m0, s42
	s_nop 0
	global_load_lds_dwordx4 v[216:217], off
	s_waitcnt vmcnt(8) lgkmcnt(0)
	s_nop 0
	s_barrier
; #define PG8_STAGEA(bufoff, gbase, voff) PG8_STAGE_X(bufoff, gbase, voff, AUXA)
; #define PG8_STAGEB(bufoff, gbase, voff) PG8_STAGE_X(bufoff, gbase, voff, AUXB)
; #define PG8_LDA(dst, b, h) do { _Pragma("unroll") for (int m = 0; m < 4; ++m) _Pragma("unroll") for (int k = 0; k < 2; ++k) dst[m][k] = *(const PG8_LAS bf16x8*)(lds + PG8_SA(b, h) + aoff + m * 2048 + k * 1024); } while (0)
; #define PG8_LDB(dst, b, h) do { _Pragma("unroll") for (int n = 0; n < 2; ++n) _Pragma("unroll") for (int k = 0; k < 2; ++k) dst[n][k] = *(const PG8_LAS bf16x8*)(lds + PG8_SB(b, h) + boff + n * 2048 + k * 1024); } while (0)
; #define PG8_MMA(ai, bj, At, Bt) do { if (GEMM_PRIO_MODE == 0) __builtin_amdgcn_s_setprio(1); PG8_MMA_LOOPS \
;         acc[ai][bj][m][n] = __builtin_amdgcn_mfma_f32_16x16x32_bf16(Bt[n][k], At[m][k], acc[ai][bj][m][n], 0, 0, 0); if (GEMM_PRIO_MODE == 0) __builtin_amdgcn_s_setprio(0); } while (0)
; #define PG8_WAIT_V(n) asm volatile("s_waitcnt vmcnt(" #n ")" ::: "memory")
; #define PG8_WAIT_VR(n, nr, flag) asm volatile("s_cmp_eq_u32 %0, 0\n\ts_cbranch_scc1 .Lpg8s%=\n\ts_waitcnt vmcnt(" #nr ")\n\ts_branch .Lpg8d%=\n.Lpg8s%=:\n\ts_waitcnt vmcnt(" #n ")\n.Lpg8d%=:" :: "s"(flag) : "memory", "scc")
; #define PG8_WAIT_L(n) asm volatile("s_waitcnt lgkmcnt(" #n ")" ::: "memory")
; #define PG8_BAR __builtin_amdgcn_s_barrier()
; #define PG8_SCHED __builtin_amdgcn_sched_barrier(0)
;     ...
;             PG8_LDA(At, 0, 1); PG8_STAGEB(PG8_SB(0, 0), b2, voffB); PG8_STAGEB(PG8_SB(0, 1), b2 + hstepB, voffB); PG8_STAGEA(PG8_SA(0, 0), a2, voffA);
;     ...
;             PG8_WAIT_VR(8, 24, relax); PG8_WAIT_L(0); PG8_BAR; PG8_MMA(1, 0, At, B0); PG8_MMA(1, 1, At, B1); PG8_BAR; PG8_SCHED;
;     ...
;             PG8_WAIT_V(8); PG8_WAIT_L(0); PG8_BAR; PG8_MMA(1, 0, At, B0); PG8_MMA(1, 1, At, B1); PG8_BAR; PG8_SCHED;
;     ...
;             PG8_LDB(B0, 1, 0); PG8_LDB(B1, 1, 1); PG8_SCHED; PG8_LDA(At, 1, 0); PG8_STAGEA(PG8_SA(0, 1), a2 + hstepA, voffA);
;             PG8_WAIT_V(8); PG8_WAIT_L(0); PG8_BAR; PG8_MMA(0, 0, At, B0); PG8_MMA(0, 1, At, B1); PG8_BAR; PG8_SCHED;
;             PG8_LDA(At, 1, 1); PG8_STAGEB(PG8_SB(1, 0), b3, voffB); PG8_STAGEB(PG8_SB(1, 1), b3 + hstepB, voffB); PG8_STAGEA(PG8_SA(1, 0), a3, voffA);
;             PG8_WAIT_V(8); PG8_WAIT_L(0); PG8_BAR; PG8_MMA(1, 0, At, B0); PG8_MMA(1, 1, At, B1); PG8_BAR; PG8_SCHED;
	v_mfma_f32_16x16x32_bf16 v[62:65], v[130:133], v[178:181], 0
	v_mfma_f32_16x16x32_bf16 v[58:61], v[148:151], v[178:181], 0
	v_mfma_f32_16x16x32_bf16 v[46:49], v[130:133], v[186:189], 0
	v_mfma_f32_16x16x32_bf16 v[42:45], v[148:151], v[186:189], 0
	v_mfma_f32_16x16x32_bf16 v[30:33], v[130:133], v[194:197], 0
	v_mfma_f32_16x16x32_bf16 v[26:29], v[148:151], v[194:197], 0
	v_mfma_f32_16x16x32_bf16 v[12:15], v[130:133], v[202:205], 0
	v_mfma_f32_16x16x32_bf16 v[8:11], v[148:151], v[202:205], 0
	v_mfma_f32_16x16x32_bf16 v[62:65], v[134:137], v[182:185], v[62:65]
	v_mfma_f32_16x16x32_bf16 v[58:61], v[152:155], v[182:185], v[58:61]
	v_mfma_f32_16x16x32_bf16 v[46:49], v[134:137], v[190:193], v[46:49]
	v_mfma_f32_16x16x32_bf16 v[42:45], v[152:155], v[190:193], v[42:45]
	v_mfma_f32_16x16x32_bf16 v[30:33], v[134:137], v[198:201], v[30:33]
	v_mfma_f32_16x16x32_bf16 v[26:29], v[152:155], v[198:201], v[26:29]
	v_mfma_f32_16x16x32_bf16 v[12:15], v[134:137], v[206:209], v[12:15]
	v_mfma_f32_16x16x32_bf16 v[8:11], v[152:155], v[206:209], v[8:11]
	v_mfma_f32_16x16x32_bf16 v[54:57], v[162:165], v[178:181], 0
	v_mfma_f32_16x16x32_bf16 v[50:53], v[170:173], v[178:181], 0
	v_mfma_f32_16x16x32_bf16 v[38:41], v[162:165], v[186:189], 0
	v_mfma_f32_16x16x32_bf16 v[34:37], v[170:173], v[186:189], 0
	v_mfma_f32_16x16x32_bf16 v[22:25], v[162:165], v[194:197], 0
	v_mfma_f32_16x16x32_bf16 v[18:21], v[170:173], v[194:197], 0
	v_mfma_f32_16x16x32_bf16 v[4:7], v[162:165], v[202:205], 0
	v_mfma_f32_16x16x32_bf16 v[0:3], v[170:173], v[202:205], 0
	v_mfma_f32_16x16x32_bf16 v[54:57], v[166:169], v[182:185], v[54:57]
	v_mfma_f32_16x16x32_bf16 v[50:53], v[174:177], v[182:185], v[50:53]
	v_mfma_f32_16x16x32_bf16 v[38:41], v[166:169], v[190:193], v[38:41]
	v_mfma_f32_16x16x32_bf16 v[34:37], v[174:177], v[190:193], v[34:37]
	v_mfma_f32_16x16x32_bf16 v[22:25], v[166:169], v[198:201], v[22:25]
	v_mfma_f32_16x16x32_bf16 v[18:21], v[174:177], v[198:201], v[18:21]
	v_mfma_f32_16x16x32_bf16 v[4:7], v[166:169], v[206:209], v[4:7]
	v_mfma_f32_16x16x32_bf16 v[0:3], v[174:177], v[206:209], v[0:3]
	s_barrier
	s_add_i32 s91, 0, 0x18000
	s_add_i32 s94, 0, 0x1c000
	v_add_u32_e32 v152, s91, v157
	v_add_u32_e32 v174, s94, v157
	ds_read_b128 v[130:133], v152
	ds_read_b128 v[134:137], v152 offset:1024
	ds_read_b128 v[148:151], v152 offset:2048
	ds_read_b128 v[152:155], v152 offset:3072
	ds_read_b128 v[162:165], v174
	ds_read_b128 v[166:169], v174 offset:1024
	ds_read_b128 v[170:173], v174 offset:2048
	ds_read_b128 v[174:177], v174 offset:3072
	s_add_u32 s6, s40, 0x100000
	s_addc_u32 s7, s41, 0
	s_mov_b32 m0, s43
	v_lshl_add_u64 v[218:219], s[6:7], 0, v[142:143]
	ds_read_b128 v[178:181], v161 offset:32768
	ds_read_b128 v[182:185], v161 offset:33792
	ds_read_b128 v[186:189], v161 offset:34816
	ds_read_b128 v[190:193], v161 offset:35840
	ds_read_b128 v[194:197], v161 offset:36864
	ds_read_b128 v[198:201], v161 offset:37888
	ds_read_b128 v[202:205], v161 offset:38912
	ds_read_b128 v[206:209], v161 offset:39936
	global_load_lds_dwordx4 v[218:219], off
	v_lshl_add_u64 v[218:219], s[6:7], 0, v[140:141]
	s_mov_b32 m0, s50
	s_nop 0
	global_load_lds_dwordx4 v[218:219], off
	s_waitcnt vmcnt(8) lgkmcnt(0)
	s_nop 0
	s_barrier
	v_mfma_f32_16x16x32_bf16 v[126:129], v[130:133], v[178:181], v[126:129]
	v_mfma_f32_16x16x32_bf16 v[122:125], v[148:151], v[178:181], v[122:125]
	v_mfma_f32_16x16x32_bf16 v[110:113], v[130:133], v[186:189], v[110:113]
	v_mfma_f32_16x16x32_bf16 v[106:109], v[148:151], v[186:189], v[106:109]
	v_mfma_f32_16x16x32_bf16 v[94:97], v[130:133], v[194:197], v[94:97]
	v_mfma_f32_16x16x32_bf16 v[90:93], v[148:151], v[194:197], v[90:93]
	v_mfma_f32_16x16x32_bf16 v[78:81], v[130:133], v[202:205], v[78:81]
	v_mfma_f32_16x16x32_bf16 v[74:77], v[148:151], v[202:205], v[74:77]
	v_mfma_f32_16x16x32_bf16 v[126:129], v[134:137], v[182:185], v[126:129]
	v_mfma_f32_16x16x32_bf16 v[122:125], v[152:155], v[182:185], v[122:125]
	v_mfma_f32_16x16x32_bf16 v[110:113], v[134:137], v[190:193], v[110:113]
	v_mfma_f32_16x16x32_bf16 v[106:109], v[152:155], v[190:193], v[106:109]
	v_mfma_f32_16x16x32_bf16 v[94:97], v[134:137], v[198:201], v[94:97]
	v_mfma_f32_16x16x32_bf16 v[90:93], v[152:155], v[198:201], v[90:93]
	v_mfma_f32_16x16x32_bf16 v[78:81], v[134:137], v[206:209], v[78:81]
	v_mfma_f32_16x16x32_bf16 v[74:77], v[152:155], v[206:209], v[74:77]
	v_mfma_f32_16x16x32_bf16 v[118:121], v[162:165], v[178:181], v[118:121]
	v_mfma_f32_16x16x32_bf16 v[114:117], v[170:173], v[178:181], v[114:117]
	v_mfma_f32_16x16x32_bf16 v[102:105], v[162:165], v[186:189], v[102:105]
	v_mfma_f32_16x16x32_bf16 v[98:101], v[170:173], v[186:189], v[98:101]
	v_mfma_f32_16x16x32_bf16 v[86:89], v[162:165], v[194:197], v[86:89]
	v_mfma_f32_16x16x32_bf16 v[82:85], v[170:173], v[194:197], v[82:85]
	v_mfma_f32_16x16x32_bf16 v[70:73], v[162:165], v[202:205], v[70:73]
	v_mfma_f32_16x16x32_bf16 v[66:69], v[170:173], v[202:205], v[66:69]
	v_mfma_f32_16x16x32_bf16 v[118:121], v[166:169], v[182:185], v[118:121]
	v_mfma_f32_16x16x32_bf16 v[114:117], v[174:177], v[182:185], v[114:117]
	v_mfma_f32_16x16x32_bf16 v[102:105], v[166:169], v[190:193], v[102:105]
	v_mfma_f32_16x16x32_bf16 v[98:101], v[174:177], v[190:193], v[98:101]
	v_mfma_f32_16x16x32_bf16 v[86:89], v[166:169], v[198:201], v[86:89]
	v_mfma_f32_16x16x32_bf16 v[82:85], v[174:177], v[198:201], v[82:85]
	v_mfma_f32_16x16x32_bf16 v[70:73], v[166:169], v[206:209], v[70:73]
	v_mfma_f32_16x16x32_bf16 v[66:69], v[174:177], v[206:209], v[66:69]
	s_barrier
; #define PG8_STAGEA(bufoff, gbase, voff) PG8_STAGE_X(bufoff, gbase, voff, AUXA)
; #define PG8_STAGEB(bufoff, gbase, voff) PG8_STAGE_X(bufoff, gbase, voff, AUXB)
; #define PG8_LDA(dst, b, h) do { _Pragma("unroll") for (int m = 0; m < 4; ++m) _Pragma("unroll") for (int k = 0; k < 2; ++k) dst[m][k] = *(const PG8_LAS bf16x8*)(lds + PG8_SA(b, h) + aoff + m * 2048 + k * 1024); } while (0)
; #define PG8_WAIT_V(n) asm volatile("s_waitcnt vmcnt(" #n ")" ::: "memory")
; #define PG8_WAIT_L(n) asm volatile("s_waitcnt lgkmcnt(" #n ")" ::: "memory")
;     ...
;         for (int t = t0; t < nt; t += 2) {
;             const bool last = (t == nt - 2);
;             const char* a1 = cA + (size_t)(t + 1) * kstepA;
;             const char* a2 = last ? nA : cA + (size_t)(t + 2) * kstepA; const char* b2 = last ? nB : cB + (size_t)(t + 2) * kstepB;
;             const char* a3 = a2 + kstepA; const char* b3 = b2 + kstepB;
;             if (last && has_next) S.a_ready(nxt);
;             if constexpr (SP2) {
;             PG8_LDB(B0, 0, 0); PG8_LDB(B1, 0, 1); PG8_SCHED; PG8_LDA(At, 0, 0); PG8_STAGEA(PG8_SA(1, 1), a1 + hstepA, voffA);
;     ...
;             const int relax = __builtin_amdgcn_readfirstlane((t == 0 && ui > 0) ? 1 : 0);
;             PG8_WAIT_VR(8, 24, relax); PG8_WAIT_L(0); PG8_BAR; PG8_MMA(0, 0, At, B0); PG8_MMA(0, 1, At, B1); PG8_BAR; PG8_SCHED;
;     ...
;             PG8_WAIT_V(8); PG8_WAIT_L(0); PG8_BAR; PG8_MMA(0, 0, At, B0); PG8_MMA(0, 1, At, B1); PG8_BAR; PG8_SCHED;
;     ...
;             PG8_LDA(At, 0, 1); PG8_STAGEB(PG8_SB(0, 0), b2, voffB); PG8_STAGEB(PG8_SB(0, 1), b2 + hstepB, voffB); PG8_STAGEA(PG8_SA(0, 0), a2, voffA);
;     ...
;             PG8_WAIT_VR(8, 24, relax); PG8_WAIT_L(0); PG8_BAR; PG8_MMA(1, 0, At, B0); PG8_MMA(1, 1, At, B1); PG8_BAR; PG8_SCHED;
;     ...
;             PG8_WAIT_V(8); PG8_WAIT_L(0); PG8_BAR; PG8_MMA(1, 0, At, B0); PG8_MMA(1, 1, At, B1); PG8_BAR; PG8_SCHED;
;     ...
;             PG8_LDB(B0, 1, 0); PG8_LDB(B1, 1, 1); PG8_SCHED; PG8_LDA(At, 1, 0); PG8_STAGEA(PG8_SA(0, 1), a2 + hstepA, voffA);
;             PG8_WAIT_V(8); PG8_WAIT_L(0); PG8_BAR; PG8_MMA(0, 0, At, B0); PG8_MMA(0, 1, At, B1); PG8_BAR; PG8_SCHED;
;             PG8_LDA(At, 1, 1); PG8_STAGEB(PG8_SB(1, 0), b3, voffB); PG8_STAGEB(PG8_SB(1, 1), b3 + hstepB, voffB); PG8_STAGEA(PG8_SA(1, 0), a3, voffA);
;             PG8_WAIT_V(8); PG8_WAIT_L(0); PG8_BAR; PG8_MMA(1, 0, At, B0); PG8_MMA(1, 1, At, B1); PG8_BAR; PG8_SCHED;
	s_add_i32 s6, s91, s12
	v_lshl_add_u64 v[210:211], v[210:211], 0, s[86:87]
	s_mov_b32 m0, s6
	ds_read_b128 v[178:181], v161 offset:49152
	ds_read_b128 v[182:185], v161 offset:50176
	ds_read_b128 v[186:189], v161 offset:51200
	ds_read_b128 v[190:193], v161 offset:52224
	ds_read_b128 v[194:197], v161 offset:53248
	ds_read_b128 v[198:201], v161 offset:54272
	ds_read_b128 v[202:205], v161 offset:55296
	ds_read_b128 v[206:209], v161 offset:56320
	global_load_lds_dwordx4 v[210:211], off
	s_add_i32 m0, s6, 0x2000
	s_add_u32 s6, s16, 0x100080
	v_lshl_add_u64 v[210:211], v[212:213], 0, s[86:87]
	s_addc_u32 s7, s17, 0
	s_add_i32 s16, s94, s12
	global_load_lds_dwordx4 v[210:211], off
	v_lshl_add_u64 v[210:211], s[6:7], 0, v[16:17]
	s_mov_b32 m0, s16
	s_nop 0
	global_load_lds_dwordx4 v[210:211], off
	v_lshl_add_u64 v[210:211], s[6:7], 0, v[138:139]
	s_add_i32 m0, s16, 0x2000
	s_nop 0
	global_load_lds_dwordx4 v[210:211], off
	v_lshl_add_u64 v[210:211], v[214:215], 0, s[86:87]
	s_mov_b32 m0, s68
	s_nop 0
	global_load_lds_dwordx4 v[210:211], off
	v_lshl_add_u64 v[210:211], v[216:217], 0, s[86:87]
	s_mov_b32 m0, s69
	s_nop 0
	global_load_lds_dwordx4 v[210:211], off
	s_waitcnt vmcnt(8) lgkmcnt(0)
	s_barrier
	v_mfma_f32_16x16x32_bf16 v[62:65], v[130:133], v[178:181], v[62:65]
	v_mfma_f32_16x16x32_bf16 v[58:61], v[148:151], v[178:181], v[58:61]
	v_mfma_f32_16x16x32_bf16 v[46:49], v[130:133], v[186:189], v[46:49]
	v_mfma_f32_16x16x32_bf16 v[42:45], v[148:151], v[186:189], v[42:45]
	v_mfma_f32_16x16x32_bf16 v[30:33], v[130:133], v[194:197], v[30:33]
	v_mfma_f32_16x16x32_bf16 v[26:29], v[148:151], v[194:197], v[26:29]
	v_mfma_f32_16x16x32_bf16 v[12:15], v[130:133], v[202:205], v[12:15]
	v_mfma_f32_16x16x32_bf16 v[8:11], v[148:151], v[202:205], v[8:11]
	v_mfma_f32_16x16x32_bf16 v[62:65], v[134:137], v[182:185], v[62:65]
	v_mfma_f32_16x16x32_bf16 v[58:61], v[152:155], v[182:185], v[58:61]
	v_mfma_f32_16x16x32_bf16 v[46:49], v[134:137], v[190:193], v[46:49]
	v_mfma_f32_16x16x32_bf16 v[42:45], v[152:155], v[190:193], v[42:45]
	v_mfma_f32_16x16x32_bf16 v[30:33], v[134:137], v[198:201], v[30:33]
	v_mfma_f32_16x16x32_bf16 v[26:29], v[152:155], v[198:201], v[26:29]
	v_mfma_f32_16x16x32_bf16 v[12:15], v[134:137], v[206:209], v[12:15]
	v_mfma_f32_16x16x32_bf16 v[8:11], v[152:155], v[206:209], v[8:11]
	v_mfma_f32_16x16x32_bf16 v[54:57], v[162:165], v[178:181], v[54:57]
	v_mfma_f32_16x16x32_bf16 v[50:53], v[170:173], v[178:181], v[50:53]
	v_mfma_f32_16x16x32_bf16 v[38:41], v[162:165], v[186:189], v[38:41]
	v_mfma_f32_16x16x32_bf16 v[34:37], v[170:173], v[186:189], v[34:37]
	v_mfma_f32_16x16x32_bf16 v[22:25], v[162:165], v[194:197], v[22:25]
	v_mfma_f32_16x16x32_bf16 v[18:21], v[170:173], v[194:197], v[18:21]
	v_mfma_f32_16x16x32_bf16 v[4:7], v[162:165], v[202:205], v[4:7]
	v_mfma_f32_16x16x32_bf16 v[0:3], v[170:173], v[202:205], v[0:3]
	v_mfma_f32_16x16x32_bf16 v[54:57], v[166:169], v[182:185], v[54:57]
	v_mfma_f32_16x16x32_bf16 v[50:53], v[174:177], v[182:185], v[50:53]
	v_mfma_f32_16x16x32_bf16 v[38:41], v[166:169], v[190:193], v[38:41]
	v_mfma_f32_16x16x32_bf16 v[34:37], v[174:177], v[190:193], v[34:37]
	v_mfma_f32_16x16x32_bf16 v[22:25], v[166:169], v[198:201], v[22:25]
	v_mfma_f32_16x16x32_bf16 v[18:21], v[174:177], v[198:201], v[18:21]
	v_mfma_f32_16x16x32_bf16 v[4:7], v[166:169], v[206:209], v[4:7]
	v_mfma_f32_16x16x32_bf16 v[0:3], v[174:177], v[206:209], v[0:3]
	s_barrier
	s_add_i32 s90, s90, 2
	s_add_u32 s38, s38, 0x100
	s_addc_u32 s39, s39, 0
	s_add_u32 s0, s0, 0x100
	s_addc_u32 s1, s1, 0
	v_add_u32_e32 v220, 0x10000, v157
.LBB0_558:
	s_add_u32 s6, s38, 0xfff00080
	s_addc_u32 s7, s39, -1
	s_add_i32 s91, 0, 0x10000
	s_cmp_eq_u32 s90, 60
	s_cselect_b32 s41, s21, s7
	s_cselect_b32 s40, s82, s6
	s_cselect_b32 s17, s23, s1
	s_cselect_b32 s16, s83, s0
	s_add_i32 s94, 0, 0x14000
	ds_read_b128 v[130:133], v220
	ds_read_b128 v[134:137], v220 offset:1024
	ds_read_b128 v[148:151], v220 offset:2048
	ds_read_b128 v[152:155], v220 offset:3072
	ds_read_b128 v[162:165], v220 offset:16384
	ds_read_b128 v[166:169], v220 offset:17408
	ds_read_b128 v[170:173], v220 offset:18432
	ds_read_b128 v[174:177], v220 offset:19456
	s_add_i32 m0, s13, 0xc000
	ds_read_b128 v[178:181], v161
	ds_read_b128 v[182:185], v161 offset:1024
	ds_read_b128 v[186:189], v161 offset:2048
	ds_read_b128 v[190:193], v161 offset:3072
	ds_read_b128 v[194:197], v161 offset:4096
	ds_read_b128 v[198:201], v161 offset:5120
	ds_read_b128 v[202:205], v161 offset:6144
	global_load_lds_dwordx4 v144, s[38:39]
	s_add_i32 m0, s13, 0xe000
	ds_read_b128 v[206:209], v161 offset:7168
	global_load_lds_dwordx4 v146, s[38:39]
	s_waitcnt vmcnt(8) lgkmcnt(0)
	s_barrier
; #define PG8_STAGEA(bufoff, gbase, voff) PG8_STAGE_X(bufoff, gbase, voff, AUXA)
; #define PG8_STAGEB(bufoff, gbase, voff) PG8_STAGE_X(bufoff, gbase, voff, AUXB)
; #define PG8_LDA(dst, b, h) do { _Pragma("unroll") for (int m = 0; m < 4; ++m) _Pragma("unroll") for (int k = 0; k < 2; ++k) dst[m][k] = *(const PG8_LAS bf16x8*)(lds + PG8_SA(b, h) + aoff + m * 2048 + k * 1024); } while (0)
; #define PG8_LDB(dst, b, h) do { _Pragma("unroll") for (int n = 0; n < 2; ++n) _Pragma("unroll") for (int k = 0; k < 2; ++k) dst[n][k] = *(const PG8_LAS bf16x8*)(lds + PG8_SB(b, h) + boff + n * 2048 + k * 1024); } while (0)
; #define PG8_MMA(ai, bj, At, Bt) do { if (GEMM_PRIO_MODE == 0) __builtin_amdgcn_s_setprio(1); PG8_MMA_LOOPS \
;         acc[ai][bj][m][n] = __builtin_amdgcn_mfma_f32_16x16x32_bf16(Bt[n][k], At[m][k], acc[ai][bj][m][n], 0, 0, 0); if (GEMM_PRIO_MODE == 0) __builtin_amdgcn_s_setprio(0); } while (0)
; #define PG8_WAIT_V(n) asm volatile("s_waitcnt vmcnt(" #n ")" ::: "memory")
;     ...
;             PG8_LDB(B0, 0, 0); PG8_LDB(B1, 0, 1); PG8_SCHED; PG8_LDA(At, 0, 0); PG8_STAGEA(PG8_SA(1, 1), a1 + hstepA, voffA);
;     ...
;             const int relax = __builtin_amdgcn_readfirstlane((t == 0 && ui > 0) ? 1 : 0);
;             PG8_WAIT_VR(8, 24, relax); PG8_WAIT_L(0); PG8_BAR; PG8_MMA(0, 0, At, B0); PG8_MMA(0, 1, At, B1); PG8_BAR; PG8_SCHED;
;     ...
;             PG8_WAIT_V(8); PG8_WAIT_L(0); PG8_BAR; PG8_MMA(0, 0, At, B0); PG8_MMA(0, 1, At, B1); PG8_BAR; PG8_SCHED;
;     ...
;             PG8_LDA(At, 0, 1); PG8_STAGEB(PG8_SB(0, 0), b2, voffB); PG8_STAGEB(PG8_SB(0, 1), b2 + hstepB, voffB); PG8_STAGEA(PG8_SA(0, 0), a2, voffA);
;     ...
;             PG8_WAIT_VR(8, 24, relax); PG8_WAIT_L(0); PG8_BAR; PG8_MMA(1, 0, At, B0); PG8_MMA(1, 1, At, B1); PG8_BAR; PG8_SCHED;
;     ...
;             PG8_WAIT_V(8); PG8_WAIT_L(0); PG8_BAR; PG8_MMA(1, 0, At, B0); PG8_MMA(1, 1, At, B1); PG8_BAR; PG8_SCHED;
;     ...
;             PG8_LDB(B0, 1, 0); PG8_LDB(B1, 1, 1); PG8_SCHED; PG8_LDA(At, 1, 0); PG8_STAGEA(PG8_SA(0, 1), a2 + hstepA, voffA);
;             PG8_WAIT_V(8); PG8_WAIT_L(0); PG8_BAR; PG8_MMA(0, 0, At, B0); PG8_MMA(0, 1, At, B1); PG8_BAR; PG8_SCHED;
;             PG8_LDA(At, 1, 1); PG8_STAGEB(PG8_SB(1, 0), b3, voffB); PG8_STAGEB(PG8_SB(1, 1), b3 + hstepB, voffB); PG8_STAGEA(PG8_SA(1, 0), a3, voffA);
;             PG8_WAIT_V(8); PG8_WAIT_L(0); PG8_BAR; PG8_MMA(1, 0, At, B0); PG8_MMA(1, 1, At, B1); PG8_BAR; PG8_SCHED;
	v_mfma_f32_16x16x32_bf16 v[126:129], v[130:133], v[178:181], v[126:129]
	v_mfma_f32_16x16x32_bf16 v[122:125], v[148:151], v[178:181], v[122:125]
	v_mfma_f32_16x16x32_bf16 v[110:113], v[130:133], v[186:189], v[110:113]
	v_mfma_f32_16x16x32_bf16 v[106:109], v[148:151], v[186:189], v[106:109]
	v_mfma_f32_16x16x32_bf16 v[94:97], v[130:133], v[194:197], v[94:97]
	v_mfma_f32_16x16x32_bf16 v[90:93], v[148:151], v[194:197], v[90:93]
	v_mfma_f32_16x16x32_bf16 v[78:81], v[130:133], v[202:205], v[78:81]
	v_mfma_f32_16x16x32_bf16 v[74:77], v[148:151], v[202:205], v[74:77]
	v_mfma_f32_16x16x32_bf16 v[126:129], v[134:137], v[182:185], v[126:129]
	v_mfma_f32_16x16x32_bf16 v[122:125], v[152:155], v[182:185], v[122:125]
	v_mfma_f32_16x16x32_bf16 v[110:113], v[134:137], v[190:193], v[110:113]
	v_mfma_f32_16x16x32_bf16 v[106:109], v[152:155], v[190:193], v[106:109]
	v_mfma_f32_16x16x32_bf16 v[94:97], v[134:137], v[198:201], v[94:97]
	v_mfma_f32_16x16x32_bf16 v[90:93], v[152:155], v[198:201], v[90:93]
	v_mfma_f32_16x16x32_bf16 v[78:81], v[134:137], v[206:209], v[78:81]
	v_mfma_f32_16x16x32_bf16 v[74:77], v[152:155], v[206:209], v[74:77]
	v_mfma_f32_16x16x32_bf16 v[118:121], v[162:165], v[178:181], v[118:121]
	v_mfma_f32_16x16x32_bf16 v[114:117], v[170:173], v[178:181], v[114:117]
	v_mfma_f32_16x16x32_bf16 v[102:105], v[162:165], v[186:189], v[102:105]
	v_mfma_f32_16x16x32_bf16 v[98:101], v[170:173], v[186:189], v[98:101]
	v_mfma_f32_16x16x32_bf16 v[86:89], v[162:165], v[194:197], v[86:89]
	v_mfma_f32_16x16x32_bf16 v[82:85], v[170:173], v[194:197], v[82:85]
	v_mfma_f32_16x16x32_bf16 v[70:73], v[162:165], v[202:205], v[70:73]
	v_mfma_f32_16x16x32_bf16 v[66:69], v[170:173], v[202:205], v[66:69]
	v_mfma_f32_16x16x32_bf16 v[118:121], v[166:169], v[182:185], v[118:121]
	v_mfma_f32_16x16x32_bf16 v[114:117], v[174:177], v[182:185], v[114:117]
	v_mfma_f32_16x16x32_bf16 v[102:105], v[166:169], v[190:193], v[102:105]
	v_mfma_f32_16x16x32_bf16 v[98:101], v[174:177], v[190:193], v[98:101]
	v_mfma_f32_16x16x32_bf16 v[86:89], v[166:169], v[198:201], v[86:89]
	v_mfma_f32_16x16x32_bf16 v[82:85], v[174:177], v[198:201], v[82:85]
	v_mfma_f32_16x16x32_bf16 v[70:73], v[166:169], v[206:209], v[70:73]
	v_mfma_f32_16x16x32_bf16 v[66:69], v[174:177], v[206:209], v[66:69]
	s_barrier
	s_add_i32 s6, s91, s12
	s_mov_b32 m0, s6
	ds_read_b128 v[178:181], v161 offset:16384
	ds_read_b128 v[182:185], v161 offset:17408
	ds_read_b128 v[186:189], v161 offset:18432
	ds_read_b128 v[190:193], v161 offset:19456
	global_load_lds_dwordx4 v16, s[16:17]
	s_add_i32 m0, s6, 0x2000
	s_add_u32 s6, s16, 0x100000
	s_addc_u32 s7, s17, 0
	s_add_i32 s91, s94, s12
	global_load_lds_dwordx4 v138, s[16:17]
	s_mov_b32 m0, s91
	ds_read_b128 v[206:209], v161 offset:23552
	global_load_lds_dwordx4 v16, s[6:7]
	s_add_i32 m0, s91, 0x2000
	ds_read_b128 v[202:205], v161 offset:22528
	global_load_lds_dwordx4 v138, s[6:7]
	s_mov_b32 m0, s13
	ds_read_b128 v[198:201], v161 offset:21504
	global_load_lds_dwordx4 v142, s[40:41]
	s_mov_b32 m0, s42
	ds_read_b128 v[194:197], v161 offset:20480
	global_load_lds_dwordx4 v140, s[40:41]
	s_waitcnt vmcnt(8) lgkmcnt(0)
	s_barrier
	v_mfma_f32_16x16x32_bf16 v[62:65], v[130:133], v[178:181], v[62:65]
	v_mfma_f32_16x16x32_bf16 v[58:61], v[148:151], v[178:181], v[58:61]
	v_mfma_f32_16x16x32_bf16 v[46:49], v[130:133], v[186:189], v[46:49]
	v_mfma_f32_16x16x32_bf16 v[42:45], v[148:151], v[186:189], v[42:45]
	v_mfma_f32_16x16x32_bf16 v[30:33], v[130:133], v[194:197], v[30:33]
	v_mfma_f32_16x16x32_bf16 v[26:29], v[148:151], v[194:197], v[26:29]
	v_mfma_f32_16x16x32_bf16 v[12:15], v[130:133], v[202:205], v[12:15]
	v_mfma_f32_16x16x32_bf16 v[8:11], v[148:151], v[202:205], v[8:11]
	v_mfma_f32_16x16x32_bf16 v[62:65], v[134:137], v[182:185], v[62:65]
	v_mfma_f32_16x16x32_bf16 v[58:61], v[152:155], v[182:185], v[58:61]
	v_mfma_f32_16x16x32_bf16 v[46:49], v[134:137], v[190:193], v[46:49]
	v_mfma_f32_16x16x32_bf16 v[42:45], v[152:155], v[190:193], v[42:45]
	v_mfma_f32_16x16x32_bf16 v[30:33], v[134:137], v[198:201], v[30:33]
	v_mfma_f32_16x16x32_bf16 v[26:29], v[152:155], v[198:201], v[26:29]
	v_mfma_f32_16x16x32_bf16 v[12:15], v[134:137], v[206:209], v[12:15]
	v_mfma_f32_16x16x32_bf16 v[8:11], v[152:155], v[206:209], v[8:11]
	v_mfma_f32_16x16x32_bf16 v[54:57], v[162:165], v[178:181], v[54:57]
	v_mfma_f32_16x16x32_bf16 v[50:53], v[170:173], v[178:181], v[50:53]
	v_mfma_f32_16x16x32_bf16 v[38:41], v[162:165], v[186:189], v[38:41]
	v_mfma_f32_16x16x32_bf16 v[34:37], v[170:173], v[186:189], v[34:37]
	v_mfma_f32_16x16x32_bf16 v[22:25], v[162:165], v[194:197], v[22:25]
	v_mfma_f32_16x16x32_bf16 v[18:21], v[170:173], v[194:197], v[18:21]
	v_mfma_f32_16x16x32_bf16 v[4:7], v[162:165], v[202:205], v[4:7]
	v_mfma_f32_16x16x32_bf16 v[0:3], v[170:173], v[202:205], v[0:3]
	v_mfma_f32_16x16x32_bf16 v[54:57], v[166:169], v[182:185], v[54:57]
	v_mfma_f32_16x16x32_bf16 v[50:53], v[174:177], v[182:185], v[50:53]
	v_mfma_f32_16x16x32_bf16 v[38:41], v[166:169], v[190:193], v[38:41]
	v_mfma_f32_16x16x32_bf16 v[34:37], v[174:177], v[190:193], v[34:37]
	v_mfma_f32_16x16x32_bf16 v[22:25], v[166:169], v[198:201], v[22:25]
	v_mfma_f32_16x16x32_bf16 v[18:21], v[174:177], v[198:201], v[18:21]
	v_mfma_f32_16x16x32_bf16 v[4:7], v[166:169], v[206:209], v[4:7]
	v_mfma_f32_16x16x32_bf16 v[0:3], v[174:177], v[206:209], v[0:3]
	s_barrier
; #define PG8_STAGEA(bufoff, gbase, voff) PG8_STAGE_X(bufoff, gbase, voff, AUXA)
; #define PG8_STAGEB(bufoff, gbase, voff) PG8_STAGE_X(bufoff, gbase, voff, AUXB)
; #define PG8_LDA(dst, b, h) do { _Pragma("unroll") for (int m = 0; m < 4; ++m) _Pragma("unroll") for (int k = 0; k < 2; ++k) dst[m][k] = *(const PG8_LAS bf16x8*)(lds + PG8_SA(b, h) + aoff + m * 2048 + k * 1024); } while (0)
; #define PG8_LDB(dst, b, h) do { _Pragma("unroll") for (int n = 0; n < 2; ++n) _Pragma("unroll") for (int k = 0; k < 2; ++k) dst[n][k] = *(const PG8_LAS bf16x8*)(lds + PG8_SB(b, h) + boff + n * 2048 + k * 1024); } while (0)
; #define PG8_MMA(ai, bj, At, Bt) do { if (GEMM_PRIO_MODE == 0) __builtin_amdgcn_s_setprio(1); PG8_MMA_LOOPS \
;         acc[ai][bj][m][n] = __builtin_amdgcn_mfma_f32_16x16x32_bf16(Bt[n][k], At[m][k], acc[ai][bj][m][n], 0, 0, 0); if (GEMM_PRIO_MODE == 0) __builtin_amdgcn_s_setprio(0); } while (0)
; #define PG8_WAIT_V(n) asm volatile("s_waitcnt vmcnt(" #n ")" ::: "memory")
;     ...
;             PG8_LDB(B0, 0, 0); PG8_LDB(B1, 0, 1); PG8_SCHED; PG8_LDA(At, 0, 0); PG8_STAGEA(PG8_SA(1, 1), a1 + hstepA, voffA);
;     ...
;             const int relax = __builtin_amdgcn_readfirstlane((t == 0 && ui > 0) ? 1 : 0);
;             PG8_WAIT_VR(8, 24, relax); PG8_WAIT_L(0); PG8_BAR; PG8_MMA(0, 0, At, B0); PG8_MMA(0, 1, At, B1); PG8_BAR; PG8_SCHED;
;     ...
;             PG8_WAIT_V(8); PG8_WAIT_L(0); PG8_BAR; PG8_MMA(0, 0, At, B0); PG8_MMA(0, 1, At, B1); PG8_BAR; PG8_SCHED;
;     ...
;             PG8_LDA(At, 0, 1); PG8_STAGEB(PG8_SB(0, 0), b2, voffB); PG8_STAGEB(PG8_SB(0, 1), b2 + hstepB, voffB); PG8_STAGEA(PG8_SA(0, 0), a2, voffA);
;     ...
;             PG8_WAIT_VR(8, 24, relax); PG8_WAIT_L(0); PG8_BAR; PG8_MMA(1, 0, At, B0); PG8_MMA(1, 1, At, B1); PG8_BAR; PG8_SCHED;
;     ...
;             PG8_WAIT_V(8); PG8_WAIT_L(0); PG8_BAR; PG8_MMA(1, 0, At, B0); PG8_MMA(1, 1, At, B1); PG8_BAR; PG8_SCHED;
;     ...
;             PG8_LDB(B0, 1, 0); PG8_LDB(B1, 1, 1); PG8_SCHED; PG8_LDA(At, 1, 0); PG8_STAGEA(PG8_SA(0, 1), a2 + hstepA, voffA);
;             PG8_WAIT_V(8); PG8_WAIT_L(0); PG8_BAR; PG8_MMA(0, 0, At, B0); PG8_MMA(0, 1, At, B1); PG8_BAR; PG8_SCHED;
;             PG8_LDA(At, 1, 1); PG8_STAGEB(PG8_SB(1, 0), b3, voffB); PG8_STAGEB(PG8_SB(1, 1), b3 + hstepB, voffB); PG8_STAGEA(PG8_SA(1, 0), a3, voffA);
;             PG8_WAIT_V(8); PG8_WAIT_L(0); PG8_BAR; PG8_MMA(1, 0, At, B0); PG8_MMA(1, 1, At, B1); PG8_BAR; PG8_SCHED;
	s_add_i32 s91, 0, 0x18000
	s_add_i32 s94, 0, 0x1c000
	ds_read_b128 v[130:133], v220 offset:32768
	ds_read_b128 v[134:137], v220 offset:33792
	ds_read_b128 v[148:151], v220 offset:34816
	ds_read_b128 v[152:155], v220 offset:35840
	ds_read_b128 v[162:165], v220 offset:49152
	ds_read_b128 v[166:169], v220 offset:50176
	ds_read_b128 v[170:173], v220 offset:51200
	ds_read_b128 v[174:177], v220 offset:52224
	s_add_u32 s6, s40, 0x100000
	s_addc_u32 s7, s41, 0
	s_mov_b32 m0, s43
	ds_read_b128 v[178:181], v161 offset:32768
	ds_read_b128 v[182:185], v161 offset:33792
	ds_read_b128 v[186:189], v161 offset:34816
	ds_read_b128 v[190:193], v161 offset:35840
	ds_read_b128 v[194:197], v161 offset:36864
	ds_read_b128 v[198:201], v161 offset:37888
	ds_read_b128 v[202:205], v161 offset:38912
	global_load_lds_dwordx4 v142, s[6:7]
	s_mov_b32 m0, s50
	ds_read_b128 v[206:209], v161 offset:39936
	global_load_lds_dwordx4 v140, s[6:7]
	s_waitcnt vmcnt(8) lgkmcnt(0)
	s_barrier
	v_mfma_f32_16x16x32_bf16 v[126:129], v[130:133], v[178:181], v[126:129]
	v_mfma_f32_16x16x32_bf16 v[122:125], v[148:151], v[178:181], v[122:125]
	v_mfma_f32_16x16x32_bf16 v[110:113], v[130:133], v[186:189], v[110:113]
	v_mfma_f32_16x16x32_bf16 v[106:109], v[148:151], v[186:189], v[106:109]
	v_mfma_f32_16x16x32_bf16 v[94:97], v[130:133], v[194:197], v[94:97]
	v_mfma_f32_16x16x32_bf16 v[90:93], v[148:151], v[194:197], v[90:93]
	v_mfma_f32_16x16x32_bf16 v[78:81], v[130:133], v[202:205], v[78:81]
	v_mfma_f32_16x16x32_bf16 v[74:77], v[148:151], v[202:205], v[74:77]
	v_mfma_f32_16x16x32_bf16 v[126:129], v[134:137], v[182:185], v[126:129]
	v_mfma_f32_16x16x32_bf16 v[122:125], v[152:155], v[182:185], v[122:125]
	v_mfma_f32_16x16x32_bf16 v[110:113], v[134:137], v[190:193], v[110:113]
	v_mfma_f32_16x16x32_bf16 v[106:109], v[152:155], v[190:193], v[106:109]
	v_mfma_f32_16x16x32_bf16 v[94:97], v[134:137], v[198:201], v[94:97]
	v_mfma_f32_16x16x32_bf16 v[90:93], v[152:155], v[198:201], v[90:93]
	v_mfma_f32_16x16x32_bf16 v[78:81], v[134:137], v[206:209], v[78:81]
	v_mfma_f32_16x16x32_bf16 v[74:77], v[152:155], v[206:209], v[74:77]
	v_mfma_f32_16x16x32_bf16 v[118:121], v[162:165], v[178:181], v[118:121]
	v_mfma_f32_16x16x32_bf16 v[114:117], v[170:173], v[178:181], v[114:117]
	v_mfma_f32_16x16x32_bf16 v[102:105], v[162:165], v[186:189], v[102:105]
	v_mfma_f32_16x16x32_bf16 v[98:101], v[170:173], v[186:189], v[98:101]
	v_mfma_f32_16x16x32_bf16 v[86:89], v[162:165], v[194:197], v[86:89]
	v_mfma_f32_16x16x32_bf16 v[82:85], v[170:173], v[194:197], v[82:85]
	v_mfma_f32_16x16x32_bf16 v[70:73], v[162:165], v[202:205], v[70:73]
	v_mfma_f32_16x16x32_bf16 v[66:69], v[170:173], v[202:205], v[66:69]
	v_mfma_f32_16x16x32_bf16 v[118:121], v[166:169], v[182:185], v[118:121]
	v_mfma_f32_16x16x32_bf16 v[114:117], v[174:177], v[182:185], v[114:117]
	v_mfma_f32_16x16x32_bf16 v[102:105], v[166:169], v[190:193], v[102:105]
	v_mfma_f32_16x16x32_bf16 v[98:101], v[174:177], v[190:193], v[98:101]
	v_mfma_f32_16x16x32_bf16 v[86:89], v[166:169], v[198:201], v[86:89]
	v_mfma_f32_16x16x32_bf16 v[82:85], v[174:177], v[198:201], v[82:85]
	v_mfma_f32_16x16x32_bf16 v[70:73], v[166:169], v[206:209], v[70:73]
	v_mfma_f32_16x16x32_bf16 v[66:69], v[174:177], v[206:209], v[66:69]
	s_barrier
	s_add_i32 s6, s91, s12
	s_mov_b32 m0, s6
	ds_read_b128 v[178:181], v161 offset:49152
	ds_read_b128 v[182:185], v161 offset:50176
	ds_read_b128 v[186:189], v161 offset:51200
	ds_read_b128 v[190:193], v161 offset:52224
	ds_read_b128 v[194:197], v161 offset:53248
	s_add_u32 s100, s16, 0x80
	s_addc_u32 s101, s17, 0
	global_load_lds_dwordx4 v16, s[100:101]
	s_add_i32 m0, s6, 0x2000
	s_add_u32 s6, s16, 0x100080
	s_addc_u32 s7, s17, 0
	s_add_i32 s16, s94, s12
	global_load_lds_dwordx4 v138, s[100:101]
	s_mov_b32 m0, s16
	ds_read_b128 v[206:209], v161 offset:56320
	global_load_lds_dwordx4 v16, s[6:7]
	s_add_i32 m0, s16, 0x2000
	ds_read_b128 v[202:205], v161 offset:55296
	global_load_lds_dwordx4 v138, s[6:7]
	s_mov_b32 m0, s68
	s_nop 0
	s_add_u32 vcc_lo, s40, 0x80
	s_addc_u32 vcc_hi, s41, 0
	global_load_lds_dwordx4 v142, vcc
	s_mov_b32 m0, s69
	ds_read_b128 v[198:201], v161 offset:54272
	global_load_lds_dwordx4 v140, vcc
	s_waitcnt vmcnt(8) lgkmcnt(0)
	s_nop 0
	s_barrier
	v_mfma_f32_16x16x32_bf16 v[62:65], v[130:133], v[178:181], v[62:65]
	v_mfma_f32_16x16x32_bf16 v[58:61], v[148:151], v[178:181], v[58:61]
	v_mfma_f32_16x16x32_bf16 v[46:49], v[130:133], v[186:189], v[46:49]
	v_mfma_f32_16x16x32_bf16 v[42:45], v[148:151], v[186:189], v[42:45]
	v_mfma_f32_16x16x32_bf16 v[30:33], v[130:133], v[194:197], v[30:33]
	v_mfma_f32_16x16x32_bf16 v[26:29], v[148:151], v[194:197], v[26:29]
	v_mfma_f32_16x16x32_bf16 v[12:15], v[130:133], v[202:205], v[12:15]
	v_mfma_f32_16x16x32_bf16 v[8:11], v[148:151], v[202:205], v[8:11]
	v_mfma_f32_16x16x32_bf16 v[62:65], v[134:137], v[182:185], v[62:65]
	v_mfma_f32_16x16x32_bf16 v[58:61], v[152:155], v[182:185], v[58:61]
	v_mfma_f32_16x16x32_bf16 v[46:49], v[134:137], v[190:193], v[46:49]
	v_mfma_f32_16x16x32_bf16 v[42:45], v[152:155], v[190:193], v[42:45]
	v_mfma_f32_16x16x32_bf16 v[30:33], v[134:137], v[198:201], v[30:33]
	v_mfma_f32_16x16x32_bf16 v[26:29], v[152:155], v[198:201], v[26:29]
	v_mfma_f32_16x16x32_bf16 v[12:15], v[134:137], v[206:209], v[12:15]
	v_mfma_f32_16x16x32_bf16 v[8:11], v[152:155], v[206:209], v[8:11]
	v_mfma_f32_16x16x32_bf16 v[54:57], v[162:165], v[178:181], v[54:57]
	v_mfma_f32_16x16x32_bf16 v[50:53], v[170:173], v[178:181], v[50:53]
	v_mfma_f32_16x16x32_bf16 v[38:41], v[162:165], v[186:189], v[38:41]
	v_mfma_f32_16x16x32_bf16 v[34:37], v[170:173], v[186:189], v[34:37]
	v_mfma_f32_16x16x32_bf16 v[22:25], v[162:165], v[194:197], v[22:25]
	v_mfma_f32_16x16x32_bf16 v[18:21], v[170:173], v[194:197], v[18:21]
	v_mfma_f32_16x16x32_bf16 v[4:7], v[162:165], v[202:205], v[4:7]
	v_mfma_f32_16x16x32_bf16 v[0:3], v[170:173], v[202:205], v[0:3]
	v_mfma_f32_16x16x32_bf16 v[54:57], v[166:169], v[182:185], v[54:57]
	v_mfma_f32_16x16x32_bf16 v[50:53], v[174:177], v[182:185], v[50:53]
	v_mfma_f32_16x16x32_bf16 v[38:41], v[166:169], v[190:193], v[38:41]
	v_mfma_f32_16x16x32_bf16 v[34:37], v[174:177], v[190:193], v[34:37]
	v_mfma_f32_16x16x32_bf16 v[22:25], v[166:169], v[198:201], v[22:25]
	v_mfma_f32_16x16x32_bf16 v[18:21], v[174:177], v[198:201], v[18:21]
	v_mfma_f32_16x16x32_bf16 v[4:7], v[166:169], v[206:209], v[4:7]
	v_mfma_f32_16x16x32_bf16 v[0:3], v[174:177], v[206:209], v[0:3]
	s_barrier
	s_add_i32 s90, s90, 2
	s_add_u32 s38, s38, 0x100
	s_addc_u32 s39, s39, 0
	s_add_u32 s0, s0, 0x100
	s_addc_u32 s1, s1, 0
	s_cmp_gt_u32 s90, 61
	s_cbranch_scc0 .LBB0_558
	s_and_b64 vcc, exec, s[18:19]
	s_cbranch_vccz .LBB0_561
	s_barrier

; #define PG8_STAGEA(bufoff, gbase, voff) PG8_STAGE_X(bufoff, gbase, voff, AUXA)
; #define PG8_STR(x) PG8_STR2(x)
;     ...
;         const bool has_next = S.next(ui + 1, nxt);
;         const char* nA = has_next ? (const char*)g.A + (size_t)nxt.pm * tstepA : cA; const char* nB = has_next ? (const char*)g.Bt + (size_t)nxt.pn * tstepB : cB;
;         int t0 = 0;
;         if constexpr (SP2 && GEMM_RELAX == 1) { if (ui > 0) {
;             const char* a1 = cA + kstepA; const char* a2 = cA + 2 * kstepA; const char* b2 = cB + 2 * kstepB; const char* a3 = a2 + kstepA; const char* b3 = b2 + kstepB;
;             PG8_LDB(B0, 0, 0); PG8_LDB(B1, 0, 1); PG8_SCHED; PG8_LDA(At, 0, 0); PG8_STAGEA(PG8_SA(1, 1), a1 + hstepA, voffA);
;             PG8_WAIT_V(24); PG8_WAIT_L(0); PG8_BAR; PG8_MMA(0, 0, At, B0); PG8_MMA(0, 1, At, B1); PG8_BAR; PG8_SCHED;
;             PG8_LDA(At, 0, 1); PG8_STAGEB(PG8_SB(0, 0), b2, voffB); PG8_STAGEB(PG8_SB(0, 1), b2 + hstepB, voffB); PG8_STAGEA(PG8_SA(0, 0), a2, voffA);
;             PG8_WAIT_V(24); PG8_WAIT_L(0); PG8_BAR; PG8_MMA(1, 0, At, B0); PG8_MMA(1, 1, At, B1); PG8_BAR; PG8_SCHED;
;             PG8_LDB(B0, 1, 0); PG8_LDB(B1, 1, 1); PG8_SCHED; PG8_LDA(At, 1, 0); PG8_STAGEA(PG8_SA(0, 1), a2 + hstepA, voffA);
;             PG8_WAIT_V(8); PG8_WAIT_L(0); PG8_BAR; PG8_MMA(0, 0, At, B0); PG8_MMA(0, 1, At, B1); PG8_BAR; PG8_SCHED;
;             PG8_LDA(At, 1, 1); PG8_STAGEB(PG8_SB(1, 0), b3, voffB); PG8_STAGEB(PG8_SB(1, 1), b3 + hstepB, voffB); PG8_STAGEA(PG8_SA(1, 0), a3, voffA);
;             PG8_WAIT_V(8); PG8_WAIT_L(0); PG8_BAR; PG8_MMA(1, 0, At, B0); PG8_MMA(1, 1, At, B1); PG8_BAR; PG8_SCHED;
;             t0 = 2; } }
;     ...
;         asm volatile(".p2align " PG8_STR(GEMM_LOOP_ALIGN) ::: "memory");
;     ...
;         for (int t = t0; t < nt; t += 2) {
;             const bool last = (t == nt - 2);
;             const char* a1 = cA + (size_t)(t + 1) * kstepA;
;             const char* a2 = last ? nA : cA + (size_t)(t + 2) * kstepA; const char* b2 = last ? nB : cB + (size_t)(t + 2) * kstepB;
;             const char* a3 = a2 + kstepA; const char* b3 = b2 + kstepB;
;             if (last && has_next) S.a_ready(nxt);
;             if constexpr (SP2) {
;             PG8_LDB(B0, 0, 0); PG8_LDB(B1, 0, 1); PG8_SCHED; PG8_LDA(At, 0, 0); PG8_STAGEA(PG8_SA(1, 1), a1 + hstepA, voffA);
;     ...
;             const int relax = __builtin_amdgcn_readfirstlane((t == 0 && ui > 0) ? 1 : 0);
.LBB0_711:
	s_ashr_i32 s25, s24, 31
	s_lshl_b64 s[0:1], s[24:25], 21
	s_add_u32 s26, s56, s0
	s_addc_u32 s27, s57, s1
	s_and_b64 s[0:1], s[10:11], exec
	s_cselect_b32 s0, s27, s13
	s_cselect_b32 s1, s26, s12
	s_ashr_i32 s23, s22, 31
	s_lshl_b64 s[6:7], s[22:23], 21
	s_add_u32 s36, s51, s6
	s_addc_u32 s37, s68, s7
	s_and_b64 s[6:7], s[10:11], exec
	s_cselect_b32 s23, s37, s43
	s_cselect_b32 s25, s36, s42
	s_add_u32 s40, s12, 0x100080
	s_addc_u32 s41, s13, 0
	s_add_u32 s12, s42, 0x100
	s_addc_u32 s13, s43, 0
	s_mov_b32 s39, -2
	s_add_u32 s6, s40, 0xfff00080
	s_addc_u32 s7, s41, -1
	s_add_i32 s95, 0, 0x10000
	s_cmp_eq_u32 s39, 60
	s_cselect_b32 s43, s0, s7
	s_cselect_b32 s42, s1, s6
	v_add_u32_e32 v144, s95, v146
	s_cselect_b32 s17, s23, s13
	s_cselect_b32 s16, s25, s12
	s_add_i32 vcc_lo, 0, 0x14000
	ds_read_b128 v[150:153], v144
	ds_read_b128 v[154:157], v144 offset:1024
	ds_read_b128 v[158:161], v144 offset:2048
	ds_read_b128 v[162:165], v144 offset:3072
	v_add_u32_e32 v144, vcc_lo, v146
	ds_read_b128 v[166:169], v144
	ds_read_b128 v[170:173], v144 offset:1024
	ds_read_b128 v[174:177], v144 offset:2048
	ds_read_b128 v[178:181], v144 offset:3072
	v_lshl_add_u64 v[144:145], s[40:41], 0, v[140:141]
	s_add_i32 m0, s69, 0xc000
	ds_read_b128 v[182:185], v148
	ds_read_b128 v[186:189], v148 offset:1024
	ds_read_b128 v[190:193], v148 offset:2048
	ds_read_b128 v[194:197], v148 offset:3072
	ds_read_b128 v[198:201], v148 offset:4096
	ds_read_b128 v[202:205], v148 offset:5120
	ds_read_b128 v[206:209], v148 offset:6144
	ds_read_b128 v[210:213], v148 offset:7168
	global_load_lds_dwordx4 v[144:145], off
	v_lshl_add_u64 v[144:145], s[40:41], 0, v[142:143]
	s_add_i32 m0, s69, 0xe000
	s_nop 0
	global_load_lds_dwordx4 v[144:145], off
	s_waitcnt vmcnt(8) lgkmcnt(0)
	s_barrier
	v_mfma_f32_16x16x32_bf16 v[126:129], v[150:153], v[182:185], 0
	v_mfma_f32_16x16x32_bf16 v[122:125], v[158:161], v[182:185], 0
	v_mfma_f32_16x16x32_bf16 v[110:113], v[150:153], v[190:193], 0
	v_mfma_f32_16x16x32_bf16 v[106:109], v[158:161], v[190:193], 0
	v_mfma_f32_16x16x32_bf16 v[94:97], v[150:153], v[198:201], 0
	v_mfma_f32_16x16x32_bf16 v[90:93], v[158:161], v[198:201], 0
	v_mfma_f32_16x16x32_bf16 v[78:81], v[150:153], v[206:209], 0
	v_mfma_f32_16x16x32_bf16 v[74:77], v[158:161], v[206:209], 0
	v_mfma_f32_16x16x32_bf16 v[126:129], v[154:157], v[186:189], v[126:129]
	v_mfma_f32_16x16x32_bf16 v[122:125], v[162:165], v[186:189], v[122:125]
	v_mfma_f32_16x16x32_bf16 v[110:113], v[154:157], v[194:197], v[110:113]
	v_mfma_f32_16x16x32_bf16 v[106:109], v[162:165], v[194:197], v[106:109]
	v_mfma_f32_16x16x32_bf16 v[94:97], v[154:157], v[202:205], v[94:97]
	v_mfma_f32_16x16x32_bf16 v[90:93], v[162:165], v[202:205], v[90:93]
	v_mfma_f32_16x16x32_bf16 v[78:81], v[154:157], v[210:213], v[78:81]
	v_mfma_f32_16x16x32_bf16 v[74:77], v[162:165], v[210:213], v[74:77]
	v_mfma_f32_16x16x32_bf16 v[118:121], v[166:169], v[182:185], 0
	v_mfma_f32_16x16x32_bf16 v[114:117], v[174:177], v[182:185], 0
	v_mfma_f32_16x16x32_bf16 v[102:105], v[166:169], v[190:193], 0
	v_mfma_f32_16x16x32_bf16 v[98:101], v[174:177], v[190:193], 0
	v_mfma_f32_16x16x32_bf16 v[86:89], v[166:169], v[198:201], 0
	v_mfma_f32_16x16x32_bf16 v[82:85], v[174:177], v[198:201], 0
	v_mfma_f32_16x16x32_bf16 v[70:73], v[166:169], v[206:209], 0
	v_mfma_f32_16x16x32_bf16 v[66:69], v[174:177], v[206:209], 0
	v_mfma_f32_16x16x32_bf16 v[118:121], v[170:173], v[186:189], v[118:121]
	v_mfma_f32_16x16x32_bf16 v[114:117], v[178:181], v[186:189], v[114:117]
	v_mfma_f32_16x16x32_bf16 v[102:105], v[170:173], v[194:197], v[102:105]
	v_mfma_f32_16x16x32_bf16 v[98:101], v[178:181], v[194:197], v[98:101]
	v_mfma_f32_16x16x32_bf16 v[86:89], v[170:173], v[202:205], v[86:89]
	v_mfma_f32_16x16x32_bf16 v[82:85], v[178:181], v[202:205], v[82:85]
	v_mfma_f32_16x16x32_bf16 v[70:73], v[170:173], v[210:213], v[70:73]
	v_mfma_f32_16x16x32_bf16 v[66:69], v[178:181], v[210:213], v[66:69]
	s_barrier
	s_add_i32 s6, s95, s50
	v_lshl_add_u64 v[144:145], s[16:17], 0, v[134:135]
	s_mov_b32 m0, s6
	ds_read_b128 v[182:185], v148 offset:16384
	ds_read_b128 v[186:189], v148 offset:17408
	ds_read_b128 v[190:193], v148 offset:18432
	ds_read_b128 v[194:197], v148 offset:19456
	ds_read_b128 v[198:201], v148 offset:20480
	ds_read_b128 v[202:205], v148 offset:21504
	ds_read_b128 v[206:209], v148 offset:22528
	ds_read_b128 v[210:213], v148 offset:23552
	global_load_lds_dwordx4 v[144:145], off
	s_add_i32 m0, s6, 0x2000
	s_add_u32 s6, s16, 0x100000
	v_lshl_add_u64 v[214:215], s[16:17], 0, v[130:131]
	s_addc_u32 s7, s17, 0
	s_add_i32 s95, vcc_lo, s50
	global_load_lds_dwordx4 v[214:215], off
	v_lshl_add_u64 v[216:217], s[6:7], 0, v[134:135]
	s_mov_b32 m0, s95
	v_lshl_add_u64 v[218:219], s[42:43], 0, v[132:133]
	global_load_lds_dwordx4 v[216:217], off
	v_lshl_add_u64 v[216:217], s[6:7], 0, v[130:131]
	s_add_i32 m0, s95, 0x2000
	s_nop 0
	global_load_lds_dwordx4 v[216:217], off
	v_lshl_add_u64 v[216:217], s[42:43], 0, v[136:137]
	s_mov_b32 m0, s69
	s_nop 0
	global_load_lds_dwordx4 v[216:217], off
	s_mov_b32 m0, s72
	s_nop 0
	global_load_lds_dwordx4 v[218:219], off
	s_waitcnt vmcnt(8) lgkmcnt(0)
	s_nop 0
	s_barrier
; #define PG8_STAGEA(bufoff, gbase, voff) PG8_STAGE_X(bufoff, gbase, voff, AUXA)
; #define PG8_STAGEB(bufoff, gbase, voff) PG8_STAGE_X(bufoff, gbase, voff, AUXB)
; #define PG8_LDA(dst, b, h) do { _Pragma("unroll") for (int m = 0; m < 4; ++m) _Pragma("unroll") for (int k = 0; k < 2; ++k) dst[m][k] = *(const PG8_LAS bf16x8*)(lds + PG8_SA(b, h) + aoff + m * 2048 + k * 1024); } while (0)
; #define PG8_LDB(dst, b, h) do { _Pragma("unroll") for (int n = 0; n < 2; ++n) _Pragma("unroll") for (int k = 0; k < 2; ++k) dst[n][k] = *(const PG8_LAS bf16x8*)(lds + PG8_SB(b, h) + boff + n * 2048 + k * 1024); } while (0)
; #define PG8_MMA(ai, bj, At, Bt) do { if (GEMM_PRIO_MODE == 0) __builtin_amdgcn_s_setprio(1); PG8_MMA_LOOPS \
;         acc[ai][bj][m][n] = __builtin_amdgcn_mfma_f32_16x16x32_bf16(Bt[n][k], At[m][k], acc[ai][bj][m][n], 0, 0, 0); if (GEMM_PRIO_MODE == 0) __builtin_amdgcn_s_setprio(0); } while (0)
; #define PG8_WAIT_V(n) asm volatile("s_waitcnt vmcnt(" #n ")" ::: "memory")
; #define PG8_WAIT_VR(n, nr, flag) asm volatile("s_cmp_eq_u32 %0, 0\n\ts_cbranch_scc1 .Lpg8s%=\n\ts_waitcnt vmcnt(" #nr ")\n\ts_branch .Lpg8d%=\n.Lpg8s%=:\n\ts_waitcnt vmcnt(" #n ")\n.Lpg8d%=:" :: "s"(flag) : "memory", "scc")
; #define PG8_WAIT_L(n) asm volatile("s_waitcnt lgkmcnt(" #n ")" ::: "memory")
; #define PG8_BAR __builtin_amdgcn_s_barrier()
; #define PG8_SCHED __builtin_amdgcn_sched_barrier(0)
;     ...
;             PG8_LDA(At, 0, 1); PG8_STAGEB(PG8_SB(0, 0), b2, voffB); PG8_STAGEB(PG8_SB(0, 1), b2 + hstepB, voffB); PG8_STAGEA(PG8_SA(0, 0), a2, voffA);
;     ...
;             PG8_WAIT_VR(8, 24, relax); PG8_WAIT_L(0); PG8_BAR; PG8_MMA(1, 0, At, B0); PG8_MMA(1, 1, At, B1); PG8_BAR; PG8_SCHED;
;     ...
;             PG8_WAIT_V(8); PG8_WAIT_L(0); PG8_BAR; PG8_MMA(1, 0, At, B0); PG8_MMA(1, 1, At, B1); PG8_BAR; PG8_SCHED;
;     ...
;             PG8_LDB(B0, 1, 0); PG8_LDB(B1, 1, 1); PG8_SCHED; PG8_LDA(At, 1, 0); PG8_STAGEA(PG8_SA(0, 1), a2 + hstepA, voffA);
;             PG8_WAIT_V(8); PG8_WAIT_L(0); PG8_BAR; PG8_MMA(0, 0, At, B0); PG8_MMA(0, 1, At, B1); PG8_BAR; PG8_SCHED;
;             PG8_LDA(At, 1, 1); PG8_STAGEB(PG8_SB(1, 0), b3, voffB); PG8_STAGEB(PG8_SB(1, 1), b3 + hstepB, voffB); PG8_STAGEA(PG8_SA(1, 0), a3, voffA);
;             PG8_WAIT_V(8); PG8_WAIT_L(0); PG8_BAR; PG8_MMA(1, 0, At, B0); PG8_MMA(1, 1, At, B1); PG8_BAR; PG8_SCHED;
	v_mfma_f32_16x16x32_bf16 v[62:65], v[150:153], v[182:185], 0
	v_mfma_f32_16x16x32_bf16 v[58:61], v[158:161], v[182:185], 0
	v_mfma_f32_16x16x32_bf16 v[46:49], v[150:153], v[190:193], 0
	v_mfma_f32_16x16x32_bf16 v[42:45], v[158:161], v[190:193], 0
	v_mfma_f32_16x16x32_bf16 v[30:33], v[150:153], v[198:201], 0
	v_mfma_f32_16x16x32_bf16 v[26:29], v[158:161], v[198:201], 0
	v_mfma_f32_16x16x32_bf16 v[12:15], v[150:153], v[206:209], 0
	v_mfma_f32_16x16x32_bf16 v[8:11], v[158:161], v[206:209], 0
	v_mfma_f32_16x16x32_bf16 v[62:65], v[154:157], v[186:189], v[62:65]
	v_mfma_f32_16x16x32_bf16 v[58:61], v[162:165], v[186:189], v[58:61]
	v_mfma_f32_16x16x32_bf16 v[46:49], v[154:157], v[194:197], v[46:49]
	v_mfma_f32_16x16x32_bf16 v[42:45], v[162:165], v[194:197], v[42:45]
	v_mfma_f32_16x16x32_bf16 v[30:33], v[154:157], v[202:205], v[30:33]
	v_mfma_f32_16x16x32_bf16 v[26:29], v[162:165], v[202:205], v[26:29]
	v_mfma_f32_16x16x32_bf16 v[12:15], v[154:157], v[210:213], v[12:15]
	v_mfma_f32_16x16x32_bf16 v[8:11], v[162:165], v[210:213], v[8:11]
	v_mfma_f32_16x16x32_bf16 v[54:57], v[166:169], v[182:185], 0
	v_mfma_f32_16x16x32_bf16 v[50:53], v[174:177], v[182:185], 0
	v_mfma_f32_16x16x32_bf16 v[38:41], v[166:169], v[190:193], 0
	v_mfma_f32_16x16x32_bf16 v[34:37], v[174:177], v[190:193], 0
	v_mfma_f32_16x16x32_bf16 v[22:25], v[166:169], v[198:201], 0
	v_mfma_f32_16x16x32_bf16 v[18:21], v[174:177], v[198:201], 0
	v_mfma_f32_16x16x32_bf16 v[4:7], v[166:169], v[206:209], 0
	v_mfma_f32_16x16x32_bf16 v[0:3], v[174:177], v[206:209], 0
	v_mfma_f32_16x16x32_bf16 v[54:57], v[170:173], v[186:189], v[54:57]
	v_mfma_f32_16x16x32_bf16 v[50:53], v[178:181], v[186:189], v[50:53]
	v_mfma_f32_16x16x32_bf16 v[38:41], v[170:173], v[194:197], v[38:41]
	v_mfma_f32_16x16x32_bf16 v[34:37], v[178:181], v[194:197], v[34:37]
	v_mfma_f32_16x16x32_bf16 v[22:25], v[170:173], v[202:205], v[22:25]
	v_mfma_f32_16x16x32_bf16 v[18:21], v[178:181], v[202:205], v[18:21]
	v_mfma_f32_16x16x32_bf16 v[4:7], v[170:173], v[210:213], v[4:7]
	v_mfma_f32_16x16x32_bf16 v[0:3], v[178:181], v[210:213], v[0:3]
	s_barrier
	s_add_i32 s95, 0, 0x18000
	v_add_u32_e32 v149, s95, v146
	s_add_i32 vcc_lo, 0, 0x1c000
	ds_read_b128 v[150:153], v149
	ds_read_b128 v[154:157], v149 offset:1024
	ds_read_b128 v[158:161], v149 offset:2048
	ds_read_b128 v[162:165], v149 offset:3072
	v_add_u32_e32 v149, vcc_lo, v146
	ds_read_b128 v[166:169], v149
	ds_read_b128 v[170:173], v149 offset:1024
	ds_read_b128 v[174:177], v149 offset:2048
	ds_read_b128 v[178:181], v149 offset:3072
	s_add_u32 s6, s42, 0x100000
	s_addc_u32 s7, s43, 0
	s_mov_b32 m0, s73
	v_lshl_add_u64 v[220:221], s[6:7], 0, v[136:137]
	ds_read_b128 v[182:185], v148 offset:32768
	ds_read_b128 v[186:189], v148 offset:33792
	ds_read_b128 v[190:193], v148 offset:34816
	ds_read_b128 v[194:197], v148 offset:35840
	ds_read_b128 v[198:201], v148 offset:36864
	ds_read_b128 v[202:205], v148 offset:37888
	ds_read_b128 v[206:209], v148 offset:38912
	ds_read_b128 v[210:213], v148 offset:39936
	global_load_lds_dwordx4 v[220:221], off
	v_lshl_add_u64 v[220:221], s[6:7], 0, v[132:133]
	s_mov_b32 m0, s82
	s_nop 0
	global_load_lds_dwordx4 v[220:221], off
	s_waitcnt vmcnt(8) lgkmcnt(0)
	s_nop 0
	s_nop 0
	s_nop 0
	s_barrier
	v_mfma_f32_16x16x32_bf16 v[126:129], v[150:153], v[182:185], v[126:129]
	v_mfma_f32_16x16x32_bf16 v[122:125], v[158:161], v[182:185], v[122:125]
	v_mfma_f32_16x16x32_bf16 v[110:113], v[150:153], v[190:193], v[110:113]
	v_mfma_f32_16x16x32_bf16 v[106:109], v[158:161], v[190:193], v[106:109]
	v_mfma_f32_16x16x32_bf16 v[94:97], v[150:153], v[198:201], v[94:97]
	v_mfma_f32_16x16x32_bf16 v[90:93], v[158:161], v[198:201], v[90:93]
	v_mfma_f32_16x16x32_bf16 v[78:81], v[150:153], v[206:209], v[78:81]
	v_mfma_f32_16x16x32_bf16 v[74:77], v[158:161], v[206:209], v[74:77]
	v_mfma_f32_16x16x32_bf16 v[126:129], v[154:157], v[186:189], v[126:129]
	v_mfma_f32_16x16x32_bf16 v[122:125], v[162:165], v[186:189], v[122:125]
	v_mfma_f32_16x16x32_bf16 v[110:113], v[154:157], v[194:197], v[110:113]
	v_mfma_f32_16x16x32_bf16 v[106:109], v[162:165], v[194:197], v[106:109]
	v_mfma_f32_16x16x32_bf16 v[94:97], v[154:157], v[202:205], v[94:97]
	v_mfma_f32_16x16x32_bf16 v[90:93], v[162:165], v[202:205], v[90:93]
	v_mfma_f32_16x16x32_bf16 v[78:81], v[154:157], v[210:213], v[78:81]
	v_mfma_f32_16x16x32_bf16 v[74:77], v[162:165], v[210:213], v[74:77]
	v_mfma_f32_16x16x32_bf16 v[118:121], v[166:169], v[182:185], v[118:121]
	v_mfma_f32_16x16x32_bf16 v[114:117], v[174:177], v[182:185], v[114:117]
	v_mfma_f32_16x16x32_bf16 v[102:105], v[166:169], v[190:193], v[102:105]
	v_mfma_f32_16x16x32_bf16 v[98:101], v[174:177], v[190:193], v[98:101]
	v_mfma_f32_16x16x32_bf16 v[86:89], v[166:169], v[198:201], v[86:89]
	v_mfma_f32_16x16x32_bf16 v[82:85], v[174:177], v[198:201], v[82:85]
	v_mfma_f32_16x16x32_bf16 v[70:73], v[166:169], v[206:209], v[70:73]
	v_mfma_f32_16x16x32_bf16 v[66:69], v[174:177], v[206:209], v[66:69]
	v_mfma_f32_16x16x32_bf16 v[118:121], v[170:173], v[186:189], v[118:121]
	v_mfma_f32_16x16x32_bf16 v[114:117], v[178:181], v[186:189], v[114:117]
	v_mfma_f32_16x16x32_bf16 v[102:105], v[170:173], v[194:197], v[102:105]
	v_mfma_f32_16x16x32_bf16 v[98:101], v[178:181], v[194:197], v[98:101]
	v_mfma_f32_16x16x32_bf16 v[86:89], v[170:173], v[202:205], v[86:89]
	v_mfma_f32_16x16x32_bf16 v[82:85], v[178:181], v[202:205], v[82:85]
	v_mfma_f32_16x16x32_bf16 v[70:73], v[170:173], v[210:213], v[70:73]
	v_mfma_f32_16x16x32_bf16 v[66:69], v[178:181], v[210:213], v[66:69]
	s_barrier
; #define PG8_STAGEA(bufoff, gbase, voff) PG8_STAGE_X(bufoff, gbase, voff, AUXA)
; #define PG8_STAGEB(bufoff, gbase, voff) PG8_STAGE_X(bufoff, gbase, voff, AUXB)
; #define PG8_LDA(dst, b, h) do { _Pragma("unroll") for (int m = 0; m < 4; ++m) _Pragma("unroll") for (int k = 0; k < 2; ++k) dst[m][k] = *(const PG8_LAS bf16x8*)(lds + PG8_SA(b, h) + aoff + m * 2048 + k * 1024); } while (0)
; #define PG8_WAIT_V(n) asm volatile("s_waitcnt vmcnt(" #n ")" ::: "memory")
; #define PG8_WAIT_L(n) asm volatile("s_waitcnt lgkmcnt(" #n ")" ::: "memory")
;     ...
;         for (int t = t0; t < nt; t += 2) {
;             const bool last = (t == nt - 2);
;             const char* a1 = cA + (size_t)(t + 1) * kstepA;
;             const char* a2 = last ? nA : cA + (size_t)(t + 2) * kstepA; const char* b2 = last ? nB : cB + (size_t)(t + 2) * kstepB;
;             const char* a3 = a2 + kstepA; const char* b3 = b2 + kstepB;
;             if (last && has_next) S.a_ready(nxt);
;             if constexpr (SP2) {
;             PG8_LDB(B0, 0, 0); PG8_LDB(B1, 0, 1); PG8_SCHED; PG8_LDA(At, 0, 0); PG8_STAGEA(PG8_SA(1, 1), a1 + hstepA, voffA);
;     ...
;             const int relax = __builtin_amdgcn_readfirstlane((t == 0 && ui > 0) ? 1 : 0);
;             PG8_WAIT_VR(8, 24, relax); PG8_WAIT_L(0); PG8_BAR; PG8_MMA(0, 0, At, B0); PG8_MMA(0, 1, At, B1); PG8_BAR; PG8_SCHED;
;     ...
;             PG8_WAIT_V(8); PG8_WAIT_L(0); PG8_BAR; PG8_MMA(0, 0, At, B0); PG8_MMA(0, 1, At, B1); PG8_BAR; PG8_SCHED;
;     ...
;             PG8_LDA(At, 0, 1); PG8_STAGEB(PG8_SB(0, 0), b2, voffB); PG8_STAGEB(PG8_SB(0, 1), b2 + hstepB, voffB); PG8_STAGEA(PG8_SA(0, 0), a2, voffA);
;     ...
;             PG8_WAIT_VR(8, 24, relax); PG8_WAIT_L(0); PG8_BAR; PG8_MMA(1, 0, At, B0); PG8_MMA(1, 1, At, B1); PG8_BAR; PG8_SCHED;
;     ...
;             PG8_WAIT_V(8); PG8_WAIT_L(0); PG8_BAR; PG8_MMA(1, 0, At, B0); PG8_MMA(1, 1, At, B1); PG8_BAR; PG8_SCHED;
;     ...
;             PG8_LDB(B0, 1, 0); PG8_LDB(B1, 1, 1); PG8_SCHED; PG8_LDA(At, 1, 0); PG8_STAGEA(PG8_SA(0, 1), a2 + hstepA, voffA);
;             PG8_WAIT_V(8); PG8_WAIT_L(0); PG8_BAR; PG8_MMA(0, 0, At, B0); PG8_MMA(0, 1, At, B1); PG8_BAR; PG8_SCHED;
;             PG8_LDA(At, 1, 1); PG8_STAGEB(PG8_SB(1, 0), b3, voffB); PG8_STAGEB(PG8_SB(1, 1), b3 + hstepB, voffB); PG8_STAGEA(PG8_SA(1, 0), a3, voffA);
;             PG8_WAIT_V(8); PG8_WAIT_L(0); PG8_BAR; PG8_MMA(1, 0, At, B0); PG8_MMA(1, 1, At, B1); PG8_BAR; PG8_SCHED;
	s_add_i32 s6, s95, s50
	v_lshl_add_u64 v[144:145], v[144:145], 0, s[86:87]
	s_mov_b32 m0, s6
	ds_read_b128 v[182:185], v148 offset:49152
	ds_read_b128 v[186:189], v148 offset:50176
	ds_read_b128 v[190:193], v148 offset:51200
	ds_read_b128 v[194:197], v148 offset:52224
	ds_read_b128 v[198:201], v148 offset:53248
	ds_read_b128 v[202:205], v148 offset:54272
	ds_read_b128 v[206:209], v148 offset:55296
	ds_read_b128 v[210:213], v148 offset:56320
	global_load_lds_dwordx4 v[144:145], off
	s_add_i32 m0, s6, 0x2000
	s_add_u32 s6, s16, 0x100080
	v_lshl_add_u64 v[144:145], v[214:215], 0, s[86:87]
	s_addc_u32 s7, s17, 0
	s_add_i32 s16, vcc_lo, s50
	global_load_lds_dwordx4 v[144:145], off
	v_lshl_add_u64 v[144:145], s[6:7], 0, v[134:135]
	s_mov_b32 m0, s16
	s_nop 0
	global_load_lds_dwordx4 v[144:145], off
	v_lshl_add_u64 v[144:145], s[6:7], 0, v[130:131]
	s_add_i32 m0, s16, 0x2000
	s_nop 0
	global_load_lds_dwordx4 v[144:145], off
	v_lshl_add_u64 v[144:145], v[216:217], 0, s[86:87]
	s_mov_b32 m0, s83
	s_nop 0
	global_load_lds_dwordx4 v[144:145], off
	v_lshl_add_u64 v[144:145], v[218:219], 0, s[86:87]
	s_mov_b32 m0, s90
	s_nop 0
	global_load_lds_dwordx4 v[144:145], off
	s_waitcnt vmcnt(8) lgkmcnt(0)
	s_barrier
	v_mfma_f32_16x16x32_bf16 v[62:65], v[150:153], v[182:185], v[62:65]
	v_mfma_f32_16x16x32_bf16 v[58:61], v[158:161], v[182:185], v[58:61]
	v_mfma_f32_16x16x32_bf16 v[46:49], v[150:153], v[190:193], v[46:49]
	v_mfma_f32_16x16x32_bf16 v[42:45], v[158:161], v[190:193], v[42:45]
	v_mfma_f32_16x16x32_bf16 v[30:33], v[150:153], v[198:201], v[30:33]
	v_mfma_f32_16x16x32_bf16 v[26:29], v[158:161], v[198:201], v[26:29]
	v_mfma_f32_16x16x32_bf16 v[12:15], v[150:153], v[206:209], v[12:15]
	v_mfma_f32_16x16x32_bf16 v[8:11], v[158:161], v[206:209], v[8:11]
	v_mfma_f32_16x16x32_bf16 v[62:65], v[154:157], v[186:189], v[62:65]
	v_mfma_f32_16x16x32_bf16 v[58:61], v[162:165], v[186:189], v[58:61]
	v_mfma_f32_16x16x32_bf16 v[46:49], v[154:157], v[194:197], v[46:49]
	v_mfma_f32_16x16x32_bf16 v[42:45], v[162:165], v[194:197], v[42:45]
	v_mfma_f32_16x16x32_bf16 v[30:33], v[154:157], v[202:205], v[30:33]
	v_mfma_f32_16x16x32_bf16 v[26:29], v[162:165], v[202:205], v[26:29]
	v_mfma_f32_16x16x32_bf16 v[12:15], v[154:157], v[210:213], v[12:15]
	v_mfma_f32_16x16x32_bf16 v[8:11], v[162:165], v[210:213], v[8:11]
	v_mfma_f32_16x16x32_bf16 v[54:57], v[166:169], v[182:185], v[54:57]
	v_mfma_f32_16x16x32_bf16 v[50:53], v[174:177], v[182:185], v[50:53]
	v_mfma_f32_16x16x32_bf16 v[38:41], v[166:169], v[190:193], v[38:41]
	v_mfma_f32_16x16x32_bf16 v[34:37], v[174:177], v[190:193], v[34:37]
	v_mfma_f32_16x16x32_bf16 v[22:25], v[166:169], v[198:201], v[22:25]
	v_mfma_f32_16x16x32_bf16 v[18:21], v[174:177], v[198:201], v[18:21]
	v_mfma_f32_16x16x32_bf16 v[4:7], v[166:169], v[206:209], v[4:7]
	v_mfma_f32_16x16x32_bf16 v[0:3], v[174:177], v[206:209], v[0:3]
	v_mfma_f32_16x16x32_bf16 v[54:57], v[170:173], v[186:189], v[54:57]
	v_mfma_f32_16x16x32_bf16 v[50:53], v[178:181], v[186:189], v[50:53]
	v_mfma_f32_16x16x32_bf16 v[38:41], v[170:173], v[194:197], v[38:41]
	v_mfma_f32_16x16x32_bf16 v[34:37], v[178:181], v[194:197], v[34:37]
	v_mfma_f32_16x16x32_bf16 v[22:25], v[170:173], v[202:205], v[22:25]
	v_mfma_f32_16x16x32_bf16 v[18:21], v[178:181], v[202:205], v[18:21]
	v_mfma_f32_16x16x32_bf16 v[4:7], v[170:173], v[210:213], v[4:7]
	v_mfma_f32_16x16x32_bf16 v[0:3], v[178:181], v[210:213], v[0:3]
	s_barrier
	s_add_i32 s39, s39, 2
	s_add_u32 s40, s40, 0x100
	s_addc_u32 s41, s41, 0
	s_add_u32 s12, s12, 0x100
	s_addc_u32 s13, s13, 0
	v_add_u32_e32 v222, 0x10000, v146
.LBB0_712:
	s_add_u32 s6, s40, 0xfff00080
	s_addc_u32 s7, s41, -1
	s_add_i32 s95, 0, 0x10000
	s_cmp_eq_u32 s39, 60
	s_cselect_b32 s43, s0, s7
	s_cselect_b32 s42, s1, s6
	s_cselect_b32 s17, s23, s13
	s_cselect_b32 s16, s25, s12
	s_add_i32 vcc_lo, 0, 0x14000
	ds_read_b128 v[150:153], v222
	ds_read_b128 v[154:157], v222 offset:1024
	ds_read_b128 v[158:161], v222 offset:2048
	ds_read_b128 v[162:165], v222 offset:3072
	ds_read_b128 v[166:169], v222 offset:16384
	ds_read_b128 v[170:173], v222 offset:17408
	ds_read_b128 v[174:177], v222 offset:18432
	ds_read_b128 v[178:181], v222 offset:19456
	s_add_i32 m0, s69, 0xc000
	ds_read_b128 v[182:185], v148
	ds_read_b128 v[186:189], v148 offset:1024
	ds_read_b128 v[190:193], v148 offset:2048
	ds_read_b128 v[194:197], v148 offset:3072
	ds_read_b128 v[198:201], v148 offset:4096
	ds_read_b128 v[202:205], v148 offset:5120
	ds_read_b128 v[206:209], v148 offset:6144
	global_load_lds_dwordx4 v140, s[40:41]
	s_add_i32 m0, s69, 0xe000
	ds_read_b128 v[210:213], v148 offset:7168
	global_load_lds_dwordx4 v142, s[40:41]
	s_waitcnt vmcnt(8) lgkmcnt(0)
	s_barrier
; #define PG8_STAGEA(bufoff, gbase, voff) PG8_STAGE_X(bufoff, gbase, voff, AUXA)
; #define PG8_STAGEB(bufoff, gbase, voff) PG8_STAGE_X(bufoff, gbase, voff, AUXB)
; #define PG8_LDA(dst, b, h) do { _Pragma("unroll") for (int m = 0; m < 4; ++m) _Pragma("unroll") for (int k = 0; k < 2; ++k) dst[m][k] = *(const PG8_LAS bf16x8*)(lds + PG8_SA(b, h) + aoff + m * 2048 + k * 1024); } while (0)
; #define PG8_LDB(dst, b, h) do { _Pragma("unroll") for (int n = 0; n < 2; ++n) _Pragma("unroll") for (int k = 0; k < 2; ++k) dst[n][k] = *(const PG8_LAS bf16x8*)(lds + PG8_SB(b, h) + boff + n * 2048 + k * 1024); } while (0)
; #define PG8_MMA(ai, bj, At, Bt) do { if (GEMM_PRIO_MODE == 0) __builtin_amdgcn_s_setprio(1); PG8_MMA_LOOPS \
;         acc[ai][bj][m][n] = __builtin_amdgcn_mfma_f32_16x16x32_bf16(Bt[n][k], At[m][k], acc[ai][bj][m][n], 0, 0, 0); if (GEMM_PRIO_MODE == 0) __builtin_amdgcn_s_setprio(0); } while (0)
; #define PG8_WAIT_V(n) asm volatile("s_waitcnt vmcnt(" #n ")" ::: "memory")
;     ...
;             PG8_LDB(B0, 0, 0); PG8_LDB(B1, 0, 1); PG8_SCHED; PG8_LDA(At, 0, 0); PG8_STAGEA(PG8_SA(1, 1), a1 + hstepA, voffA);
;     ...
;             const int relax = __builtin_amdgcn_readfirstlane((t == 0 && ui > 0) ? 1 : 0);
;             PG8_WAIT_VR(8, 24, relax); PG8_WAIT_L(0); PG8_BAR; PG8_MMA(0, 0, At, B0); PG8_MMA(0, 1, At, B1); PG8_BAR; PG8_SCHED;
;     ...
;             PG8_WAIT_V(8); PG8_WAIT_L(0); PG8_BAR; PG8_MMA(0, 0, At, B0); PG8_MMA(0, 1, At, B1); PG8_BAR; PG8_SCHED;
;     ...
;             PG8_LDA(At, 0, 1); PG8_STAGEB(PG8_SB(0, 0), b2, voffB); PG8_STAGEB(PG8_SB(0, 1), b2 + hstepB, voffB); PG8_STAGEA(PG8_SA(0, 0), a2, voffA);
;     ...
;             PG8_WAIT_VR(8, 24, relax); PG8_WAIT_L(0); PG8_BAR; PG8_MMA(1, 0, At, B0); PG8_MMA(1, 1, At, B1); PG8_BAR; PG8_SCHED;
;     ...
;             PG8_WAIT_V(8); PG8_WAIT_L(0); PG8_BAR; PG8_MMA(1, 0, At, B0); PG8_MMA(1, 1, At, B1); PG8_BAR; PG8_SCHED;
;     ...
;             PG8_LDB(B0, 1, 0); PG8_LDB(B1, 1, 1); PG8_SCHED; PG8_LDA(At, 1, 0); PG8_STAGEA(PG8_SA(0, 1), a2 + hstepA, voffA);
;             PG8_WAIT_V(8); PG8_WAIT_L(0); PG8_BAR; PG8_MMA(0, 0, At, B0); PG8_MMA(0, 1, At, B1); PG8_BAR; PG8_SCHED;
;             PG8_LDA(At, 1, 1); PG8_STAGEB(PG8_SB(1, 0), b3, voffB); PG8_STAGEB(PG8_SB(1, 1), b3 + hstepB, voffB); PG8_STAGEA(PG8_SA(1, 0), a3, voffA);
;             PG8_WAIT_V(8); PG8_WAIT_L(0); PG8_BAR; PG8_MMA(1, 0, At, B0); PG8_MMA(1, 1, At, B1); PG8_BAR; PG8_SCHED;
	v_mfma_f32_16x16x32_bf16 v[126:129], v[150:153], v[182:185], v[126:129]
	v_mfma_f32_16x16x32_bf16 v[122:125], v[158:161], v[182:185], v[122:125]
	v_mfma_f32_16x16x32_bf16 v[110:113], v[150:153], v[190:193], v[110:113]
	v_mfma_f32_16x16x32_bf16 v[106:109], v[158:161], v[190:193], v[106:109]
	v_mfma_f32_16x16x32_bf16 v[94:97], v[150:153], v[198:201], v[94:97]
	v_mfma_f32_16x16x32_bf16 v[90:93], v[158:161], v[198:201], v[90:93]
	v_mfma_f32_16x16x32_bf16 v[78:81], v[150:153], v[206:209], v[78:81]
	v_mfma_f32_16x16x32_bf16 v[74:77], v[158:161], v[206:209], v[74:77]
	v_mfma_f32_16x16x32_bf16 v[126:129], v[154:157], v[186:189], v[126:129]
	v_mfma_f32_16x16x32_bf16 v[122:125], v[162:165], v[186:189], v[122:125]
	v_mfma_f32_16x16x32_bf16 v[110:113], v[154:157], v[194:197], v[110:113]
	v_mfma_f32_16x16x32_bf16 v[106:109], v[162:165], v[194:197], v[106:109]
	v_mfma_f32_16x16x32_bf16 v[94:97], v[154:157], v[202:205], v[94:97]
	v_mfma_f32_16x16x32_bf16 v[90:93], v[162:165], v[202:205], v[90:93]
	v_mfma_f32_16x16x32_bf16 v[78:81], v[154:157], v[210:213], v[78:81]
	v_mfma_f32_16x16x32_bf16 v[74:77], v[162:165], v[210:213], v[74:77]
	v_mfma_f32_16x16x32_bf16 v[118:121], v[166:169], v[182:185], v[118:121]
	v_mfma_f32_16x16x32_bf16 v[114:117], v[174:177], v[182:185], v[114:117]
	v_mfma_f32_16x16x32_bf16 v[102:105], v[166:169], v[190:193], v[102:105]
	v_mfma_f32_16x16x32_bf16 v[98:101], v[174:177], v[190:193], v[98:101]
	v_mfma_f32_16x16x32_bf16 v[86:89], v[166:169], v[198:201], v[86:89]
	v_mfma_f32_16x16x32_bf16 v[82:85], v[174:177], v[198:201], v[82:85]
	v_mfma_f32_16x16x32_bf16 v[70:73], v[166:169], v[206:209], v[70:73]
	v_mfma_f32_16x16x32_bf16 v[66:69], v[174:177], v[206:209], v[66:69]
	v_mfma_f32_16x16x32_bf16 v[118:121], v[170:173], v[186:189], v[118:121]
	v_mfma_f32_16x16x32_bf16 v[114:117], v[178:181], v[186:189], v[114:117]
	v_mfma_f32_16x16x32_bf16 v[102:105], v[170:173], v[194:197], v[102:105]
	v_mfma_f32_16x16x32_bf16 v[98:101], v[178:181], v[194:197], v[98:101]
	v_mfma_f32_16x16x32_bf16 v[86:89], v[170:173], v[202:205], v[86:89]
	v_mfma_f32_16x16x32_bf16 v[82:85], v[178:181], v[202:205], v[82:85]
	v_mfma_f32_16x16x32_bf16 v[70:73], v[170:173], v[210:213], v[70:73]
	v_mfma_f32_16x16x32_bf16 v[66:69], v[178:181], v[210:213], v[66:69]
	s_barrier
	s_add_i32 s6, s95, s50
	s_mov_b32 m0, s6
	ds_read_b128 v[182:185], v148 offset:16384
	ds_read_b128 v[186:189], v148 offset:17408
	ds_read_b128 v[190:193], v148 offset:18432
	ds_read_b128 v[194:197], v148 offset:19456
	global_load_lds_dwordx4 v134, s[16:17]
	s_add_i32 m0, s6, 0x2000
	s_add_u32 s6, s16, 0x100000
	s_addc_u32 s7, s17, 0
	s_add_i32 s95, vcc_lo, s50
	global_load_lds_dwordx4 v130, s[16:17]
	s_mov_b32 m0, s95
	ds_read_b128 v[210:213], v148 offset:23552
	global_load_lds_dwordx4 v134, s[6:7]
	s_add_i32 m0, s95, 0x2000
	ds_read_b128 v[206:209], v148 offset:22528
	global_load_lds_dwordx4 v130, s[6:7]
	s_mov_b32 m0, s69
	ds_read_b128 v[202:205], v148 offset:21504
	global_load_lds_dwordx4 v136, s[42:43]
	s_mov_b32 m0, s72
	ds_read_b128 v[198:201], v148 offset:20480
	global_load_lds_dwordx4 v132, s[42:43]
	s_waitcnt vmcnt(8) lgkmcnt(0)
	s_barrier
	v_mfma_f32_16x16x32_bf16 v[62:65], v[150:153], v[182:185], v[62:65]
	v_mfma_f32_16x16x32_bf16 v[58:61], v[158:161], v[182:185], v[58:61]
	v_mfma_f32_16x16x32_bf16 v[46:49], v[150:153], v[190:193], v[46:49]
	v_mfma_f32_16x16x32_bf16 v[42:45], v[158:161], v[190:193], v[42:45]
	v_mfma_f32_16x16x32_bf16 v[30:33], v[150:153], v[198:201], v[30:33]
	v_mfma_f32_16x16x32_bf16 v[26:29], v[158:161], v[198:201], v[26:29]
	v_mfma_f32_16x16x32_bf16 v[12:15], v[150:153], v[206:209], v[12:15]
	v_mfma_f32_16x16x32_bf16 v[8:11], v[158:161], v[206:209], v[8:11]
	v_mfma_f32_16x16x32_bf16 v[62:65], v[154:157], v[186:189], v[62:65]
	v_mfma_f32_16x16x32_bf16 v[58:61], v[162:165], v[186:189], v[58:61]
	v_mfma_f32_16x16x32_bf16 v[46:49], v[154:157], v[194:197], v[46:49]
	v_mfma_f32_16x16x32_bf16 v[42:45], v[162:165], v[194:197], v[42:45]
	v_mfma_f32_16x16x32_bf16 v[30:33], v[154:157], v[202:205], v[30:33]
	v_mfma_f32_16x16x32_bf16 v[26:29], v[162:165], v[202:205], v[26:29]
	v_mfma_f32_16x16x32_bf16 v[12:15], v[154:157], v[210:213], v[12:15]
	v_mfma_f32_16x16x32_bf16 v[8:11], v[162:165], v[210:213], v[8:11]
	v_mfma_f32_16x16x32_bf16 v[54:57], v[166:169], v[182:185], v[54:57]
	v_mfma_f32_16x16x32_bf16 v[50:53], v[174:177], v[182:185], v[50:53]
	v_mfma_f32_16x16x32_bf16 v[38:41], v[166:169], v[190:193], v[38:41]
	v_mfma_f32_16x16x32_bf16 v[34:37], v[174:177], v[190:193], v[34:37]
	v_mfma_f32_16x16x32_bf16 v[22:25], v[166:169], v[198:201], v[22:25]
	v_mfma_f32_16x16x32_bf16 v[18:21], v[174:177], v[198:201], v[18:21]
	v_mfma_f32_16x16x32_bf16 v[4:7], v[166:169], v[206:209], v[4:7]
	v_mfma_f32_16x16x32_bf16 v[0:3], v[174:177], v[206:209], v[0:3]
	v_mfma_f32_16x16x32_bf16 v[54:57], v[170:173], v[186:189], v[54:57]
	v_mfma_f32_16x16x32_bf16 v[50:53], v[178:181], v[186:189], v[50:53]
	v_mfma_f32_16x16x32_bf16 v[38:41], v[170:173], v[194:197], v[38:41]
	v_mfma_f32_16x16x32_bf16 v[34:37], v[178:181], v[194:197], v[34:37]
	v_mfma_f32_16x16x32_bf16 v[22:25], v[170:173], v[202:205], v[22:25]
	v_mfma_f32_16x16x32_bf16 v[18:21], v[178:181], v[202:205], v[18:21]
	v_mfma_f32_16x16x32_bf16 v[4:7], v[170:173], v[210:213], v[4:7]
	v_mfma_f32_16x16x32_bf16 v[0:3], v[178:181], v[210:213], v[0:3]
	s_barrier
; #define PG8_STAGEA(bufoff, gbase, voff) PG8_STAGE_X(bufoff, gbase, voff, AUXA)
; #define PG8_STAGEB(bufoff, gbase, voff) PG8_STAGE_X(bufoff, gbase, voff, AUXB)
; #define PG8_LDA(dst, b, h) do { _Pragma("unroll") for (int m = 0; m < 4; ++m) _Pragma("unroll") for (int k = 0; k < 2; ++k) dst[m][k] = *(const PG8_LAS bf16x8*)(lds + PG8_SA(b, h) + aoff + m * 2048 + k * 1024); } while (0)
; #define PG8_LDB(dst, b, h) do { _Pragma("unroll") for (int n = 0; n < 2; ++n) _Pragma("unroll") for (int k = 0; k < 2; ++k) dst[n][k] = *(const PG8_LAS bf16x8*)(lds + PG8_SB(b, h) + boff + n * 2048 + k * 1024); } while (0)
; #define PG8_MMA(ai, bj, At, Bt) do { if (GEMM_PRIO_MODE == 0) __builtin_amdgcn_s_setprio(1); PG8_MMA_LOOPS \
;         acc[ai][bj][m][n] = __builtin_amdgcn_mfma_f32_16x16x32_bf16(Bt[n][k], At[m][k], acc[ai][bj][m][n], 0, 0, 0); if (GEMM_PRIO_MODE == 0) __builtin_amdgcn_s_setprio(0); } while (0)
; #define PG8_WAIT_V(n) asm volatile("s_waitcnt vmcnt(" #n ")" ::: "memory")
;     ...
;             PG8_LDB(B0, 0, 0); PG8_LDB(B1, 0, 1); PG8_SCHED; PG8_LDA(At, 0, 0); PG8_STAGEA(PG8_SA(1, 1), a1 + hstepA, voffA);
;     ...
;             const int relax = __builtin_amdgcn_readfirstlane((t == 0 && ui > 0) ? 1 : 0);
;             PG8_WAIT_VR(8, 24, relax); PG8_WAIT_L(0); PG8_BAR; PG8_MMA(0, 0, At, B0); PG8_MMA(0, 1, At, B1); PG8_BAR; PG8_SCHED;
;     ...
;             PG8_WAIT_V(8); PG8_WAIT_L(0); PG8_BAR; PG8_MMA(0, 0, At, B0); PG8_MMA(0, 1, At, B1); PG8_BAR; PG8_SCHED;
;     ...
;             PG8_LDA(At, 0, 1); PG8_STAGEB(PG8_SB(0, 0), b2, voffB); PG8_STAGEB(PG8_SB(0, 1), b2 + hstepB, voffB); PG8_STAGEA(PG8_SA(0, 0), a2, voffA);
;     ...
;             PG8_WAIT_VR(8, 24, relax); PG8_WAIT_L(0); PG8_BAR; PG8_MMA(1, 0, At, B0); PG8_MMA(1, 1, At, B1); PG8_BAR; PG8_SCHED;
;     ...
;             PG8_WAIT_V(8); PG8_WAIT_L(0); PG8_BAR; PG8_MMA(1, 0, At, B0); PG8_MMA(1, 1, At, B1); PG8_BAR; PG8_SCHED;
;     ...
;             PG8_LDB(B0, 1, 0); PG8_LDB(B1, 1, 1); PG8_SCHED; PG8_LDA(At, 1, 0); PG8_STAGEA(PG8_SA(0, 1), a2 + hstepA, voffA);
;             PG8_WAIT_V(8); PG8_WAIT_L(0); PG8_BAR; PG8_MMA(0, 0, At, B0); PG8_MMA(0, 1, At, B1); PG8_BAR; PG8_SCHED;
;             PG8_LDA(At, 1, 1); PG8_STAGEB(PG8_SB(1, 0), b3, voffB); PG8_STAGEB(PG8_SB(1, 1), b3 + hstepB, voffB); PG8_STAGEA(PG8_SA(1, 0), a3, voffA);
;             PG8_WAIT_V(8); PG8_WAIT_L(0); PG8_BAR; PG8_MMA(1, 0, At, B0); PG8_MMA(1, 1, At, B1); PG8_BAR; PG8_SCHED;
	s_add_i32 s95, 0, 0x18000
	s_add_i32 vcc_lo, 0, 0x1c000
	ds_read_b128 v[150:153], v222 offset:32768
	ds_read_b128 v[154:157], v222 offset:33792
	ds_read_b128 v[158:161], v222 offset:34816
	ds_read_b128 v[162:165], v222 offset:35840
	ds_read_b128 v[166:169], v222 offset:49152
	ds_read_b128 v[170:173], v222 offset:50176
	ds_read_b128 v[174:177], v222 offset:51200
	ds_read_b128 v[178:181], v222 offset:52224
	s_add_u32 s6, s42, 0x100000
	s_addc_u32 s7, s43, 0
	s_mov_b32 m0, s73
	ds_read_b128 v[182:185], v148 offset:32768
	ds_read_b128 v[186:189], v148 offset:33792
	ds_read_b128 v[190:193], v148 offset:34816
	ds_read_b128 v[194:197], v148 offset:35840
	ds_read_b128 v[198:201], v148 offset:36864
	ds_read_b128 v[202:205], v148 offset:37888
	ds_read_b128 v[206:209], v148 offset:38912
	global_load_lds_dwordx4 v136, s[6:7]
	s_mov_b32 m0, s82
	ds_read_b128 v[210:213], v148 offset:39936
	global_load_lds_dwordx4 v132, s[6:7]
	s_waitcnt vmcnt(8) lgkmcnt(0)
	s_barrier
	v_mfma_f32_16x16x32_bf16 v[126:129], v[150:153], v[182:185], v[126:129]
	v_mfma_f32_16x16x32_bf16 v[122:125], v[158:161], v[182:185], v[122:125]
	v_mfma_f32_16x16x32_bf16 v[110:113], v[150:153], v[190:193], v[110:113]
	v_mfma_f32_16x16x32_bf16 v[106:109], v[158:161], v[190:193], v[106:109]
	v_mfma_f32_16x16x32_bf16 v[94:97], v[150:153], v[198:201], v[94:97]
	v_mfma_f32_16x16x32_bf16 v[90:93], v[158:161], v[198:201], v[90:93]
	v_mfma_f32_16x16x32_bf16 v[78:81], v[150:153], v[206:209], v[78:81]
	v_mfma_f32_16x16x32_bf16 v[74:77], v[158:161], v[206:209], v[74:77]
	v_mfma_f32_16x16x32_bf16 v[126:129], v[154:157], v[186:189], v[126:129]
	v_mfma_f32_16x16x32_bf16 v[122:125], v[162:165], v[186:189], v[122:125]
	v_mfma_f32_16x16x32_bf16 v[110:113], v[154:157], v[194:197], v[110:113]
	v_mfma_f32_16x16x32_bf16 v[106:109], v[162:165], v[194:197], v[106:109]
	v_mfma_f32_16x16x32_bf16 v[94:97], v[154:157], v[202:205], v[94:97]
	v_mfma_f32_16x16x32_bf16 v[90:93], v[162:165], v[202:205], v[90:93]
	v_mfma_f32_16x16x32_bf16 v[78:81], v[154:157], v[210:213], v[78:81]
	v_mfma_f32_16x16x32_bf16 v[74:77], v[162:165], v[210:213], v[74:77]
	v_mfma_f32_16x16x32_bf16 v[118:121], v[166:169], v[182:185], v[118:121]
	v_mfma_f32_16x16x32_bf16 v[114:117], v[174:177], v[182:185], v[114:117]
	v_mfma_f32_16x16x32_bf16 v[102:105], v[166:169], v[190:193], v[102:105]
	v_mfma_f32_16x16x32_bf16 v[98:101], v[174:177], v[190:193], v[98:101]
	v_mfma_f32_16x16x32_bf16 v[86:89], v[166:169], v[198:201], v[86:89]
	v_mfma_f32_16x16x32_bf16 v[82:85], v[174:177], v[198:201], v[82:85]
	v_mfma_f32_16x16x32_bf16 v[70:73], v[166:169], v[206:209], v[70:73]
	v_mfma_f32_16x16x32_bf16 v[66:69], v[174:177], v[206:209], v[66:69]
	v_mfma_f32_16x16x32_bf16 v[118:121], v[170:173], v[186:189], v[118:121]
	v_mfma_f32_16x16x32_bf16 v[114:117], v[178:181], v[186:189], v[114:117]
	v_mfma_f32_16x16x32_bf16 v[102:105], v[170:173], v[194:197], v[102:105]
	v_mfma_f32_16x16x32_bf16 v[98:101], v[178:181], v[194:197], v[98:101]
	v_mfma_f32_16x16x32_bf16 v[86:89], v[170:173], v[202:205], v[86:89]
	v_mfma_f32_16x16x32_bf16 v[82:85], v[178:181], v[202:205], v[82:85]
	v_mfma_f32_16x16x32_bf16 v[70:73], v[170:173], v[210:213], v[70:73]
	v_mfma_f32_16x16x32_bf16 v[66:69], v[178:181], v[210:213], v[66:69]
	s_barrier
	s_add_i32 s6, s95, s50
	s_mov_b32 m0, s6
	ds_read_b128 v[182:185], v148 offset:49152
	ds_read_b128 v[186:189], v148 offset:50176
	ds_read_b128 v[190:193], v148 offset:51200
	ds_read_b128 v[194:197], v148 offset:52224
	ds_read_b128 v[198:201], v148 offset:53248
	s_add_u32 s100, s16, 0x80
	s_addc_u32 s101, s17, 0
	global_load_lds_dwordx4 v134, s[100:101]
	s_add_i32 m0, s6, 0x2000
	s_add_u32 s6, s16, 0x100080
	s_addc_u32 s7, s17, 0
	s_add_i32 s16, vcc_lo, s50
	global_load_lds_dwordx4 v130, s[100:101]
	s_mov_b32 m0, s16
	ds_read_b128 v[210:213], v148 offset:56320
	global_load_lds_dwordx4 v134, s[6:7]
	s_add_i32 m0, s16, 0x2000
	ds_read_b128 v[206:209], v148 offset:55296
	global_load_lds_dwordx4 v130, s[6:7]
	s_mov_b32 m0, s83
	s_nop 0
	s_add_u32 s100, s42, 0x80
	s_addc_u32 s101, s43, 0
	global_load_lds_dwordx4 v136, s[100:101]
	s_mov_b32 m0, s90
	ds_read_b128 v[202:205], v148 offset:54272
	global_load_lds_dwordx4 v132, s[100:101]
	s_waitcnt vmcnt(8) lgkmcnt(0)
	s_nop 0
	s_barrier
	v_mfma_f32_16x16x32_bf16 v[62:65], v[150:153], v[182:185], v[62:65]
	v_mfma_f32_16x16x32_bf16 v[58:61], v[158:161], v[182:185], v[58:61]
	v_mfma_f32_16x16x32_bf16 v[46:49], v[150:153], v[190:193], v[46:49]
	v_mfma_f32_16x16x32_bf16 v[42:45], v[158:161], v[190:193], v[42:45]
	v_mfma_f32_16x16x32_bf16 v[30:33], v[150:153], v[198:201], v[30:33]
	v_mfma_f32_16x16x32_bf16 v[26:29], v[158:161], v[198:201], v[26:29]
	v_mfma_f32_16x16x32_bf16 v[12:15], v[150:153], v[206:209], v[12:15]
	v_mfma_f32_16x16x32_bf16 v[8:11], v[158:161], v[206:209], v[8:11]
	v_mfma_f32_16x16x32_bf16 v[62:65], v[154:157], v[186:189], v[62:65]
	v_mfma_f32_16x16x32_bf16 v[58:61], v[162:165], v[186:189], v[58:61]
	v_mfma_f32_16x16x32_bf16 v[46:49], v[154:157], v[194:197], v[46:49]
	v_mfma_f32_16x16x32_bf16 v[42:45], v[162:165], v[194:197], v[42:45]
	v_mfma_f32_16x16x32_bf16 v[30:33], v[154:157], v[202:205], v[30:33]
	v_mfma_f32_16x16x32_bf16 v[26:29], v[162:165], v[202:205], v[26:29]
	v_mfma_f32_16x16x32_bf16 v[12:15], v[154:157], v[210:213], v[12:15]
	v_mfma_f32_16x16x32_bf16 v[8:11], v[162:165], v[210:213], v[8:11]
	v_mfma_f32_16x16x32_bf16 v[54:57], v[166:169], v[182:185], v[54:57]
	v_mfma_f32_16x16x32_bf16 v[50:53], v[174:177], v[182:185], v[50:53]
	v_mfma_f32_16x16x32_bf16 v[38:41], v[166:169], v[190:193], v[38:41]
	v_mfma_f32_16x16x32_bf16 v[34:37], v[174:177], v[190:193], v[34:37]
	v_mfma_f32_16x16x32_bf16 v[22:25], v[166:169], v[198:201], v[22:25]
	v_mfma_f32_16x16x32_bf16 v[18:21], v[174:177], v[198:201], v[18:21]
	v_mfma_f32_16x16x32_bf16 v[4:7], v[166:169], v[206:209], v[4:7]
	v_mfma_f32_16x16x32_bf16 v[0:3], v[174:177], v[206:209], v[0:3]
	v_mfma_f32_16x16x32_bf16 v[54:57], v[170:173], v[186:189], v[54:57]
	v_mfma_f32_16x16x32_bf16 v[50:53], v[178:181], v[186:189], v[50:53]
	v_mfma_f32_16x16x32_bf16 v[38:41], v[170:173], v[194:197], v[38:41]
	v_mfma_f32_16x16x32_bf16 v[34:37], v[178:181], v[194:197], v[34:37]
	v_mfma_f32_16x16x32_bf16 v[22:25], v[170:173], v[202:205], v[22:25]
	v_mfma_f32_16x16x32_bf16 v[18:21], v[178:181], v[202:205], v[18:21]
	v_mfma_f32_16x16x32_bf16 v[4:7], v[170:173], v[210:213], v[4:7]
	v_mfma_f32_16x16x32_bf16 v[0:3], v[178:181], v[210:213], v[0:3]
	s_barrier
	s_add_i32 s39, s39, 2
	s_add_u32 s40, s40, 0x100
	s_addc_u32 s41, s41, 0
	s_add_u32 s12, s12, 0x100
	s_addc_u32 s13, s13, 0
	s_cmp_gt_u32 s39, 61
	s_cbranch_scc0 .LBB0_712
	s_and_b64 vcc, exec, s[18:19]
	s_cbranch_vccz .LBB0_715
	s_barrier

; #define PG8_STAGEA(bufoff, gbase, voff) PG8_STAGE_X(bufoff, gbase, voff, AUXA)
; #define PG8_STR(x) PG8_STR2(x)
;     ...
;         const bool has_next = S.next(ui + 1, nxt);
;         const char* nA = has_next ? (const char*)g.A + (size_t)nxt.pm * tstepA : cA; const char* nB = has_next ? (const char*)g.Bt + (size_t)nxt.pn * tstepB : cB;
;         int t0 = 0;
;         if constexpr (SP2 && GEMM_RELAX == 1) { if (ui > 0) {
;             const char* a1 = cA + kstepA; const char* a2 = cA + 2 * kstepA; const char* b2 = cB + 2 * kstepB; const char* a3 = a2 + kstepA; const char* b3 = b2 + kstepB;
;             PG8_LDB(B0, 0, 0); PG8_LDB(B1, 0, 1); PG8_SCHED; PG8_LDA(At, 0, 0); PG8_STAGEA(PG8_SA(1, 1), a1 + hstepA, voffA);
;             PG8_WAIT_V(24); PG8_WAIT_L(0); PG8_BAR; PG8_MMA(0, 0, At, B0); PG8_MMA(0, 1, At, B1); PG8_BAR; PG8_SCHED;
;             PG8_LDA(At, 0, 1); PG8_STAGEB(PG8_SB(0, 0), b2, voffB); PG8_STAGEB(PG8_SB(0, 1), b2 + hstepB, voffB); PG8_STAGEA(PG8_SA(0, 0), a2, voffA);
;             PG8_WAIT_V(24); PG8_WAIT_L(0); PG8_BAR; PG8_MMA(1, 0, At, B0); PG8_MMA(1, 1, At, B1); PG8_BAR; PG8_SCHED;
;             PG8_LDB(B0, 1, 0); PG8_LDB(B1, 1, 1); PG8_SCHED; PG8_LDA(At, 1, 0); PG8_STAGEA(PG8_SA(0, 1), a2 + hstepA, voffA);
;             PG8_WAIT_V(8); PG8_WAIT_L(0); PG8_BAR; PG8_MMA(0, 0, At, B0); PG8_MMA(0, 1, At, B1); PG8_BAR; PG8_SCHED;
;             PG8_LDA(At, 1, 1); PG8_STAGEB(PG8_SB(1, 0), b3, voffB); PG8_STAGEB(PG8_SB(1, 1), b3 + hstepB, voffB); PG8_STAGEA(PG8_SA(1, 0), a3, voffA);
;             PG8_WAIT_V(8); PG8_WAIT_L(0); PG8_BAR; PG8_MMA(1, 0, At, B0); PG8_MMA(1, 1, At, B1); PG8_BAR; PG8_SCHED;
;             t0 = 2; } }
;     ...
;         asm volatile(".p2align " PG8_STR(GEMM_LOOP_ALIGN) ::: "memory");
;     ...
;         for (int t = t0; t < nt; t += 2) {
;             const bool last = (t == nt - 2);
;             const char* a1 = cA + (size_t)(t + 1) * kstepA;
;             const char* a2 = last ? nA : cA + (size_t)(t + 2) * kstepA; const char* b2 = last ? nB : cB + (size_t)(t + 2) * kstepB;
;             const char* a3 = a2 + kstepA; const char* b3 = b2 + kstepB;
;             if (last && has_next) S.a_ready(nxt);
;             if constexpr (SP2) {
;             PG8_LDB(B0, 0, 0); PG8_LDB(B1, 0, 1); PG8_SCHED; PG8_LDA(At, 0, 0); PG8_STAGEA(PG8_SA(1, 1), a1 + hstepA, voffA);
;     ...
;             const int relax = __builtin_amdgcn_readfirstlane((t == 0 && ui > 0) ? 1 : 0);
.LBB0_847:
	s_ashr_i32 s11, s10, 31
	s_lshl_b64 s[18:19], s[10:11], 23
	s_add_u32 s18, s62, s18
	s_addc_u32 s19, s63, s19
	s_and_b64 s[22:23], s[20:21], exec
	s_cselect_b32 s11, s19, s1
	s_cselect_b32 s73, s18, s0
	s_ashr_i32 s15, s14, 31
	s_lshl_b64 s[22:23], s[14:15], 23
	s_add_u32 s22, s12, s22
	s_addc_u32 s23, s13, s23
	s_and_b64 s[24:25], s[20:21], exec
	s_cselect_b32 s15, s23, s17
	s_cselect_b32 s78, s22, s16
	s_add_u32 s24, s0, 0xc000
	s_addc_u32 s25, s1, 0
	s_add_u32 s0, s16, 0x10000
	s_addc_u32 s1, s17, 0
	s_mov_b32 s82, -2
	s_waitcnt lgkmcnt(0)
	s_add_u32 s16, s24, 0x4000
	s_addc_u32 s17, s25, 0
	s_cmpk_eq_i32 s82, 0xfc
	s_cselect_b32 s36, s73, s16
	s_cselect_b32 s37, s11, s17
	s_cselect_b32 s16, s78, s0
	s_cselect_b32 s17, s15, s1
	s_add_u32 s26, s36, 0x8000
	s_addc_u32 s27, s37, 0
	s_add_i32 s83, 0, 0x10000
	s_add_i32 s94, 0, 0x14000
	v_add_u32_e32 v152, s83, v157
	v_add_u32_e32 v174, s94, v157
	ds_read_b128 v[130:133], v152
	ds_read_b128 v[134:137], v152 offset:1024
	ds_read_b128 v[148:151], v152 offset:2048
	ds_read_b128 v[152:155], v152 offset:3072
	ds_read_b128 v[162:165], v174
	ds_read_b128 v[166:169], v174 offset:1024
	ds_read_b128 v[170:173], v174 offset:2048
	ds_read_b128 v[174:177], v174 offset:3072
	v_lshl_add_u64 v[210:211], s[24:25], 0, v[144:145]
	s_add_i32 m0, s39, 0xc000
	ds_read_b128 v[178:181], v161
	ds_read_b128 v[182:185], v161 offset:1024
	ds_read_b128 v[186:189], v161 offset:2048
	ds_read_b128 v[190:193], v161 offset:3072
	ds_read_b128 v[194:197], v161 offset:4096
	ds_read_b128 v[198:201], v161 offset:5120
	ds_read_b128 v[202:205], v161 offset:6144
	ds_read_b128 v[206:209], v161 offset:7168
	global_load_lds_dwordx4 v[210:211], off
	v_lshl_add_u64 v[210:211], s[24:25], 0, v[146:147]
	s_add_i32 m0, s39, 0xe000
	s_nop 0
	global_load_lds_dwordx4 v[210:211], off
	s_waitcnt vmcnt(8) lgkmcnt(0)
	s_nop 0
	s_barrier
	v_mfma_f32_16x16x32_bf16 v[126:129], v[130:133], v[178:181], 0
	v_mfma_f32_16x16x32_bf16 v[122:125], v[148:151], v[178:181], 0
	v_mfma_f32_16x16x32_bf16 v[110:113], v[130:133], v[186:189], 0
	v_mfma_f32_16x16x32_bf16 v[106:109], v[148:151], v[186:189], 0
	v_mfma_f32_16x16x32_bf16 v[94:97], v[130:133], v[194:197], 0
	v_mfma_f32_16x16x32_bf16 v[90:93], v[148:151], v[194:197], 0
	v_mfma_f32_16x16x32_bf16 v[78:81], v[130:133], v[202:205], 0
	v_mfma_f32_16x16x32_bf16 v[74:77], v[148:151], v[202:205], 0
	v_mfma_f32_16x16x32_bf16 v[126:129], v[134:137], v[182:185], v[126:129]
	v_mfma_f32_16x16x32_bf16 v[122:125], v[152:155], v[182:185], v[122:125]
	v_mfma_f32_16x16x32_bf16 v[110:113], v[134:137], v[190:193], v[110:113]
	v_mfma_f32_16x16x32_bf16 v[106:109], v[152:155], v[190:193], v[106:109]
	v_mfma_f32_16x16x32_bf16 v[94:97], v[134:137], v[198:201], v[94:97]
	v_mfma_f32_16x16x32_bf16 v[90:93], v[152:155], v[198:201], v[90:93]
	v_mfma_f32_16x16x32_bf16 v[78:81], v[134:137], v[206:209], v[78:81]
	v_mfma_f32_16x16x32_bf16 v[74:77], v[152:155], v[206:209], v[74:77]
	v_mfma_f32_16x16x32_bf16 v[118:121], v[162:165], v[178:181], 0
	v_mfma_f32_16x16x32_bf16 v[114:117], v[170:173], v[178:181], 0
	v_mfma_f32_16x16x32_bf16 v[102:105], v[162:165], v[186:189], 0
	v_mfma_f32_16x16x32_bf16 v[98:101], v[170:173], v[186:189], 0
	v_mfma_f32_16x16x32_bf16 v[86:89], v[162:165], v[194:197], 0
	v_mfma_f32_16x16x32_bf16 v[82:85], v[170:173], v[194:197], 0
	v_mfma_f32_16x16x32_bf16 v[70:73], v[162:165], v[202:205], 0
	v_mfma_f32_16x16x32_bf16 v[66:69], v[170:173], v[202:205], 0
	v_mfma_f32_16x16x32_bf16 v[118:121], v[166:169], v[182:185], v[118:121]
	v_mfma_f32_16x16x32_bf16 v[114:117], v[174:177], v[182:185], v[114:117]
	v_mfma_f32_16x16x32_bf16 v[102:105], v[166:169], v[190:193], v[102:105]
	v_mfma_f32_16x16x32_bf16 v[98:101], v[174:177], v[190:193], v[98:101]
	v_mfma_f32_16x16x32_bf16 v[86:89], v[166:169], v[198:201], v[86:89]
	v_mfma_f32_16x16x32_bf16 v[82:85], v[174:177], v[198:201], v[82:85]
	v_mfma_f32_16x16x32_bf16 v[70:73], v[166:169], v[206:209], v[70:73]
	v_mfma_f32_16x16x32_bf16 v[66:69], v[174:177], v[206:209], v[66:69]
	s_barrier
	s_add_i32 s83, s83, s38
	v_lshl_add_u64 v[210:211], s[16:17], 0, v[16:17]
	s_mov_b32 m0, s83
	ds_read_b128 v[178:181], v161 offset:16384
	ds_read_b128 v[182:185], v161 offset:17408
	ds_read_b128 v[186:189], v161 offset:18432
	ds_read_b128 v[190:193], v161 offset:19456
	ds_read_b128 v[194:197], v161 offset:20480
	ds_read_b128 v[198:201], v161 offset:21504
	ds_read_b128 v[202:205], v161 offset:22528
	ds_read_b128 v[206:209], v161 offset:23552
	global_load_lds_dwordx4 v[210:211], off
	s_add_i32 m0, s83, 0x2000
	s_add_u32 s90, s16, 0x4000
	v_lshl_add_u64 v[210:211], s[16:17], 0, v[138:139]
	s_addc_u32 s91, s17, 0
	s_add_i32 s83, s94, s38
	global_load_lds_dwordx4 v[210:211], off
	v_lshl_add_u64 v[210:211], s[90:91], 0, v[16:17]
	s_mov_b32 m0, s83
	s_nop 0
	global_load_lds_dwordx4 v[210:211], off
	v_lshl_add_u64 v[210:211], s[90:91], 0, v[138:139]
	s_add_i32 m0, s83, 0x2000
	s_nop 0
	global_load_lds_dwordx4 v[210:211], off
	v_lshl_add_u64 v[210:211], s[36:37], 0, v[142:143]
	s_mov_b32 m0, s39
	s_nop 0
	global_load_lds_dwordx4 v[210:211], off
	v_lshl_add_u64 v[210:211], s[36:37], 0, v[140:141]
	s_mov_b32 m0, s40
	s_nop 0
	global_load_lds_dwordx4 v[210:211], off
	s_waitcnt vmcnt(8) lgkmcnt(0)
	s_barrier
; #define PG8_STAGEA(bufoff, gbase, voff) PG8_STAGE_X(bufoff, gbase, voff, AUXA)
; #define PG8_STAGEB(bufoff, gbase, voff) PG8_STAGE_X(bufoff, gbase, voff, AUXB)
; #define PG8_LDA(dst, b, h) do { _Pragma("unroll") for (int m = 0; m < 4; ++m) _Pragma("unroll") for (int k = 0; k < 2; ++k) dst[m][k] = *(const PG8_LAS bf16x8*)(lds + PG8_SA(b, h) + aoff + m * 2048 + k * 1024); } while (0)
; #define PG8_LDB(dst, b, h) do { _Pragma("unroll") for (int n = 0; n < 2; ++n) _Pragma("unroll") for (int k = 0; k < 2; ++k) dst[n][k] = *(const PG8_LAS bf16x8*)(lds + PG8_SB(b, h) + boff + n * 2048 + k * 1024); } while (0)
; #define PG8_MMA(ai, bj, At, Bt) do { if (GEMM_PRIO_MODE == 0) __builtin_amdgcn_s_setprio(1); PG8_MMA_LOOPS \
;         acc[ai][bj][m][n] = __builtin_amdgcn_mfma_f32_16x16x32_bf16(Bt[n][k], At[m][k], acc[ai][bj][m][n], 0, 0, 0); if (GEMM_PRIO_MODE == 0) __builtin_amdgcn_s_setprio(0); } while (0)
; #define PG8_WAIT_V(n) asm volatile("s_waitcnt vmcnt(" #n ")" ::: "memory")
; #define PG8_WAIT_VR(n, nr, flag) asm volatile("s_cmp_eq_u32 %0, 0\n\ts_cbranch_scc1 .Lpg8s%=\n\ts_waitcnt vmcnt(" #nr ")\n\ts_branch .Lpg8d%=\n.Lpg8s%=:\n\ts_waitcnt vmcnt(" #n ")\n.Lpg8d%=:" :: "s"(flag) : "memory", "scc")
; #define PG8_WAIT_L(n) asm volatile("s_waitcnt lgkmcnt(" #n ")" ::: "memory")
; #define PG8_BAR __builtin_amdgcn_s_barrier()
; #define PG8_SCHED __builtin_amdgcn_sched_barrier(0)
;     ...
;             PG8_LDA(At, 0, 1); PG8_STAGEB(PG8_SB(0, 0), b2, voffB); PG8_STAGEB(PG8_SB(0, 1), b2 + hstepB, voffB); PG8_STAGEA(PG8_SA(0, 0), a2, voffA);
;     ...
;             PG8_WAIT_VR(8, 24, relax); PG8_WAIT_L(0); PG8_BAR; PG8_MMA(1, 0, At, B0); PG8_MMA(1, 1, At, B1); PG8_BAR; PG8_SCHED;
;     ...
;             PG8_WAIT_V(8); PG8_WAIT_L(0); PG8_BAR; PG8_MMA(1, 0, At, B0); PG8_MMA(1, 1, At, B1); PG8_BAR; PG8_SCHED;
;     ...
;             PG8_LDB(B0, 1, 0); PG8_LDB(B1, 1, 1); PG8_SCHED; PG8_LDA(At, 1, 0); PG8_STAGEA(PG8_SA(0, 1), a2 + hstepA, voffA);
;             PG8_WAIT_V(8); PG8_WAIT_L(0); PG8_BAR; PG8_MMA(0, 0, At, B0); PG8_MMA(0, 1, At, B1); PG8_BAR; PG8_SCHED;
;             PG8_LDA(At, 1, 1); PG8_STAGEB(PG8_SB(1, 0), b3, voffB); PG8_STAGEB(PG8_SB(1, 1), b3 + hstepB, voffB); PG8_STAGEA(PG8_SA(1, 0), a3, voffA);
;             PG8_WAIT_V(8); PG8_WAIT_L(0); PG8_BAR; PG8_MMA(1, 0, At, B0); PG8_MMA(1, 1, At, B1); PG8_BAR; PG8_SCHED;
	v_mfma_f32_16x16x32_bf16 v[62:65], v[130:133], v[178:181], 0
	v_mfma_f32_16x16x32_bf16 v[58:61], v[148:151], v[178:181], 0
	v_mfma_f32_16x16x32_bf16 v[46:49], v[130:133], v[186:189], 0
	v_mfma_f32_16x16x32_bf16 v[42:45], v[148:151], v[186:189], 0
	v_mfma_f32_16x16x32_bf16 v[30:33], v[130:133], v[194:197], 0
	v_mfma_f32_16x16x32_bf16 v[26:29], v[148:151], v[194:197], 0
	v_mfma_f32_16x16x32_bf16 v[12:15], v[130:133], v[202:205], 0
	v_mfma_f32_16x16x32_bf16 v[8:11], v[148:151], v[202:205], 0
	v_mfma_f32_16x16x32_bf16 v[62:65], v[134:137], v[182:185], v[62:65]
	v_mfma_f32_16x16x32_bf16 v[58:61], v[152:155], v[182:185], v[58:61]
	v_mfma_f32_16x16x32_bf16 v[46:49], v[134:137], v[190:193], v[46:49]
	v_mfma_f32_16x16x32_bf16 v[42:45], v[152:155], v[190:193], v[42:45]
	v_mfma_f32_16x16x32_bf16 v[30:33], v[134:137], v[198:201], v[30:33]
	v_mfma_f32_16x16x32_bf16 v[26:29], v[152:155], v[198:201], v[26:29]
	v_mfma_f32_16x16x32_bf16 v[12:15], v[134:137], v[206:209], v[12:15]
	v_mfma_f32_16x16x32_bf16 v[8:11], v[152:155], v[206:209], v[8:11]
	v_mfma_f32_16x16x32_bf16 v[54:57], v[162:165], v[178:181], 0
	v_mfma_f32_16x16x32_bf16 v[50:53], v[170:173], v[178:181], 0
	v_mfma_f32_16x16x32_bf16 v[38:41], v[162:165], v[186:189], 0
	v_mfma_f32_16x16x32_bf16 v[34:37], v[170:173], v[186:189], 0
	v_mfma_f32_16x16x32_bf16 v[22:25], v[162:165], v[194:197], 0
	v_mfma_f32_16x16x32_bf16 v[18:21], v[170:173], v[194:197], 0
	v_mfma_f32_16x16x32_bf16 v[4:7], v[162:165], v[202:205], 0
	v_mfma_f32_16x16x32_bf16 v[0:3], v[170:173], v[202:205], 0
	v_mfma_f32_16x16x32_bf16 v[54:57], v[166:169], v[182:185], v[54:57]
	v_mfma_f32_16x16x32_bf16 v[50:53], v[174:177], v[182:185], v[50:53]
	v_mfma_f32_16x16x32_bf16 v[38:41], v[166:169], v[190:193], v[38:41]
	v_mfma_f32_16x16x32_bf16 v[34:37], v[174:177], v[190:193], v[34:37]
	v_mfma_f32_16x16x32_bf16 v[22:25], v[166:169], v[198:201], v[22:25]
	v_mfma_f32_16x16x32_bf16 v[18:21], v[174:177], v[198:201], v[18:21]
	v_mfma_f32_16x16x32_bf16 v[4:7], v[166:169], v[206:209], v[4:7]
	v_mfma_f32_16x16x32_bf16 v[0:3], v[174:177], v[206:209], v[0:3]
	s_barrier
	s_add_i32 s83, 0, 0x18000
	s_add_i32 s90, 0, 0x1c000
	v_add_u32_e32 v152, s83, v157
	v_add_u32_e32 v174, s90, v157
	ds_read_b128 v[130:133], v152
	ds_read_b128 v[134:137], v152 offset:1024
	ds_read_b128 v[148:151], v152 offset:2048
	ds_read_b128 v[152:155], v152 offset:3072
	ds_read_b128 v[162:165], v174
	ds_read_b128 v[166:169], v174 offset:1024
	ds_read_b128 v[170:173], v174 offset:2048
	ds_read_b128 v[174:177], v174 offset:3072
	s_add_u32 s36, s36, 0x4000
	s_addc_u32 s37, s37, 0
	s_mov_b32 m0, s41
	v_lshl_add_u64 v[210:211], s[36:37], 0, v[142:143]
	ds_read_b128 v[178:181], v161 offset:32768
	ds_read_b128 v[182:185], v161 offset:33792
	ds_read_b128 v[186:189], v161 offset:34816
	ds_read_b128 v[190:193], v161 offset:35840
	ds_read_b128 v[194:197], v161 offset:36864
	ds_read_b128 v[198:201], v161 offset:37888
	ds_read_b128 v[202:205], v161 offset:38912
	ds_read_b128 v[206:209], v161 offset:39936
	global_load_lds_dwordx4 v[210:211], off
	v_lshl_add_u64 v[210:211], s[36:37], 0, v[140:141]
	s_mov_b32 m0, s42
	s_nop 0
	global_load_lds_dwordx4 v[210:211], off
	s_waitcnt vmcnt(8) lgkmcnt(0)
	s_nop 0
	s_barrier
	v_mfma_f32_16x16x32_bf16 v[126:129], v[130:133], v[178:181], v[126:129]
	v_mfma_f32_16x16x32_bf16 v[122:125], v[148:151], v[178:181], v[122:125]
	v_mfma_f32_16x16x32_bf16 v[110:113], v[130:133], v[186:189], v[110:113]
	v_mfma_f32_16x16x32_bf16 v[106:109], v[148:151], v[186:189], v[106:109]
	v_mfma_f32_16x16x32_bf16 v[94:97], v[130:133], v[194:197], v[94:97]
	v_mfma_f32_16x16x32_bf16 v[90:93], v[148:151], v[194:197], v[90:93]
	v_mfma_f32_16x16x32_bf16 v[78:81], v[130:133], v[202:205], v[78:81]
	v_mfma_f32_16x16x32_bf16 v[74:77], v[148:151], v[202:205], v[74:77]
	v_mfma_f32_16x16x32_bf16 v[126:129], v[134:137], v[182:185], v[126:129]
	v_mfma_f32_16x16x32_bf16 v[122:125], v[152:155], v[182:185], v[122:125]
	v_mfma_f32_16x16x32_bf16 v[110:113], v[134:137], v[190:193], v[110:113]
	v_mfma_f32_16x16x32_bf16 v[106:109], v[152:155], v[190:193], v[106:109]
	v_mfma_f32_16x16x32_bf16 v[94:97], v[134:137], v[198:201], v[94:97]
	v_mfma_f32_16x16x32_bf16 v[90:93], v[152:155], v[198:201], v[90:93]
	v_mfma_f32_16x16x32_bf16 v[78:81], v[134:137], v[206:209], v[78:81]
	v_mfma_f32_16x16x32_bf16 v[74:77], v[152:155], v[206:209], v[74:77]
	v_mfma_f32_16x16x32_bf16 v[118:121], v[162:165], v[178:181], v[118:121]
	v_mfma_f32_16x16x32_bf16 v[114:117], v[170:173], v[178:181], v[114:117]
	v_mfma_f32_16x16x32_bf16 v[102:105], v[162:165], v[186:189], v[102:105]
	v_mfma_f32_16x16x32_bf16 v[98:101], v[170:173], v[186:189], v[98:101]
	v_mfma_f32_16x16x32_bf16 v[86:89], v[162:165], v[194:197], v[86:89]
	v_mfma_f32_16x16x32_bf16 v[82:85], v[170:173], v[194:197], v[82:85]
	v_mfma_f32_16x16x32_bf16 v[70:73], v[162:165], v[202:205], v[70:73]
	v_mfma_f32_16x16x32_bf16 v[66:69], v[170:173], v[202:205], v[66:69]
	v_mfma_f32_16x16x32_bf16 v[118:121], v[166:169], v[182:185], v[118:121]
	v_mfma_f32_16x16x32_bf16 v[114:117], v[174:177], v[182:185], v[114:117]
	v_mfma_f32_16x16x32_bf16 v[102:105], v[166:169], v[190:193], v[102:105]
	v_mfma_f32_16x16x32_bf16 v[98:101], v[174:177], v[190:193], v[98:101]
	v_mfma_f32_16x16x32_bf16 v[86:89], v[166:169], v[198:201], v[86:89]
	v_mfma_f32_16x16x32_bf16 v[82:85], v[174:177], v[198:201], v[82:85]
	v_mfma_f32_16x16x32_bf16 v[70:73], v[166:169], v[206:209], v[70:73]
	v_mfma_f32_16x16x32_bf16 v[66:69], v[174:177], v[206:209], v[66:69]
	s_barrier
; #define PG8_STAGEA(bufoff, gbase, voff) PG8_STAGE_X(bufoff, gbase, voff, AUXA)
; #define PG8_STAGEB(bufoff, gbase, voff) PG8_STAGE_X(bufoff, gbase, voff, AUXB)
; #define PG8_LDA(dst, b, h) do { _Pragma("unroll") for (int m = 0; m < 4; ++m) _Pragma("unroll") for (int k = 0; k < 2; ++k) dst[m][k] = *(const PG8_LAS bf16x8*)(lds + PG8_SA(b, h) + aoff + m * 2048 + k * 1024); } while (0)
; #define PG8_WAIT_V(n) asm volatile("s_waitcnt vmcnt(" #n ")" ::: "memory")
; #define PG8_WAIT_L(n) asm volatile("s_waitcnt lgkmcnt(" #n ")" ::: "memory")
;     ...
;         for (int t = t0; t < nt; t += 2) {
;             const bool last = (t == nt - 2);
;             const char* a1 = cA + (size_t)(t + 1) * kstepA;
;             const char* a2 = last ? nA : cA + (size_t)(t + 2) * kstepA; const char* b2 = last ? nB : cB + (size_t)(t + 2) * kstepB;
;             const char* a3 = a2 + kstepA; const char* b3 = b2 + kstepB;
;             if (last && has_next) S.a_ready(nxt);
;             if constexpr (SP2) {
;             PG8_LDB(B0, 0, 0); PG8_LDB(B1, 0, 1); PG8_SCHED; PG8_LDA(At, 0, 0); PG8_STAGEA(PG8_SA(1, 1), a1 + hstepA, voffA);
;     ...
;             const int relax = __builtin_amdgcn_readfirstlane((t == 0 && ui > 0) ? 1 : 0);
;             PG8_WAIT_VR(8, 24, relax); PG8_WAIT_L(0); PG8_BAR; PG8_MMA(0, 0, At, B0); PG8_MMA(0, 1, At, B1); PG8_BAR; PG8_SCHED;
;     ...
;             PG8_WAIT_V(8); PG8_WAIT_L(0); PG8_BAR; PG8_MMA(0, 0, At, B0); PG8_MMA(0, 1, At, B1); PG8_BAR; PG8_SCHED;
;     ...
;             PG8_LDA(At, 0, 1); PG8_STAGEB(PG8_SB(0, 0), b2, voffB); PG8_STAGEB(PG8_SB(0, 1), b2 + hstepB, voffB); PG8_STAGEA(PG8_SA(0, 0), a2, voffA);
;     ...
;             PG8_WAIT_VR(8, 24, relax); PG8_WAIT_L(0); PG8_BAR; PG8_MMA(1, 0, At, B0); PG8_MMA(1, 1, At, B1); PG8_BAR; PG8_SCHED;
;     ...
;             PG8_WAIT_V(8); PG8_WAIT_L(0); PG8_BAR; PG8_MMA(1, 0, At, B0); PG8_MMA(1, 1, At, B1); PG8_BAR; PG8_SCHED;
;     ...
;             PG8_LDB(B0, 1, 0); PG8_LDB(B1, 1, 1); PG8_SCHED; PG8_LDA(At, 1, 0); PG8_STAGEA(PG8_SA(0, 1), a2 + hstepA, voffA);
;             PG8_WAIT_V(8); PG8_WAIT_L(0); PG8_BAR; PG8_MMA(0, 0, At, B0); PG8_MMA(0, 1, At, B1); PG8_BAR; PG8_SCHED;
;             PG8_LDA(At, 1, 1); PG8_STAGEB(PG8_SB(1, 0), b3, voffB); PG8_STAGEB(PG8_SB(1, 1), b3 + hstepB, voffB); PG8_STAGEA(PG8_SA(1, 0), a3, voffA);
;             PG8_WAIT_V(8); PG8_WAIT_L(0); PG8_BAR; PG8_MMA(1, 0, At, B0); PG8_MMA(1, 1, At, B1); PG8_BAR; PG8_SCHED;
	s_add_u32 s36, s16, 0x8000
	s_addc_u32 s37, s17, 0
	s_add_i32 s83, s83, s38
	v_lshl_add_u64 v[210:211], s[36:37], 0, v[16:17]
	s_mov_b32 m0, s83
	ds_read_b128 v[178:181], v161 offset:49152
	ds_read_b128 v[182:185], v161 offset:50176
	ds_read_b128 v[186:189], v161 offset:51200
	ds_read_b128 v[190:193], v161 offset:52224
	ds_read_b128 v[194:197], v161 offset:53248
	ds_read_b128 v[198:201], v161 offset:54272
	ds_read_b128 v[202:205], v161 offset:55296
	ds_read_b128 v[206:209], v161 offset:56320
	global_load_lds_dwordx4 v[210:211], off
	s_add_i32 m0, s83, 0x2000
	s_add_u32 s16, s16, 0xc000
	v_lshl_add_u64 v[210:211], s[36:37], 0, v[138:139]
	s_addc_u32 s17, s17, 0
	s_add_i32 s36, s90, s38
	global_load_lds_dwordx4 v[210:211], off
	v_lshl_add_u64 v[210:211], s[16:17], 0, v[16:17]
	s_mov_b32 m0, s36
	s_nop 0
	global_load_lds_dwordx4 v[210:211], off
	v_lshl_add_u64 v[210:211], s[16:17], 0, v[138:139]
	s_add_i32 m0, s36, 0x2000
	s_nop 0
	global_load_lds_dwordx4 v[210:211], off
	v_lshl_add_u64 v[210:211], s[26:27], 0, v[142:143]
	s_mov_b32 m0, s50
	s_nop 0
	global_load_lds_dwordx4 v[210:211], off
	v_lshl_add_u64 v[210:211], s[26:27], 0, v[140:141]
	s_mov_b32 m0, s51
	s_nop 0
	global_load_lds_dwordx4 v[210:211], off
	s_waitcnt vmcnt(8) lgkmcnt(0)
	s_nop 0
	s_barrier
	v_mfma_f32_16x16x32_bf16 v[62:65], v[130:133], v[178:181], v[62:65]
	v_mfma_f32_16x16x32_bf16 v[58:61], v[148:151], v[178:181], v[58:61]
	v_mfma_f32_16x16x32_bf16 v[46:49], v[130:133], v[186:189], v[46:49]
	v_mfma_f32_16x16x32_bf16 v[42:45], v[148:151], v[186:189], v[42:45]
	v_mfma_f32_16x16x32_bf16 v[30:33], v[130:133], v[194:197], v[30:33]
	v_mfma_f32_16x16x32_bf16 v[26:29], v[148:151], v[194:197], v[26:29]
	v_mfma_f32_16x16x32_bf16 v[12:15], v[130:133], v[202:205], v[12:15]
	v_mfma_f32_16x16x32_bf16 v[8:11], v[148:151], v[202:205], v[8:11]
	v_mfma_f32_16x16x32_bf16 v[62:65], v[134:137], v[182:185], v[62:65]
	v_mfma_f32_16x16x32_bf16 v[58:61], v[152:155], v[182:185], v[58:61]
	v_mfma_f32_16x16x32_bf16 v[46:49], v[134:137], v[190:193], v[46:49]
	v_mfma_f32_16x16x32_bf16 v[42:45], v[152:155], v[190:193], v[42:45]
	v_mfma_f32_16x16x32_bf16 v[30:33], v[134:137], v[198:201], v[30:33]
	v_mfma_f32_16x16x32_bf16 v[26:29], v[152:155], v[198:201], v[26:29]
	v_mfma_f32_16x16x32_bf16 v[12:15], v[134:137], v[206:209], v[12:15]
	v_mfma_f32_16x16x32_bf16 v[8:11], v[152:155], v[206:209], v[8:11]
	v_mfma_f32_16x16x32_bf16 v[54:57], v[162:165], v[178:181], v[54:57]
	v_mfma_f32_16x16x32_bf16 v[50:53], v[170:173], v[178:181], v[50:53]
	v_mfma_f32_16x16x32_bf16 v[38:41], v[162:165], v[186:189], v[38:41]
	v_mfma_f32_16x16x32_bf16 v[34:37], v[170:173], v[186:189], v[34:37]
	v_mfma_f32_16x16x32_bf16 v[22:25], v[162:165], v[194:197], v[22:25]
	v_mfma_f32_16x16x32_bf16 v[18:21], v[170:173], v[194:197], v[18:21]
	v_mfma_f32_16x16x32_bf16 v[4:7], v[162:165], v[202:205], v[4:7]
	v_mfma_f32_16x16x32_bf16 v[0:3], v[170:173], v[202:205], v[0:3]
	v_mfma_f32_16x16x32_bf16 v[54:57], v[166:169], v[182:185], v[54:57]
	v_mfma_f32_16x16x32_bf16 v[50:53], v[174:177], v[182:185], v[50:53]
	v_mfma_f32_16x16x32_bf16 v[38:41], v[166:169], v[190:193], v[38:41]
	v_mfma_f32_16x16x32_bf16 v[34:37], v[174:177], v[190:193], v[34:37]
	v_mfma_f32_16x16x32_bf16 v[22:25], v[166:169], v[198:201], v[22:25]
	v_mfma_f32_16x16x32_bf16 v[18:21], v[174:177], v[198:201], v[18:21]
	v_mfma_f32_16x16x32_bf16 v[4:7], v[166:169], v[206:209], v[4:7]
	v_mfma_f32_16x16x32_bf16 v[0:3], v[174:177], v[206:209], v[0:3]
	s_barrier
	s_add_i32 s82, s82, 2
	s_add_u32 s24, s24, 0x10000
	s_addc_u32 s25, s25, 0
	s_add_u32 s0, s0, 0x10000
	s_addc_u32 s1, s1, 0
	v_add_u32_e32 v212, 0x10000, v157
.LBB0_848:
	s_add_u32 s16, s24, 0x4000
	s_addc_u32 s17, s25, 0
	s_cmpk_eq_i32 s82, 0xfc
	s_cselect_b32 s36, s73, s16
	s_cselect_b32 s37, s11, s17
	s_cselect_b32 s16, s78, s0
	s_cselect_b32 s17, s15, s1
	s_add_u32 s26, s36, 0x8000
	s_addc_u32 s27, s37, 0
	s_add_i32 s83, 0, 0x10000
	s_add_i32 s94, 0, 0x14000
	ds_read_b128 v[130:133], v212
	ds_read_b128 v[134:137], v212 offset:1024
	ds_read_b128 v[148:151], v212 offset:2048
	ds_read_b128 v[152:155], v212 offset:3072
	ds_read_b128 v[162:165], v212 offset:16384
	ds_read_b128 v[166:169], v212 offset:17408
	ds_read_b128 v[170:173], v212 offset:18432
	ds_read_b128 v[174:177], v212 offset:19456
	s_add_i32 m0, s39, 0xc000
	ds_read_b128 v[178:181], v161
	ds_read_b128 v[182:185], v161 offset:1024
	ds_read_b128 v[186:189], v161 offset:2048
	ds_read_b128 v[190:193], v161 offset:3072
	ds_read_b128 v[194:197], v161 offset:4096
	ds_read_b128 v[198:201], v161 offset:5120
	ds_read_b128 v[202:205], v161 offset:6144
	global_load_lds_dwordx4 v144, s[24:25]
	s_add_i32 m0, s39, 0xe000
	ds_read_b128 v[206:209], v161 offset:7168
	global_load_lds_dwordx4 v146, s[24:25]
	s_waitcnt vmcnt(8) lgkmcnt(0)
	s_nop 0
	s_barrier
; #define PG8_STAGEA(bufoff, gbase, voff) PG8_STAGE_X(bufoff, gbase, voff, AUXA)
; #define PG8_STAGEB(bufoff, gbase, voff) PG8_STAGE_X(bufoff, gbase, voff, AUXB)
; #define PG8_LDA(dst, b, h) do { _Pragma("unroll") for (int m = 0; m < 4; ++m) _Pragma("unroll") for (int k = 0; k < 2; ++k) dst[m][k] = *(const PG8_LAS bf16x8*)(lds + PG8_SA(b, h) + aoff + m * 2048 + k * 1024); } while (0)
; #define PG8_LDB(dst, b, h) do { _Pragma("unroll") for (int n = 0; n < 2; ++n) _Pragma("unroll") for (int k = 0; k < 2; ++k) dst[n][k] = *(const PG8_LAS bf16x8*)(lds + PG8_SB(b, h) + boff + n * 2048 + k * 1024); } while (0)
; #define PG8_MMA(ai, bj, At, Bt) do { if (GEMM_PRIO_MODE == 0) __builtin_amdgcn_s_setprio(1); PG8_MMA_LOOPS \
;         acc[ai][bj][m][n] = __builtin_amdgcn_mfma_f32_16x16x32_bf16(Bt[n][k], At[m][k], acc[ai][bj][m][n], 0, 0, 0); if (GEMM_PRIO_MODE == 0) __builtin_amdgcn_s_setprio(0); } while (0)
; #define PG8_WAIT_V(n) asm volatile("s_waitcnt vmcnt(" #n ")" ::: "memory")
;     ...
;             PG8_LDB(B0, 0, 0); PG8_LDB(B1, 0, 1); PG8_SCHED; PG8_LDA(At, 0, 0); PG8_STAGEA(PG8_SA(1, 1), a1 + hstepA, voffA);
;     ...
;             const int relax = __builtin_amdgcn_readfirstlane((t == 0 && ui > 0) ? 1 : 0);
;             PG8_WAIT_VR(8, 24, relax); PG8_WAIT_L(0); PG8_BAR; PG8_MMA(0, 0, At, B0); PG8_MMA(0, 1, At, B1); PG8_BAR; PG8_SCHED;
;     ...
;             PG8_WAIT_V(8); PG8_WAIT_L(0); PG8_BAR; PG8_MMA(0, 0, At, B0); PG8_MMA(0, 1, At, B1); PG8_BAR; PG8_SCHED;
;     ...
;             PG8_LDA(At, 0, 1); PG8_STAGEB(PG8_SB(0, 0), b2, voffB); PG8_STAGEB(PG8_SB(0, 1), b2 + hstepB, voffB); PG8_STAGEA(PG8_SA(0, 0), a2, voffA);
;     ...
;             PG8_WAIT_VR(8, 24, relax); PG8_WAIT_L(0); PG8_BAR; PG8_MMA(1, 0, At, B0); PG8_MMA(1, 1, At, B1); PG8_BAR; PG8_SCHED;
;     ...
;             PG8_WAIT_V(8); PG8_WAIT_L(0); PG8_BAR; PG8_MMA(1, 0, At, B0); PG8_MMA(1, 1, At, B1); PG8_BAR; PG8_SCHED;
;     ...
;             PG8_LDB(B0, 1, 0); PG8_LDB(B1, 1, 1); PG8_SCHED; PG8_LDA(At, 1, 0); PG8_STAGEA(PG8_SA(0, 1), a2 + hstepA, voffA);
;             PG8_WAIT_V(8); PG8_WAIT_L(0); PG8_BAR; PG8_MMA(0, 0, At, B0); PG8_MMA(0, 1, At, B1); PG8_BAR; PG8_SCHED;
;             PG8_LDA(At, 1, 1); PG8_STAGEB(PG8_SB(1, 0), b3, voffB); PG8_STAGEB(PG8_SB(1, 1), b3 + hstepB, voffB); PG8_STAGEA(PG8_SA(1, 0), a3, voffA);
;             PG8_WAIT_V(8); PG8_WAIT_L(0); PG8_BAR; PG8_MMA(1, 0, At, B0); PG8_MMA(1, 1, At, B1); PG8_BAR; PG8_SCHED;
	v_mfma_f32_16x16x32_bf16 v[126:129], v[130:133], v[178:181], v[126:129]
	v_mfma_f32_16x16x32_bf16 v[122:125], v[148:151], v[178:181], v[122:125]
	v_mfma_f32_16x16x32_bf16 v[110:113], v[130:133], v[186:189], v[110:113]
	v_mfma_f32_16x16x32_bf16 v[106:109], v[148:151], v[186:189], v[106:109]
	v_mfma_f32_16x16x32_bf16 v[94:97], v[130:133], v[194:197], v[94:97]
	v_mfma_f32_16x16x32_bf16 v[90:93], v[148:151], v[194:197], v[90:93]
	v_mfma_f32_16x16x32_bf16 v[78:81], v[130:133], v[202:205], v[78:81]
	v_mfma_f32_16x16x32_bf16 v[74:77], v[148:151], v[202:205], v[74:77]
	v_mfma_f32_16x16x32_bf16 v[126:129], v[134:137], v[182:185], v[126:129]
	v_mfma_f32_16x16x32_bf16 v[122:125], v[152:155], v[182:185], v[122:125]
	v_mfma_f32_16x16x32_bf16 v[110:113], v[134:137], v[190:193], v[110:113]
	v_mfma_f32_16x16x32_bf16 v[106:109], v[152:155], v[190:193], v[106:109]
	v_mfma_f32_16x16x32_bf16 v[94:97], v[134:137], v[198:201], v[94:97]
	v_mfma_f32_16x16x32_bf16 v[90:93], v[152:155], v[198:201], v[90:93]
	v_mfma_f32_16x16x32_bf16 v[78:81], v[134:137], v[206:209], v[78:81]
	v_mfma_f32_16x16x32_bf16 v[74:77], v[152:155], v[206:209], v[74:77]
	v_mfma_f32_16x16x32_bf16 v[118:121], v[162:165], v[178:181], v[118:121]
	v_mfma_f32_16x16x32_bf16 v[114:117], v[170:173], v[178:181], v[114:117]
	v_mfma_f32_16x16x32_bf16 v[102:105], v[162:165], v[186:189], v[102:105]
	v_mfma_f32_16x16x32_bf16 v[98:101], v[170:173], v[186:189], v[98:101]
	v_mfma_f32_16x16x32_bf16 v[86:89], v[162:165], v[194:197], v[86:89]
	v_mfma_f32_16x16x32_bf16 v[82:85], v[170:173], v[194:197], v[82:85]
	v_mfma_f32_16x16x32_bf16 v[70:73], v[162:165], v[202:205], v[70:73]
	v_mfma_f32_16x16x32_bf16 v[66:69], v[170:173], v[202:205], v[66:69]
	v_mfma_f32_16x16x32_bf16 v[118:121], v[166:169], v[182:185], v[118:121]
	v_mfma_f32_16x16x32_bf16 v[114:117], v[174:177], v[182:185], v[114:117]
	v_mfma_f32_16x16x32_bf16 v[102:105], v[166:169], v[190:193], v[102:105]
	v_mfma_f32_16x16x32_bf16 v[98:101], v[174:177], v[190:193], v[98:101]
	v_mfma_f32_16x16x32_bf16 v[86:89], v[166:169], v[198:201], v[86:89]
	v_mfma_f32_16x16x32_bf16 v[82:85], v[174:177], v[198:201], v[82:85]
	v_mfma_f32_16x16x32_bf16 v[70:73], v[166:169], v[206:209], v[70:73]
	v_mfma_f32_16x16x32_bf16 v[66:69], v[174:177], v[206:209], v[66:69]
	s_barrier
	s_add_i32 s83, s83, s38
	s_mov_b32 m0, s83
	ds_read_b128 v[178:181], v161 offset:16384
	ds_read_b128 v[182:185], v161 offset:17408
	ds_read_b128 v[186:189], v161 offset:18432
	ds_read_b128 v[190:193], v161 offset:19456
	global_load_lds_dwordx4 v16, s[16:17]
	s_add_i32 m0, s83, 0x2000
	s_add_u32 s90, s16, 0x4000
	s_addc_u32 s91, s17, 0
	s_add_i32 s83, s94, s38
	global_load_lds_dwordx4 v138, s[16:17]
	s_mov_b32 m0, s83
	ds_read_b128 v[206:209], v161 offset:23552
	global_load_lds_dwordx4 v16, s[90:91]
	s_add_i32 m0, s83, 0x2000
	ds_read_b128 v[202:205], v161 offset:22528
	global_load_lds_dwordx4 v138, s[90:91]
	s_mov_b32 m0, s39
	ds_read_b128 v[198:201], v161 offset:21504
	global_load_lds_dwordx4 v142, s[36:37]
	s_mov_b32 m0, s40
	ds_read_b128 v[194:197], v161 offset:20480
	global_load_lds_dwordx4 v140, s[36:37]
	s_waitcnt vmcnt(8) lgkmcnt(0)
	s_barrier
	v_mfma_f32_16x16x32_bf16 v[62:65], v[130:133], v[178:181], v[62:65]
	v_mfma_f32_16x16x32_bf16 v[58:61], v[148:151], v[178:181], v[58:61]
	v_mfma_f32_16x16x32_bf16 v[46:49], v[130:133], v[186:189], v[46:49]
	v_mfma_f32_16x16x32_bf16 v[42:45], v[148:151], v[186:189], v[42:45]
	v_mfma_f32_16x16x32_bf16 v[30:33], v[130:133], v[194:197], v[30:33]
	v_mfma_f32_16x16x32_bf16 v[26:29], v[148:151], v[194:197], v[26:29]
	v_mfma_f32_16x16x32_bf16 v[12:15], v[130:133], v[202:205], v[12:15]
	v_mfma_f32_16x16x32_bf16 v[8:11], v[148:151], v[202:205], v[8:11]
	v_mfma_f32_16x16x32_bf16 v[62:65], v[134:137], v[182:185], v[62:65]
	v_mfma_f32_16x16x32_bf16 v[58:61], v[152:155], v[182:185], v[58:61]
	v_mfma_f32_16x16x32_bf16 v[46:49], v[134:137], v[190:193], v[46:49]
	v_mfma_f32_16x16x32_bf16 v[42:45], v[152:155], v[190:193], v[42:45]
	v_mfma_f32_16x16x32_bf16 v[30:33], v[134:137], v[198:201], v[30:33]
	v_mfma_f32_16x16x32_bf16 v[26:29], v[152:155], v[198:201], v[26:29]
	v_mfma_f32_16x16x32_bf16 v[12:15], v[134:137], v[206:209], v[12:15]
	v_mfma_f32_16x16x32_bf16 v[8:11], v[152:155], v[206:209], v[8:11]
	v_mfma_f32_16x16x32_bf16 v[54:57], v[162:165], v[178:181], v[54:57]
	v_mfma_f32_16x16x32_bf16 v[50:53], v[170:173], v[178:181], v[50:53]
	v_mfma_f32_16x16x32_bf16 v[38:41], v[162:165], v[186:189], v[38:41]
	v_mfma_f32_16x16x32_bf16 v[34:37], v[170:173], v[186:189], v[34:37]
	v_mfma_f32_16x16x32_bf16 v[22:25], v[162:165], v[194:197], v[22:25]
	v_mfma_f32_16x16x32_bf16 v[18:21], v[170:173], v[194:197], v[18:21]
	v_mfma_f32_16x16x32_bf16 v[4:7], v[162:165], v[202:205], v[4:7]
	v_mfma_f32_16x16x32_bf16 v[0:3], v[170:173], v[202:205], v[0:3]
	v_mfma_f32_16x16x32_bf16 v[54:57], v[166:169], v[182:185], v[54:57]
	v_mfma_f32_16x16x32_bf16 v[50:53], v[174:177], v[182:185], v[50:53]
	v_mfma_f32_16x16x32_bf16 v[38:41], v[166:169], v[190:193], v[38:41]
	v_mfma_f32_16x16x32_bf16 v[34:37], v[174:177], v[190:193], v[34:37]
	v_mfma_f32_16x16x32_bf16 v[22:25], v[166:169], v[198:201], v[22:25]
	v_mfma_f32_16x16x32_bf16 v[18:21], v[174:177], v[198:201], v[18:21]
	v_mfma_f32_16x16x32_bf16 v[4:7], v[166:169], v[206:209], v[4:7]
	v_mfma_f32_16x16x32_bf16 v[0:3], v[174:177], v[206:209], v[0:3]
	s_barrier
; #define PG8_STAGEA(bufoff, gbase, voff) PG8_STAGE_X(bufoff, gbase, voff, AUXA)
; #define PG8_STAGEB(bufoff, gbase, voff) PG8_STAGE_X(bufoff, gbase, voff, AUXB)
; #define PG8_LDA(dst, b, h) do { _Pragma("unroll") for (int m = 0; m < 4; ++m) _Pragma("unroll") for (int k = 0; k < 2; ++k) dst[m][k] = *(const PG8_LAS bf16x8*)(lds + PG8_SA(b, h) + aoff + m * 2048 + k * 1024); } while (0)
; #define PG8_LDB(dst, b, h) do { _Pragma("unroll") for (int n = 0; n < 2; ++n) _Pragma("unroll") for (int k = 0; k < 2; ++k) dst[n][k] = *(const PG8_LAS bf16x8*)(lds + PG8_SB(b, h) + boff + n * 2048 + k * 1024); } while (0)
; #define PG8_MMA(ai, bj, At, Bt) do { if (GEMM_PRIO_MODE == 0) __builtin_amdgcn_s_setprio(1); PG8_MMA_LOOPS \
;         acc[ai][bj][m][n] = __builtin_amdgcn_mfma_f32_16x16x32_bf16(Bt[n][k], At[m][k], acc[ai][bj][m][n], 0, 0, 0); if (GEMM_PRIO_MODE == 0) __builtin_amdgcn_s_setprio(0); } while (0)
; #define PG8_WAIT_V(n) asm volatile("s_waitcnt vmcnt(" #n ")" ::: "memory")
;     ...
;             PG8_LDB(B0, 0, 0); PG8_LDB(B1, 0, 1); PG8_SCHED; PG8_LDA(At, 0, 0); PG8_STAGEA(PG8_SA(1, 1), a1 + hstepA, voffA);
;     ...
;             const int relax = __builtin_amdgcn_readfirstlane((t == 0 && ui > 0) ? 1 : 0);
;             PG8_WAIT_VR(8, 24, relax); PG8_WAIT_L(0); PG8_BAR; PG8_MMA(0, 0, At, B0); PG8_MMA(0, 1, At, B1); PG8_BAR; PG8_SCHED;
;     ...
;             PG8_WAIT_V(8); PG8_WAIT_L(0); PG8_BAR; PG8_MMA(0, 0, At, B0); PG8_MMA(0, 1, At, B1); PG8_BAR; PG8_SCHED;
;     ...
;             PG8_LDA(At, 0, 1); PG8_STAGEB(PG8_SB(0, 0), b2, voffB); PG8_STAGEB(PG8_SB(0, 1), b2 + hstepB, voffB); PG8_STAGEA(PG8_SA(0, 0), a2, voffA);
;     ...
;             PG8_WAIT_VR(8, 24, relax); PG8_WAIT_L(0); PG8_BAR; PG8_MMA(1, 0, At, B0); PG8_MMA(1, 1, At, B1); PG8_BAR; PG8_SCHED;
;     ...
;             PG8_WAIT_V(8); PG8_WAIT_L(0); PG8_BAR; PG8_MMA(1, 0, At, B0); PG8_MMA(1, 1, At, B1); PG8_BAR; PG8_SCHED;
;     ...
;             PG8_LDB(B0, 1, 0); PG8_LDB(B1, 1, 1); PG8_SCHED; PG8_LDA(At, 1, 0); PG8_STAGEA(PG8_SA(0, 1), a2 + hstepA, voffA);
;             PG8_WAIT_V(8); PG8_WAIT_L(0); PG8_BAR; PG8_MMA(0, 0, At, B0); PG8_MMA(0, 1, At, B1); PG8_BAR; PG8_SCHED;
;             PG8_LDA(At, 1, 1); PG8_STAGEB(PG8_SB(1, 0), b3, voffB); PG8_STAGEB(PG8_SB(1, 1), b3 + hstepB, voffB); PG8_STAGEA(PG8_SA(1, 0), a3, voffA);
;             PG8_WAIT_V(8); PG8_WAIT_L(0); PG8_BAR; PG8_MMA(1, 0, At, B0); PG8_MMA(1, 1, At, B1); PG8_BAR; PG8_SCHED;
	s_add_i32 s83, 0, 0x18000
	s_add_i32 s90, 0, 0x1c000
	ds_read_b128 v[130:133], v212 offset:32768
	ds_read_b128 v[134:137], v212 offset:33792
	ds_read_b128 v[148:151], v212 offset:34816
	ds_read_b128 v[152:155], v212 offset:35840
	ds_read_b128 v[162:165], v212 offset:49152
	ds_read_b128 v[166:169], v212 offset:50176
	ds_read_b128 v[170:173], v212 offset:51200
	ds_read_b128 v[174:177], v212 offset:52224
	s_add_u32 s36, s36, 0x4000
	s_addc_u32 s37, s37, 0
	s_mov_b32 m0, s41
	ds_read_b128 v[178:181], v161 offset:32768
	ds_read_b128 v[182:185], v161 offset:33792
	ds_read_b128 v[186:189], v161 offset:34816
	ds_read_b128 v[190:193], v161 offset:35840
	ds_read_b128 v[194:197], v161 offset:36864
	ds_read_b128 v[198:201], v161 offset:37888
	ds_read_b128 v[202:205], v161 offset:38912
	global_load_lds_dwordx4 v142, s[36:37]
	s_mov_b32 m0, s42
	ds_read_b128 v[206:209], v161 offset:39936
	global_load_lds_dwordx4 v140, s[36:37]
	s_waitcnt vmcnt(8) lgkmcnt(0)
	s_barrier
	v_mfma_f32_16x16x32_bf16 v[126:129], v[130:133], v[178:181], v[126:129]
	v_mfma_f32_16x16x32_bf16 v[122:125], v[148:151], v[178:181], v[122:125]
	v_mfma_f32_16x16x32_bf16 v[110:113], v[130:133], v[186:189], v[110:113]
	v_mfma_f32_16x16x32_bf16 v[106:109], v[148:151], v[186:189], v[106:109]
	v_mfma_f32_16x16x32_bf16 v[94:97], v[130:133], v[194:197], v[94:97]
	v_mfma_f32_16x16x32_bf16 v[90:93], v[148:151], v[194:197], v[90:93]
	v_mfma_f32_16x16x32_bf16 v[78:81], v[130:133], v[202:205], v[78:81]
	v_mfma_f32_16x16x32_bf16 v[74:77], v[148:151], v[202:205], v[74:77]
	v_mfma_f32_16x16x32_bf16 v[126:129], v[134:137], v[182:185], v[126:129]
	v_mfma_f32_16x16x32_bf16 v[122:125], v[152:155], v[182:185], v[122:125]
	v_mfma_f32_16x16x32_bf16 v[110:113], v[134:137], v[190:193], v[110:113]
	v_mfma_f32_16x16x32_bf16 v[106:109], v[152:155], v[190:193], v[106:109]
	v_mfma_f32_16x16x32_bf16 v[94:97], v[134:137], v[198:201], v[94:97]
	v_mfma_f32_16x16x32_bf16 v[90:93], v[152:155], v[198:201], v[90:93]
	v_mfma_f32_16x16x32_bf16 v[78:81], v[134:137], v[206:209], v[78:81]
	v_mfma_f32_16x16x32_bf16 v[74:77], v[152:155], v[206:209], v[74:77]
	v_mfma_f32_16x16x32_bf16 v[118:121], v[162:165], v[178:181], v[118:121]
	v_mfma_f32_16x16x32_bf16 v[114:117], v[170:173], v[178:181], v[114:117]
	v_mfma_f32_16x16x32_bf16 v[102:105], v[162:165], v[186:189], v[102:105]
	v_mfma_f32_16x16x32_bf16 v[98:101], v[170:173], v[186:189], v[98:101]
	v_mfma_f32_16x16x32_bf16 v[86:89], v[162:165], v[194:197], v[86:89]
	v_mfma_f32_16x16x32_bf16 v[82:85], v[170:173], v[194:197], v[82:85]
	v_mfma_f32_16x16x32_bf16 v[70:73], v[162:165], v[202:205], v[70:73]
	v_mfma_f32_16x16x32_bf16 v[66:69], v[170:173], v[202:205], v[66:69]
	v_mfma_f32_16x16x32_bf16 v[118:121], v[166:169], v[182:185], v[118:121]
	v_mfma_f32_16x16x32_bf16 v[114:117], v[174:177], v[182:185], v[114:117]
	v_mfma_f32_16x16x32_bf16 v[102:105], v[166:169], v[190:193], v[102:105]
	v_mfma_f32_16x16x32_bf16 v[98:101], v[174:177], v[190:193], v[98:101]
	v_mfma_f32_16x16x32_bf16 v[86:89], v[166:169], v[198:201], v[86:89]
	v_mfma_f32_16x16x32_bf16 v[82:85], v[174:177], v[198:201], v[82:85]
	v_mfma_f32_16x16x32_bf16 v[70:73], v[166:169], v[206:209], v[70:73]
	v_mfma_f32_16x16x32_bf16 v[66:69], v[174:177], v[206:209], v[66:69]
	s_barrier
	s_add_u32 s36, s16, 0x8000
	s_addc_u32 s37, s17, 0
	s_add_i32 s83, s83, s38
	s_mov_b32 m0, s83
	ds_read_b128 v[178:181], v161 offset:49152
	ds_read_b128 v[182:185], v161 offset:50176
	ds_read_b128 v[186:189], v161 offset:51200
	ds_read_b128 v[190:193], v161 offset:52224
	global_load_lds_dwordx4 v16, s[36:37]
	s_add_i32 m0, s83, 0x2000
	s_add_u32 s16, s16, 0xc000
	s_addc_u32 s17, s17, 0
	global_load_lds_dwordx4 v138, s[36:37]
	s_add_i32 s36, s90, s38
	s_mov_b32 m0, s36
	ds_read_b128 v[206:209], v161 offset:56320
	global_load_lds_dwordx4 v16, s[16:17]
	s_add_i32 m0, s36, 0x2000
	ds_read_b128 v[202:205], v161 offset:55296
	global_load_lds_dwordx4 v138, s[16:17]
	s_mov_b32 m0, s50
	ds_read_b128 v[198:201], v161 offset:54272
	global_load_lds_dwordx4 v142, s[26:27]
	s_mov_b32 m0, s51
	ds_read_b128 v[194:197], v161 offset:53248
	global_load_lds_dwordx4 v140, s[26:27]
	s_waitcnt vmcnt(8) lgkmcnt(0)
	s_nop 0
	s_barrier
	v_mfma_f32_16x16x32_bf16 v[62:65], v[130:133], v[178:181], v[62:65]
	v_mfma_f32_16x16x32_bf16 v[58:61], v[148:151], v[178:181], v[58:61]
	v_mfma_f32_16x16x32_bf16 v[46:49], v[130:133], v[186:189], v[46:49]
	v_mfma_f32_16x16x32_bf16 v[42:45], v[148:151], v[186:189], v[42:45]
	v_mfma_f32_16x16x32_bf16 v[30:33], v[130:133], v[194:197], v[30:33]
	v_mfma_f32_16x16x32_bf16 v[26:29], v[148:151], v[194:197], v[26:29]
	v_mfma_f32_16x16x32_bf16 v[12:15], v[130:133], v[202:205], v[12:15]
	v_mfma_f32_16x16x32_bf16 v[8:11], v[148:151], v[202:205], v[8:11]
	v_mfma_f32_16x16x32_bf16 v[62:65], v[134:137], v[182:185], v[62:65]
	v_mfma_f32_16x16x32_bf16 v[58:61], v[152:155], v[182:185], v[58:61]
	v_mfma_f32_16x16x32_bf16 v[46:49], v[134:137], v[190:193], v[46:49]
	v_mfma_f32_16x16x32_bf16 v[42:45], v[152:155], v[190:193], v[42:45]
	v_mfma_f32_16x16x32_bf16 v[30:33], v[134:137], v[198:201], v[30:33]
	v_mfma_f32_16x16x32_bf16 v[26:29], v[152:155], v[198:201], v[26:29]
	v_mfma_f32_16x16x32_bf16 v[12:15], v[134:137], v[206:209], v[12:15]
	v_mfma_f32_16x16x32_bf16 v[8:11], v[152:155], v[206:209], v[8:11]
	v_mfma_f32_16x16x32_bf16 v[54:57], v[162:165], v[178:181], v[54:57]
	v_mfma_f32_16x16x32_bf16 v[50:53], v[170:173], v[178:181], v[50:53]
	v_mfma_f32_16x16x32_bf16 v[38:41], v[162:165], v[186:189], v[38:41]
	v_mfma_f32_16x16x32_bf16 v[34:37], v[170:173], v[186:189], v[34:37]
	v_mfma_f32_16x16x32_bf16 v[22:25], v[162:165], v[194:197], v[22:25]
	v_mfma_f32_16x16x32_bf16 v[18:21], v[170:173], v[194:197], v[18:21]
	v_mfma_f32_16x16x32_bf16 v[4:7], v[162:165], v[202:205], v[4:7]
	v_mfma_f32_16x16x32_bf16 v[0:3], v[170:173], v[202:205], v[0:3]
	v_mfma_f32_16x16x32_bf16 v[54:57], v[166:169], v[182:185], v[54:57]
	v_mfma_f32_16x16x32_bf16 v[50:53], v[174:177], v[182:185], v[50:53]
	v_mfma_f32_16x16x32_bf16 v[38:41], v[166:169], v[190:193], v[38:41]
	v_mfma_f32_16x16x32_bf16 v[34:37], v[174:177], v[190:193], v[34:37]
	v_mfma_f32_16x16x32_bf16 v[22:25], v[166:169], v[198:201], v[22:25]
	v_mfma_f32_16x16x32_bf16 v[18:21], v[174:177], v[198:201], v[18:21]
	v_mfma_f32_16x16x32_bf16 v[4:7], v[166:169], v[206:209], v[4:7]
	v_mfma_f32_16x16x32_bf16 v[0:3], v[174:177], v[206:209], v[0:3]
	s_barrier
	s_add_i32 s82, s82, 2
	s_add_u32 s24, s24, 0x10000
	s_addc_u32 s25, s25, 0
	s_add_u32 s0, s0, 0x10000
	s_addc_u32 s1, s1, 0
	s_cmpk_gt_u32 s82, 0xfd
	s_cbranch_scc0 .LBB0_848
	s_and_b64 vcc, exec, s[8:9]
	s_cbranch_vccz .LBB0_851
	s_barrier
